# GEMM: leading half issues its epilogue global loads before its align barrier (4 of 6 epilogues)
# speedup vs baseline: 1.0035x; 1.0035x over previous
; #define PG8_STAGE(bufoff, gbase, voff) do { _Pragma("unroll") for (int _i = 0; _i < 2; ++_i) \
;         __builtin_amdgcn_global_load_lds((const unsigned*)((const char*)(gbase) + (voff)[_i]), (PG8_LAS unsigned*)(lds + (bufoff) + ldsw + _i * 8192), 16, 0, 0); } while (0)
; #define PG8_LDA(dst, b, h) do { _Pragma("unroll") for (int m = 0; m < 4; ++m) _Pragma("unroll") for (int k = 0; k < 2; ++k) dst[m][k] = *(const PG8_LAS bf16x8*)(lds + PG8_SA(b, h) + aoff + m * 2048 + k * 1024); } while (0)
; #define PG8_LDB(dst, b, h) do { _Pragma("unroll") for (int n = 0; n < 2; ++n) _Pragma("unroll") for (int k = 0; k < 2; ++k) dst[n][k] = *(const PG8_LAS bf16x8*)(lds + PG8_SB(b, h) + boff + n * 2048 + k * 1024); } while (0)
; #define PG8_MMA(ai, bj, At, Bt) do { __builtin_amdgcn_s_setprio(1); _Pragma("unroll") for (int m = 0; m < 4; ++m) _Pragma("unroll") for (int n = 0; n < 2; ++n) _Pragma("unroll") for (int k = 0; k < 2; ++k) \
;         acc[ai][bj][m][n] = __builtin_amdgcn_mfma_f32_16x16x32_bf16(Bt[n][k], At[m][k], acc[ai][bj][m][n], 0, 0, 0); __builtin_amdgcn_s_setprio(0); } while (0)
; #define PG8_WAIT_V(n) asm volatile("s_waitcnt vmcnt(" #n ")" ::: "memory")
; #define PG8_WAIT_L(n) asm volatile("s_waitcnt lgkmcnt(" #n ")" ::: "memory")
; #define PG8_BAR __builtin_amdgcn_s_barrier()
; #define PG8_SCHED __builtin_amdgcn_sched_barrier(0)
; template <class Epi, class Sched, bool ALIGN_EPI = false, bool SP2 = false>
; __device__ __forceinline__ void gemm_phase(PG8_LAS unsigned char* lds, const Gemm g, const Sched& S, const Epi& E) {
;     ...
;             PG8_LDB(B0, 0, 0); PG8_LDB(B1, 0, 1); PG8_SCHED; PG8_LDA(At, 0, 0); PG8_STAGE(PG8_SA(1, 1), a1 + hstep, voffA);
;             PG8_WAIT_V(8); PG8_WAIT_L(0); PG8_BAR; PG8_MMA(0, 0, At, B0); PG8_MMA(0, 1, At, B1); PG8_BAR; PG8_SCHED;
;             PG8_LDA(At, 0, 1); PG8_STAGE(PG8_SB(0, 0), b2, voffB); PG8_STAGE(PG8_SB(0, 1), b2 + hstep, voffB); PG8_STAGE(PG8_SA(0, 0), a2, voffA);
;             PG8_WAIT_V(8); PG8_WAIT_L(0); PG8_BAR; PG8_MMA(1, 0, At, B0); PG8_MMA(1, 1, At, B1); PG8_BAR; PG8_SCHED;
.LBB0_291:
	s_add_u32 s53, s18, 0xfffc0080
	s_addc_u32 s58, s19, -1
	s_add_i32 s64, 0, 0x10000
	s_cmp_eq_u32 s52, 12
	s_cselect_b32 s61, s30, s58
	s_cselect_b32 s60, s31, s53
	s_cselect_b32 s59, s34, s45
	s_cselect_b32 s58, s35, s43
	s_add_i32 s53, 0, 0x14000
	v_add_u32_e32 v142, s64, v167
	v_add_u32_e32 v164, s53, v167
	ds_read_b128 v[130:133], v142
	ds_read_b128 v[134:137], v142 offset:1024
	ds_read_b128 v[138:141], v142 offset:2048
	ds_read_b128 v[142:145], v142 offset:3072
	ds_read_b128 v[156:159], v164
	ds_read_b128 v[160:163], v164 offset:1024
	ds_read_b128 v[170:173], v164 offset:2048
	ds_read_b128 v[174:177], v164 offset:3072
	v_lshl_add_u64 v[164:165], s[18:19], 0, v[152:153]
	s_add_i32 m0, s27, 0xc000
	ds_read_b128 v[178:181], v169
	ds_read_b128 v[182:185], v169 offset:1024
	ds_read_b128 v[186:189], v169 offset:2048
	ds_read_b128 v[194:197], v169 offset:3072
	ds_read_b128 v[198:201], v169 offset:4096
	ds_read_b128 v[202:205], v169 offset:5120
	ds_read_b128 v[206:209], v169 offset:6144
	ds_read_b128 v[210:213], v169 offset:7168
	global_load_lds_dwordx4 v[164:165], off
	v_lshl_add_u64 v[164:165], s[18:19], 0, v[154:155]
	s_add_i32 m0, s27, 0xe000
	s_nop 0
	global_load_lds_dwordx4 v[164:165], off
	s_waitcnt vmcnt(8)
	s_waitcnt lgkmcnt(0)
	s_barrier
	s_setprio 1
	s_waitcnt lgkmcnt(0)
	v_mfma_f32_16x16x32_bf16 v[126:129], v[130:133], v[178:181], v[126:129]
	v_mfma_f32_16x16x32_bf16 v[122:125], v[138:141], v[178:181], v[122:125]
	v_mfma_f32_16x16x32_bf16 v[114:117], v[130:133], v[186:189], v[114:117]
	v_mfma_f32_16x16x32_bf16 v[110:113], v[138:141], v[186:189], v[110:113]
	v_mfma_f32_16x16x32_bf16 v[102:105], v[130:133], v[198:201], v[102:105]
	v_mfma_f32_16x16x32_bf16 v[94:97], v[138:141], v[198:201], v[94:97]
	v_mfma_f32_16x16x32_bf16 v[86:89], v[130:133], v[206:209], v[86:89]
	v_mfma_f32_16x16x32_bf16 v[78:81], v[138:141], v[206:209], v[78:81]
	v_mfma_f32_16x16x32_bf16 v[126:129], v[134:137], v[182:185], v[126:129]
	v_mfma_f32_16x16x32_bf16 v[122:125], v[142:145], v[182:185], v[122:125]
	v_mfma_f32_16x16x32_bf16 v[114:117], v[134:137], v[194:197], v[114:117]
	v_mfma_f32_16x16x32_bf16 v[110:113], v[142:145], v[194:197], v[110:113]
	v_mfma_f32_16x16x32_bf16 v[102:105], v[134:137], v[202:205], v[102:105]
	v_mfma_f32_16x16x32_bf16 v[94:97], v[142:145], v[202:205], v[94:97]
	v_mfma_f32_16x16x32_bf16 v[86:89], v[134:137], v[210:213], v[86:89]
	v_mfma_f32_16x16x32_bf16 v[78:81], v[142:145], v[210:213], v[78:81]
	s_setprio 0
	s_setprio 1
	v_mfma_f32_16x16x32_bf16 v[118:121], v[156:159], v[178:181], v[118:121]
	v_mfma_f32_16x16x32_bf16 v[106:109], v[170:173], v[178:181], v[106:109]
	v_mfma_f32_16x16x32_bf16 v[98:101], v[156:159], v[186:189], v[98:101]
	v_mfma_f32_16x16x32_bf16 v[90:93], v[170:173], v[186:189], v[90:93]
	v_mfma_f32_16x16x32_bf16 v[82:85], v[156:159], v[198:201], v[82:85]
	v_mfma_f32_16x16x32_bf16 v[74:77], v[170:173], v[198:201], v[74:77]
	v_mfma_f32_16x16x32_bf16 v[70:73], v[156:159], v[206:209], v[70:73]
	v_mfma_f32_16x16x32_bf16 v[66:69], v[170:173], v[206:209], v[66:69]
	v_mfma_f32_16x16x32_bf16 v[118:121], v[160:163], v[182:185], v[118:121]
	v_mfma_f32_16x16x32_bf16 v[106:109], v[174:177], v[182:185], v[106:109]
	v_mfma_f32_16x16x32_bf16 v[98:101], v[160:163], v[194:197], v[98:101]
	v_mfma_f32_16x16x32_bf16 v[90:93], v[174:177], v[194:197], v[90:93]
	v_mfma_f32_16x16x32_bf16 v[82:85], v[160:163], v[202:205], v[82:85]
	v_mfma_f32_16x16x32_bf16 v[74:77], v[174:177], v[202:205], v[74:77]
	v_mfma_f32_16x16x32_bf16 v[70:73], v[160:163], v[210:213], v[70:73]
	v_mfma_f32_16x16x32_bf16 v[66:69], v[174:177], v[210:213], v[66:69]
	s_setprio 0
	s_barrier
	s_add_i32 s64, s64, s24
	v_lshl_add_u64 v[164:165], s[58:59], 0, v[0:1]
	s_mov_b32 m0, s64
	ds_read_b128 v[178:181], v169 offset:16384
	ds_read_b128 v[182:185], v169 offset:17408
	ds_read_b128 v[186:189], v169 offset:18432
	ds_read_b128 v[194:197], v169 offset:19456
	ds_read_b128 v[198:201], v169 offset:20480
	ds_read_b128 v[202:205], v169 offset:21504
	ds_read_b128 v[206:209], v169 offset:22528
	ds_read_b128 v[210:213], v169 offset:23552
	global_load_lds_dwordx4 v[164:165], off
	s_add_i32 m0, s64, 0x2000
	s_add_u32 s64, s58, 0x40000
	v_lshl_add_u64 v[214:215], s[58:59], 0, v[150:151]
	s_addc_u32 s65, s59, 0
	s_add_i32 s53, s53, s24
	global_load_lds_dwordx4 v[214:215], off
	v_lshl_add_u64 v[216:217], s[64:65], 0, v[0:1]
	s_mov_b32 m0, s53
	v_lshl_add_u64 v[218:219], s[60:61], 0, v[148:149]
	global_load_lds_dwordx4 v[216:217], off
	v_lshl_add_u64 v[216:217], s[64:65], 0, v[150:151]
	s_add_i32 m0, s53, 0x2000
	s_nop 0
	global_load_lds_dwordx4 v[216:217], off
	v_lshl_add_u64 v[216:217], s[60:61], 0, v[146:147]
	s_mov_b32 m0, s27
	s_nop 0
	global_load_lds_dwordx4 v[216:217], off
	s_mov_b32 m0, s28
	s_nop 0
	global_load_lds_dwordx4 v[218:219], off
	s_waitcnt vmcnt(8)
	s_waitcnt lgkmcnt(0)
	s_barrier
; #define PG8_STAGE(bufoff, gbase, voff) do { _Pragma("unroll") for (int _i = 0; _i < 2; ++_i) \
;         __builtin_amdgcn_global_load_lds((const unsigned*)((const char*)(gbase) + (voff)[_i]), (PG8_LAS unsigned*)(lds + (bufoff) + ldsw + _i * 8192), 16, 0, 0); } while (0)
; #define PG8_LDA(dst, b, h) do { _Pragma("unroll") for (int m = 0; m < 4; ++m) _Pragma("unroll") for (int k = 0; k < 2; ++k) dst[m][k] = *(const PG8_LAS bf16x8*)(lds + PG8_SA(b, h) + aoff + m * 2048 + k * 1024); } while (0)
; #define PG8_LDB(dst, b, h) do { _Pragma("unroll") for (int n = 0; n < 2; ++n) _Pragma("unroll") for (int k = 0; k < 2; ++k) dst[n][k] = *(const PG8_LAS bf16x8*)(lds + PG8_SB(b, h) + boff + n * 2048 + k * 1024); } while (0)
; #define PG8_MMA(ai, bj, At, Bt) do { __builtin_amdgcn_s_setprio(1); _Pragma("unroll") for (int m = 0; m < 4; ++m) _Pragma("unroll") for (int n = 0; n < 2; ++n) _Pragma("unroll") for (int k = 0; k < 2; ++k) \
;         acc[ai][bj][m][n] = __builtin_amdgcn_mfma_f32_16x16x32_bf16(Bt[n][k], At[m][k], acc[ai][bj][m][n], 0, 0, 0); __builtin_amdgcn_s_setprio(0); } while (0)
; #define PG8_WAIT_V(n) asm volatile("s_waitcnt vmcnt(" #n ")" ::: "memory")
; #define PG8_WAIT_L(n) asm volatile("s_waitcnt lgkmcnt(" #n ")" ::: "memory")
; #define PG8_BAR __builtin_amdgcn_s_barrier()
; #define PG8_SCHED __builtin_amdgcn_sched_barrier(0)
; template <class Epi, class Sched, bool ALIGN_EPI = false, bool SP2 = false>
; __device__ __forceinline__ void gemm_phase(PG8_LAS unsigned char* lds, const Gemm g, const Sched& S, const Epi& E) {
;     ...
;             PG8_WAIT_V(8); PG8_WAIT_L(0); PG8_BAR; PG8_MMA(1, 0, At, B0); PG8_MMA(1, 1, At, B1); PG8_BAR; PG8_SCHED;
;             PG8_LDB(B0, 1, 0); PG8_LDB(B1, 1, 1); PG8_SCHED; PG8_LDA(At, 1, 0); PG8_STAGE(PG8_SA(0, 1), a2 + hstep, voffA);
;             PG8_WAIT_V(8); PG8_WAIT_L(0); PG8_BAR; PG8_MMA(0, 0, At, B0); PG8_MMA(0, 1, At, B1); PG8_BAR; PG8_SCHED;
	s_setprio 1
	s_waitcnt lgkmcnt(0)
	v_mfma_f32_16x16x32_bf16 v[62:65], v[130:133], v[178:181], v[62:65]
	v_mfma_f32_16x16x32_bf16 v[58:61], v[138:141], v[178:181], v[58:61]
	v_mfma_f32_16x16x32_bf16 v[54:57], v[130:133], v[186:189], v[54:57]
	v_mfma_f32_16x16x32_bf16 v[46:49], v[138:141], v[186:189], v[46:49]
	v_mfma_f32_16x16x32_bf16 v[38:41], v[130:133], v[198:201], v[38:41]
	v_mfma_f32_16x16x32_bf16 v[30:33], v[138:141], v[198:201], v[30:33]
	v_mfma_f32_16x16x32_bf16 v[22:25], v[130:133], v[206:209], v[22:25]
	v_mfma_f32_16x16x32_bf16 v[14:17], v[138:141], v[206:209], v[14:17]
	v_mfma_f32_16x16x32_bf16 v[62:65], v[134:137], v[182:185], v[62:65]
	v_mfma_f32_16x16x32_bf16 v[58:61], v[142:145], v[182:185], v[58:61]
	v_mfma_f32_16x16x32_bf16 v[54:57], v[134:137], v[194:197], v[54:57]
	v_mfma_f32_16x16x32_bf16 v[46:49], v[142:145], v[194:197], v[46:49]
	v_mfma_f32_16x16x32_bf16 v[38:41], v[134:137], v[202:205], v[38:41]
	v_mfma_f32_16x16x32_bf16 v[30:33], v[142:145], v[202:205], v[30:33]
	v_mfma_f32_16x16x32_bf16 v[22:25], v[134:137], v[210:213], v[22:25]
	v_mfma_f32_16x16x32_bf16 v[14:17], v[142:145], v[210:213], v[14:17]
	s_setprio 0
	s_setprio 1
	v_mfma_f32_16x16x32_bf16 v[50:53], v[156:159], v[178:181], v[50:53]
	v_mfma_f32_16x16x32_bf16 v[42:45], v[170:173], v[178:181], v[42:45]
	v_mfma_f32_16x16x32_bf16 v[34:37], v[156:159], v[186:189], v[34:37]
	v_mfma_f32_16x16x32_bf16 v[26:29], v[170:173], v[186:189], v[26:29]
	v_mfma_f32_16x16x32_bf16 v[18:21], v[156:159], v[198:201], v[18:21]
	v_mfma_f32_16x16x32_bf16 v[10:13], v[170:173], v[198:201], v[10:13]
	v_mfma_f32_16x16x32_bf16 v[6:9], v[156:159], v[206:209], v[6:9]
	v_mfma_f32_16x16x32_bf16 v[2:5], v[170:173], v[206:209], v[2:5]
	v_mfma_f32_16x16x32_bf16 v[50:53], v[160:163], v[182:185], v[50:53]
	v_mfma_f32_16x16x32_bf16 v[42:45], v[174:177], v[182:185], v[42:45]
	v_mfma_f32_16x16x32_bf16 v[34:37], v[160:163], v[194:197], v[34:37]
	v_mfma_f32_16x16x32_bf16 v[26:29], v[174:177], v[194:197], v[26:29]
	v_mfma_f32_16x16x32_bf16 v[18:21], v[160:163], v[202:205], v[18:21]
	v_mfma_f32_16x16x32_bf16 v[10:13], v[174:177], v[202:205], v[10:13]
	v_mfma_f32_16x16x32_bf16 v[6:9], v[160:163], v[210:213], v[6:9]
	v_mfma_f32_16x16x32_bf16 v[2:5], v[174:177], v[210:213], v[2:5]
	s_setprio 0
	s_barrier
	s_add_i32 s53, 0, 0x18000
	s_add_i32 s64, 0, 0x1c000
	v_add_u32_e32 v142, s53, v167
	v_add_u32_e32 v174, s64, v167
	ds_read_b128 v[130:133], v142
	ds_read_b128 v[134:137], v142 offset:1024
	ds_read_b128 v[138:141], v142 offset:2048
	ds_read_b128 v[142:145], v142 offset:3072
	ds_read_b128 v[156:159], v174
	ds_read_b128 v[160:163], v174 offset:1024
	ds_read_b128 v[170:173], v174 offset:2048
	ds_read_b128 v[174:177], v174 offset:3072
	s_add_u32 s60, s60, 0x40000
	s_addc_u32 s61, s61, 0
	s_mov_b32 m0, s29
	v_lshl_add_u64 v[220:221], s[60:61], 0, v[146:147]
	ds_read_b128 v[178:181], v169 offset:32768
	ds_read_b128 v[182:185], v169 offset:33792
	ds_read_b128 v[186:189], v169 offset:34816
	ds_read_b128 v[194:197], v169 offset:35840
	ds_read_b128 v[198:201], v169 offset:36864
	ds_read_b128 v[202:205], v169 offset:37888
	ds_read_b128 v[206:209], v169 offset:38912
	ds_read_b128 v[210:213], v169 offset:39936
	global_load_lds_dwordx4 v[220:221], off
	v_lshl_add_u64 v[220:221], s[60:61], 0, v[148:149]
	s_mov_b32 m0, s47
	s_nop 0
	global_load_lds_dwordx4 v[220:221], off
	s_waitcnt vmcnt(8)
	s_waitcnt lgkmcnt(0)
	s_barrier
	s_setprio 1
	s_waitcnt lgkmcnt(0)
	v_mfma_f32_16x16x32_bf16 v[126:129], v[130:133], v[178:181], v[126:129]
	v_mfma_f32_16x16x32_bf16 v[122:125], v[138:141], v[178:181], v[122:125]
	v_mfma_f32_16x16x32_bf16 v[114:117], v[130:133], v[186:189], v[114:117]
	v_mfma_f32_16x16x32_bf16 v[110:113], v[138:141], v[186:189], v[110:113]
	v_mfma_f32_16x16x32_bf16 v[102:105], v[130:133], v[198:201], v[102:105]
	v_mfma_f32_16x16x32_bf16 v[94:97], v[138:141], v[198:201], v[94:97]
	v_mfma_f32_16x16x32_bf16 v[86:89], v[130:133], v[206:209], v[86:89]
	v_mfma_f32_16x16x32_bf16 v[78:81], v[138:141], v[206:209], v[78:81]
	v_mfma_f32_16x16x32_bf16 v[126:129], v[134:137], v[182:185], v[126:129]
	v_mfma_f32_16x16x32_bf16 v[122:125], v[142:145], v[182:185], v[122:125]
	v_mfma_f32_16x16x32_bf16 v[114:117], v[134:137], v[194:197], v[114:117]
	v_mfma_f32_16x16x32_bf16 v[110:113], v[142:145], v[194:197], v[110:113]
	v_mfma_f32_16x16x32_bf16 v[102:105], v[134:137], v[202:205], v[102:105]
	v_mfma_f32_16x16x32_bf16 v[94:97], v[142:145], v[202:205], v[94:97]
	v_mfma_f32_16x16x32_bf16 v[86:89], v[134:137], v[210:213], v[86:89]
	v_mfma_f32_16x16x32_bf16 v[78:81], v[142:145], v[210:213], v[78:81]
	s_setprio 0
	s_setprio 1
	v_mfma_f32_16x16x32_bf16 v[118:121], v[156:159], v[178:181], v[118:121]
	v_mfma_f32_16x16x32_bf16 v[106:109], v[170:173], v[178:181], v[106:109]
	v_mfma_f32_16x16x32_bf16 v[98:101], v[156:159], v[186:189], v[98:101]
	v_mfma_f32_16x16x32_bf16 v[90:93], v[170:173], v[186:189], v[90:93]
	v_mfma_f32_16x16x32_bf16 v[82:85], v[156:159], v[198:201], v[82:85]
	v_mfma_f32_16x16x32_bf16 v[74:77], v[170:173], v[198:201], v[74:77]
	v_mfma_f32_16x16x32_bf16 v[70:73], v[156:159], v[206:209], v[70:73]
	v_mfma_f32_16x16x32_bf16 v[66:69], v[170:173], v[206:209], v[66:69]
	v_mfma_f32_16x16x32_bf16 v[118:121], v[160:163], v[182:185], v[118:121]
	v_mfma_f32_16x16x32_bf16 v[106:109], v[174:177], v[182:185], v[106:109]
	v_mfma_f32_16x16x32_bf16 v[98:101], v[160:163], v[194:197], v[98:101]
	v_mfma_f32_16x16x32_bf16 v[90:93], v[174:177], v[194:197], v[90:93]
	v_mfma_f32_16x16x32_bf16 v[82:85], v[160:163], v[202:205], v[82:85]
	v_mfma_f32_16x16x32_bf16 v[74:77], v[174:177], v[202:205], v[74:77]
	v_mfma_f32_16x16x32_bf16 v[70:73], v[160:163], v[210:213], v[70:73]
	v_mfma_f32_16x16x32_bf16 v[66:69], v[174:177], v[210:213], v[66:69]
	s_setprio 0
	s_barrier
; #define PG8_STAGE(bufoff, gbase, voff) do { _Pragma("unroll") for (int _i = 0; _i < 2; ++_i) \
;         __builtin_amdgcn_global_load_lds((const unsigned*)((const char*)(gbase) + (voff)[_i]), (PG8_LAS unsigned*)(lds + (bufoff) + ldsw + _i * 8192), 16, 0, 0); } while (0)
; #define PG8_LDA(dst, b, h) do { _Pragma("unroll") for (int m = 0; m < 4; ++m) _Pragma("unroll") for (int k = 0; k < 2; ++k) dst[m][k] = *(const PG8_LAS bf16x8*)(lds + PG8_SA(b, h) + aoff + m * 2048 + k * 1024); } while (0)
; #define PG8_MMA(ai, bj, At, Bt) do { __builtin_amdgcn_s_setprio(1); _Pragma("unroll") for (int m = 0; m < 4; ++m) _Pragma("unroll") for (int n = 0; n < 2; ++n) _Pragma("unroll") for (int k = 0; k < 2; ++k) \
;         acc[ai][bj][m][n] = __builtin_amdgcn_mfma_f32_16x16x32_bf16(Bt[n][k], At[m][k], acc[ai][bj][m][n], 0, 0, 0); __builtin_amdgcn_s_setprio(0); } while (0)
; #define PG8_WAIT_V(n) asm volatile("s_waitcnt vmcnt(" #n ")" ::: "memory")
; #define PG8_WAIT_L(n) asm volatile("s_waitcnt lgkmcnt(" #n ")" ::: "memory")
; #define PG8_BAR __builtin_amdgcn_s_barrier()
; #define PG8_SCHED __builtin_amdgcn_sched_barrier(0)
; template <class Epi, class Sched, bool ALIGN_EPI = false, bool SP2 = false>
; __device__ __forceinline__ void gemm_phase(PG8_LAS unsigned char* lds, const Gemm g, const Sched& S, const Epi& E) {
;     ...
;             PG8_LDA(At, 1, 1); PG8_STAGE(PG8_SB(1, 0), b3, voffB); PG8_STAGE(PG8_SB(1, 1), b3 + hstep, voffB); PG8_STAGE(PG8_SA(1, 0), a3, voffA);
;             PG8_WAIT_V(8); PG8_WAIT_L(0); PG8_BAR; PG8_MMA(1, 0, At, B0); PG8_MMA(1, 1, At, B1); PG8_BAR; PG8_SCHED;
;     ...
;         if constexpr (ALIGN_EPI) { if (wr == 0) PG8_BAR; }
	s_add_i32 s53, s53, s24
	v_lshl_add_u64 v[164:165], v[164:165], 0, s[8:9]
	s_mov_b32 m0, s53
	ds_read_b128 v[178:181], v169 offset:49152
	ds_read_b128 v[182:185], v169 offset:50176
	ds_read_b128 v[186:189], v169 offset:51200
	ds_read_b128 v[194:197], v169 offset:52224
	ds_read_b128 v[198:201], v169 offset:53248
	ds_read_b128 v[202:205], v169 offset:54272
	ds_read_b128 v[206:209], v169 offset:55296
	ds_read_b128 v[210:213], v169 offset:56320
	global_load_lds_dwordx4 v[164:165], off
	s_add_i32 m0, s53, 0x2000
	s_add_u32 s58, s58, 0x40080
	v_lshl_add_u64 v[164:165], v[214:215], 0, s[8:9]
	s_addc_u32 s59, s59, 0
	s_add_i32 s53, s64, s24
	global_load_lds_dwordx4 v[164:165], off
	v_lshl_add_u64 v[164:165], s[58:59], 0, v[0:1]
	s_mov_b32 m0, s53
	s_nop 0
	global_load_lds_dwordx4 v[164:165], off
	v_lshl_add_u64 v[164:165], s[58:59], 0, v[150:151]
	s_add_i32 m0, s53, 0x2000
	s_nop 0
	global_load_lds_dwordx4 v[164:165], off
	v_lshl_add_u64 v[164:165], v[216:217], 0, s[8:9]
	s_mov_b32 m0, s57
	s_nop 0
	global_load_lds_dwordx4 v[164:165], off
	v_lshl_add_u64 v[164:165], v[218:219], 0, s[8:9]
	s_mov_b32 m0, s62
	s_nop 0
	global_load_lds_dwordx4 v[164:165], off
	s_waitcnt vmcnt(8)
	s_waitcnt lgkmcnt(0)
	s_barrier
	s_setprio 1
	s_waitcnt lgkmcnt(0)
	v_mfma_f32_16x16x32_bf16 v[62:65], v[130:133], v[178:181], v[62:65]
	v_mfma_f32_16x16x32_bf16 v[58:61], v[138:141], v[178:181], v[58:61]
	v_mfma_f32_16x16x32_bf16 v[54:57], v[130:133], v[186:189], v[54:57]
	v_mfma_f32_16x16x32_bf16 v[46:49], v[138:141], v[186:189], v[46:49]
	v_mfma_f32_16x16x32_bf16 v[38:41], v[130:133], v[198:201], v[38:41]
	v_mfma_f32_16x16x32_bf16 v[30:33], v[138:141], v[198:201], v[30:33]
	v_mfma_f32_16x16x32_bf16 v[22:25], v[130:133], v[206:209], v[22:25]
	v_mfma_f32_16x16x32_bf16 v[14:17], v[138:141], v[206:209], v[14:17]
	v_mfma_f32_16x16x32_bf16 v[62:65], v[134:137], v[182:185], v[62:65]
	v_mfma_f32_16x16x32_bf16 v[58:61], v[142:145], v[182:185], v[58:61]
	v_mfma_f32_16x16x32_bf16 v[54:57], v[134:137], v[194:197], v[54:57]
	v_mfma_f32_16x16x32_bf16 v[46:49], v[142:145], v[194:197], v[46:49]
	v_mfma_f32_16x16x32_bf16 v[38:41], v[134:137], v[202:205], v[38:41]
	v_mfma_f32_16x16x32_bf16 v[30:33], v[142:145], v[202:205], v[30:33]
	v_mfma_f32_16x16x32_bf16 v[22:25], v[134:137], v[210:213], v[22:25]
	v_mfma_f32_16x16x32_bf16 v[14:17], v[142:145], v[210:213], v[14:17]
	s_setprio 0
	s_setprio 1
	v_mfma_f32_16x16x32_bf16 v[50:53], v[156:159], v[178:181], v[50:53]
	v_mfma_f32_16x16x32_bf16 v[42:45], v[170:173], v[178:181], v[42:45]
	v_mfma_f32_16x16x32_bf16 v[34:37], v[156:159], v[186:189], v[34:37]
	v_mfma_f32_16x16x32_bf16 v[26:29], v[170:173], v[186:189], v[26:29]
	v_mfma_f32_16x16x32_bf16 v[18:21], v[156:159], v[198:201], v[18:21]
	v_mfma_f32_16x16x32_bf16 v[10:13], v[170:173], v[198:201], v[10:13]
	v_mfma_f32_16x16x32_bf16 v[6:9], v[156:159], v[206:209], v[6:9]
	v_mfma_f32_16x16x32_bf16 v[2:5], v[170:173], v[206:209], v[2:5]
	v_mfma_f32_16x16x32_bf16 v[50:53], v[160:163], v[182:185], v[50:53]
	v_mfma_f32_16x16x32_bf16 v[42:45], v[174:177], v[182:185], v[42:45]
	v_mfma_f32_16x16x32_bf16 v[34:37], v[160:163], v[194:197], v[34:37]
	v_mfma_f32_16x16x32_bf16 v[26:29], v[174:177], v[194:197], v[26:29]
	v_mfma_f32_16x16x32_bf16 v[18:21], v[160:163], v[202:205], v[18:21]
	v_mfma_f32_16x16x32_bf16 v[10:13], v[174:177], v[202:205], v[10:13]
	v_mfma_f32_16x16x32_bf16 v[6:9], v[160:163], v[210:213], v[6:9]
	v_mfma_f32_16x16x32_bf16 v[2:5], v[174:177], v[210:213], v[2:5]
	s_setprio 0
	s_barrier
	s_add_i32 s52, s52, 2
	s_add_u32 s18, s18, 0x100
	s_addc_u32 s19, s19, 0
	s_add_u32 s43, s43, 0x100
	s_addc_u32 s45, s45, 0
	s_cmp_gt_u32 s52, 13
	s_cbranch_scc0 .LBB0_291


; #define PG8_BAR __builtin_amdgcn_s_barrier()
; __device__ __forceinline__ float row_rs(const u64* ss, int row) { return __builtin_amdgcn_rsqf((float)ss[row] * SS_INV + 1e-6f); }
; template <class Epi, class Sched, bool ALIGN_EPI = false, bool SP2 = false>
; __device__ __forceinline__ void gemm_phase(PG8_LAS unsigned char* lds, const Gemm g, const Sched& S, const Epi& E) {
;     ...
;         if constexpr (ALIGN_EPI) { if (wr == 0) PG8_BAR; }
;     __device__ __forceinline__ void operator()(const f32x4 (&acc)[2][2][4][2], const pg8::Unit& u, int wr, int wc, int fr, int fq) const {
;         const int row0 = u.pm * 256 + wr * 64 + fr, col0 = u.pn * 256 + wc * 32 + 8 * fq;
;         f32x4 r[2][2];
; #pragma unroll
;         for (int bj = 0; bj < 2; ++bj)
; #pragma unroll
;             for (int n = 0; n < 2; ++n) {
; #pragma unroll
;                 for (int i = 0; i < 4; ++i) r[bj][n][i] = row_rs(ss, col0 + bj * 128 + 4 * n + i); }
.LBB0_294:
	v_lshl_or_b32 v164, s56, 8, v168
	v_ashrrev_i32_e32 v165, 31, v164
	v_lshl_add_u64 v[142:143], v[164:165], 3, s[40:41]
	global_load_dwordx4 v[130:133], v[142:143], off offset:48
	global_load_dwordx4 v[134:137], v[142:143], off offset:32
	global_load_dwordx4 v[138:141], v[142:143], off offset:16
	global_load_dwordx4 v[156:159], v[142:143], off
	s_mov_b64 s[18:19], 0x1000000
	s_and_b64 vcc, exec, s[36:37]
	s_cbranch_vccz .Lalign_go_1
	s_barrier
.Lalign_go_1:
	s_waitcnt vmcnt(0)
	v_ffbh_u32_e32 v144, v157
	v_min_u32_e32 v160, 32, v144
	v_lshlrev_b64 v[144:145], v160, v[156:157]
	v_min_u32_e32 v144, 1, v144
	v_or_b32_e32 v144, v145, v144
	v_cvt_f32_u32_e32 v144, v144
	v_sub_u32_e32 v145, 32, v160
	v_ldexp_f32 v144, v144, v145
	v_fmamk_f32 v144, v144, 0x30800000, v229
	v_rsq_f32_e32 v156, v144
	v_ffbh_u32_e32 v144, v159
	v_min_u32_e32 v157, 32, v144
	v_lshlrev_b64 v[144:145], v157, v[158:159]
	v_min_u32_e32 v144, 1, v144
	v_or_b32_e32 v144, v145, v144
	v_cvt_f32_u32_e32 v144, v144
	v_sub_u32_e32 v145, 32, v157
	v_ldexp_f32 v144, v144, v145
	v_fmamk_f32 v144, v144, 0x30800000, v229
	v_rsq_f32_e32 v157, v144
	v_ffbh_u32_e32 v144, v139
	v_min_u32_e32 v144, 32, v144
	v_lshlrev_b64 v[138:139], v144, v[138:139]
	v_min_u32_e32 v138, 1, v138
	v_or_b32_e32 v138, v139, v138
	v_cvt_f32_u32_e32 v138, v138
	v_sub_u32_e32 v139, 32, v144
	v_pk_mul_f32 v[126:127], v[126:127], v[156:157]
	v_pk_mul_f32 v[62:63], v[62:63], v[156:157]
	v_ldexp_f32 v138, v138, v139
	v_fmamk_f32 v138, v138, 0x30800000, v229
	v_rsq_f32_e32 v158, v138
	v_ffbh_u32_e32 v138, v141
	v_min_u32_e32 v144, 32, v138
	v_lshlrev_b64 v[138:139], v144, v[140:141]
	v_min_u32_e32 v138, 1, v138
	v_or_b32_e32 v138, v139, v138
	v_cvt_f32_u32_e32 v138, v138
	v_sub_u32_e32 v139, 32, v144
	v_ldexp_f32 v138, v138, v139
	v_fmamk_f32 v138, v138, 0x30800000, v229
	v_rsq_f32_e32 v159, v138
	v_ffbh_u32_e32 v138, v135
	v_min_u32_e32 v138, 32, v138
	v_lshlrev_b64 v[134:135], v138, v[134:135]
	v_min_u32_e32 v134, 1, v134
	v_or_b32_e32 v134, v135, v134
	v_cvt_f32_u32_e32 v134, v134
	v_sub_u32_e32 v135, 32, v138
	v_pk_mul_f32 v[128:129], v[128:129], v[158:159]
	v_pk_mul_f32 v[64:65], v[64:65], v[158:159]
	v_ldexp_f32 v134, v134, v135
	v_fmamk_f32 v134, v134, 0x30800000, v229
	v_rsq_f32_e32 v160, v134
	v_ffbh_u32_e32 v134, v137
	v_min_u32_e32 v138, 32, v134
	v_lshlrev_b64 v[134:135], v138, v[136:137]
	v_min_u32_e32 v134, 1, v134
	v_or_b32_e32 v134, v135, v134
	v_cvt_f32_u32_e32 v134, v134
	v_sub_u32_e32 v135, 32, v138
	v_ldexp_f32 v134, v134, v135
	v_fmamk_f32 v134, v134, 0x30800000, v229
	v_rsq_f32_e32 v161, v134
	v_ffbh_u32_e32 v134, v131
	v_min_u32_e32 v134, 32, v134
	v_lshlrev_b64 v[130:131], v134, v[130:131]
	v_min_u32_e32 v130, 1, v130
	v_or_b32_e32 v130, v131, v130
	v_cvt_f32_u32_e32 v130, v130
	v_sub_u32_e32 v131, 32, v134
	v_pk_mul_f32 v[122:123], v[122:123], v[160:161]
	v_pk_mul_f32 v[110:111], v[110:111], v[160:161]
	v_ldexp_f32 v130, v130, v131
	v_fmamk_f32 v130, v130, 0x30800000, v229
	v_rsq_f32_e32 v162, v130
	v_ffbh_u32_e32 v130, v133
	v_min_u32_e32 v134, 32, v130
	v_lshlrev_b64 v[130:131], v134, v[132:133]
	v_min_u32_e32 v130, 1, v130
	v_or_b32_e32 v130, v131, v130
	v_cvt_f32_u32_e32 v130, v130
	v_sub_u32_e32 v131, 32, v134
	v_pk_mul_f32 v[94:95], v[94:95], v[160:161]
	v_pk_mul_f32 v[78:79], v[78:79], v[160:161]
	v_ldexp_f32 v130, v130, v131
	v_fmamk_f32 v130, v130, 0x30800000, v229
	v_rsq_f32_e32 v163, v130
	global_load_dwordx4 v[130:133], v[142:143], off offset:1072
	global_load_dwordx4 v[134:137], v[142:143], off offset:1056
	global_load_dwordx4 v[138:141], v[142:143], off offset:1040
	s_nop 0
	global_load_dwordx4 v[142:145], v[142:143], off offset:1024
	v_pk_mul_f32 v[46:47], v[46:47], v[160:161]
	v_pk_mul_f32 v[30:31], v[30:31], v[160:161]
	v_pk_mul_f32 v[112:113], v[112:113], v[162:163]
	v_pk_mul_f32 v[96:97], v[96:97], v[162:163]
	v_pk_mul_f32 v[80:81], v[80:81], v[162:163]
	v_pk_mul_f32 v[48:49], v[48:49], v[162:163]
	v_pk_mul_f32 v[32:33], v[32:33], v[162:163]
	v_pk_mul_f32 v[14:15], v[14:15], v[160:161]
	v_pk_mul_f32 v[16:17], v[16:17], v[162:163]
	s_waitcnt vmcnt(0)
	v_ffbh_u32_e32 v170, v143
	v_min_u32_e32 v170, 32, v170
	v_lshlrev_b64 v[142:143], v170, v[142:143]
	v_min_u32_e32 v142, 1, v142
	v_or_b32_e32 v142, v143, v142
	v_cvt_f32_u32_e32 v142, v142
	v_sub_u32_e32 v143, 32, v170
	v_ldexp_f32 v142, v142, v143
	v_ffbh_u32_e32 v143, v145
	v_min_u32_e32 v143, 32, v143
	v_lshlrev_b64 v[144:145], v143, v[144:145]
	v_min_u32_e32 v144, 1, v144
	v_or_b32_e32 v144, v145, v144
	v_cvt_f32_u32_e32 v144, v144
	v_sub_u32_e32 v143, 32, v143
	v_fmamk_f32 v142, v142, 0x30800000, v229
	v_rsq_f32_e32 v142, v142
	v_ldexp_f32 v143, v144, v143
	v_ffbh_u32_e32 v144, v139
	v_min_u32_e32 v144, 32, v144
	v_lshlrev_b64 v[138:139], v144, v[138:139]
	v_min_u32_e32 v138, 1, v138
	v_or_b32_e32 v138, v139, v138
	v_cvt_f32_u32_e32 v138, v138
	v_sub_u32_e32 v139, 32, v144
	v_fmamk_f32 v143, v143, 0x30800000, v229
	v_rsq_f32_e32 v143, v143
	v_ldexp_f32 v138, v138, v139
	v_ffbh_u32_e32 v139, v141
	v_min_u32_e32 v139, 32, v139
	v_lshlrev_b64 v[140:141], v139, v[140:141]
	v_min_u32_e32 v140, 1, v140
	v_or_b32_e32 v140, v141, v140
	v_cvt_f32_u32_e32 v140, v140
	v_sub_u32_e32 v139, 32, v139
	v_fmamk_f32 v138, v138, 0x30800000, v229
	v_rsq_f32_e32 v138, v138
	v_ldexp_f32 v139, v140, v139
	v_ffbh_u32_e32 v140, v135
	v_min_u32_e32 v140, 32, v140
	v_lshlrev_b64 v[134:135], v140, v[134:135]
	v_min_u32_e32 v134, 1, v134
	v_or_b32_e32 v134, v135, v134
	v_cvt_f32_u32_e32 v134, v134
	v_sub_u32_e32 v135, 32, v140
	v_fmamk_f32 v139, v139, 0x30800000, v229
	v_rsq_f32_e32 v139, v139
	v_ldexp_f32 v134, v134, v135
; __device__ __forceinline__ float row_rs(const u64* ss, int row) { return __builtin_amdgcn_rsqf((float)ss[row] * SS_INV + 1e-6f); }
; __device__ __forceinline__ unsigned pkbf(float lo, float hi) { const f32x2_t v = {lo, hi}; const bf16x2_t b = __builtin_convertvector(v, bf16x2_t); return __builtin_bit_cast(unsigned, b); }
;     __device__ __forceinline__ void operator()(const f32x4 (&acc)[2][2][4][2], const pg8::Unit& u, int wr, int wc, int fr, int fq) const {
;     ...
;                 for (int i = 0; i < 4; ++i) r[bj][n][i] = row_rs(ss, col0 + bj * 128 + 4 * n + i); }
; #pragma unroll
;         for (int ai = 0; ai < 2; ++ai)
; #pragma unroll
;             for (int m = 0; m < 4; ++m) {
;                 const int row = row0 + ai * 128 + m * 16;
; #pragma unroll
;                 for (int bj = 0; bj < 2; ++bj) { const f32x4 y0 = acc[ai][bj][m][0] * r[bj][0], y1 = acc[ai][bj][m][1] * r[bj][1];
;                     u32x4 w; w.x = pkbf(y0[0], y0[1]); w.y = pkbf(y0[2], y0[3]); w.z = pkbf(y1[0], y1[1]); w.w = pkbf(y1[2], y1[3]);
;                     *(u32x4*)(O + (size_t)row * MTOK + col0 + bj * 128) = w; }
	v_ffbh_u32_e32 v135, v137
	v_min_u32_e32 v135, 32, v135
	v_lshlrev_b64 v[136:137], v135, v[136:137]
	v_min_u32_e32 v136, 1, v136
	v_or_b32_e32 v136, v137, v136
	v_cvt_f32_u32_e32 v136, v136
	v_sub_u32_e32 v135, 32, v135
	v_fmamk_f32 v134, v134, 0x30800000, v229
	v_rsq_f32_e32 v134, v134
	v_ldexp_f32 v135, v136, v135
	v_ffbh_u32_e32 v136, v131
	v_min_u32_e32 v136, 32, v136
	v_lshlrev_b64 v[130:131], v136, v[130:131]
	v_min_u32_e32 v130, 1, v130
	v_or_b32_e32 v130, v131, v130
	v_cvt_f32_u32_e32 v130, v130
	v_sub_u32_e32 v131, 32, v136
	v_fmamk_f32 v135, v135, 0x30800000, v229
	v_rsq_f32_e32 v135, v135
	v_ldexp_f32 v130, v130, v131
	v_ffbh_u32_e32 v131, v133
	v_min_u32_e32 v131, 32, v131
	v_lshlrev_b64 v[132:133], v131, v[132:133]
	v_min_u32_e32 v132, 1, v132
	v_or_b32_e32 v132, v133, v132
	v_cvt_f32_u32_e32 v132, v132
	v_sub_u32_e32 v131, 32, v131
	v_fmamk_f32 v130, v130, 0x30800000, v229
	v_rsq_f32_e32 v130, v130
	v_ldexp_f32 v131, v132, v131
	v_fmamk_f32 v131, v131, 0x30800000, v229
	v_lshl_add_u32 v132, s46, 8, v166
	v_rsq_f32_e32 v131, v131
	v_ashrrev_i32_e32 v133, 31, v132
	v_lshlrev_b64 v[136:137], 17, v[132:133]
	v_pk_mul_f32 v[140:141], v[124:125], v[162:163]
	v_cvt_pk_bf16_f32 v124, v126, v127
	v_cvt_pk_bf16_f32 v125, v128, v129
	v_cvt_pk_bf16_f32 v126, v122, v123
	v_lshl_add_u64 v[122:123], s[4:5], 0, v[136:137]
	v_lshlrev_b64 v[128:129], 1, v[164:165]
	v_cvt_pk_bf16_f32 v127, v140, v141
	v_lshl_add_u64 v[122:123], v[122:123], 0, v[128:129]
	global_store_dwordx4 v[122:123], v[124:127], off
	v_pk_mul_f32 v[120:121], v[120:121], v[138:139]
	v_pk_mul_f32 v[118:119], v[118:119], v[142:143]
	v_pk_mul_f32 v[124:125], v[108:109], v[130:131]
	v_pk_mul_f32 v[108:109], v[106:107], v[134:135]
	v_cvt_pk_bf16_f32 v106, v118, v119
	v_cvt_pk_bf16_f32 v107, v120, v121
	v_cvt_pk_bf16_f32 v108, v108, v109
	v_cvt_pk_bf16_f32 v109, v124, v125
	global_store_dwordx4 v[122:123], v[106:109], off offset:256
	v_pk_mul_f32 v[100:101], v[100:101], v[138:139]
	v_pk_mul_f32 v[98:99], v[98:99], v[142:143]
	v_or_b32_e32 v106, 16, v132
	v_ashrrev_i32_e32 v107, 31, v106
	v_lshlrev_b64 v[118:119], 17, v[106:107]
	v_pk_mul_f32 v[108:109], v[116:117], v[158:159]
	v_pk_mul_f32 v[106:107], v[114:115], v[156:157]
	v_pk_mul_f32 v[84:85], v[84:85], v[138:139]
	v_cvt_pk_bf16_f32 v106, v106, v107
	v_cvt_pk_bf16_f32 v107, v108, v109
	v_cvt_pk_bf16_f32 v108, v110, v111
	v_lshl_add_u64 v[110:111], s[4:5], 0, v[118:119]
	v_cvt_pk_bf16_f32 v109, v112, v113
	v_lshl_add_u64 v[110:111], v[110:111], 0, v[128:129]
	global_store_dwordx4 v[110:111], v[106:109], off
	v_pk_mul_f32 v[82:83], v[82:83], v[142:143]
	v_pk_mul_f32 v[72:73], v[72:73], v[138:139]
	v_pk_mul_f32 v[106:107], v[92:93], v[130:131]
	v_pk_mul_f32 v[92:93], v[90:91], v[134:135]
	v_cvt_pk_bf16_f32 v90, v98, v99
	v_cvt_pk_bf16_f32 v91, v100, v101
	v_cvt_pk_bf16_f32 v92, v92, v93
	v_cvt_pk_bf16_f32 v93, v106, v107
	global_store_dwordx4 v[110:111], v[90:93], off offset:256
	v_pk_mul_f32 v[70:71], v[70:71], v[142:143]
	v_pk_mul_f32 v[52:53], v[52:53], v[138:139]
	v_or_b32_e32 v90, 32, v132
	v_ashrrev_i32_e32 v91, 31, v90
	v_lshlrev_b64 v[98:99], 17, v[90:91]
	v_pk_mul_f32 v[92:93], v[104:105], v[158:159]
	v_pk_mul_f32 v[90:91], v[102:103], v[156:157]
	v_pk_mul_f32 v[50:51], v[50:51], v[142:143]
	v_cvt_pk_bf16_f32 v90, v90, v91
	v_cvt_pk_bf16_f32 v91, v92, v93
	v_cvt_pk_bf16_f32 v92, v94, v95
	v_lshl_add_u64 v[94:95], s[4:5], 0, v[98:99]
	v_cvt_pk_bf16_f32 v93, v96, v97
	v_lshl_add_u64 v[94:95], v[94:95], 0, v[128:129]
	global_store_dwordx4 v[94:95], v[90:93], off
	v_pk_mul_f32 v[36:37], v[36:37], v[138:139]
	v_pk_mul_f32 v[34:35], v[34:35], v[142:143]
	v_pk_mul_f32 v[90:91], v[76:77], v[130:131]
	v_pk_mul_f32 v[76:77], v[74:75], v[134:135]
	v_cvt_pk_bf16_f32 v74, v82, v83
	v_cvt_pk_bf16_f32 v75, v84, v85
	v_cvt_pk_bf16_f32 v76, v76, v77
	v_cvt_pk_bf16_f32 v77, v90, v91
	global_store_dwordx4 v[94:95], v[74:77], off offset:256
	v_pk_mul_f32 v[20:21], v[20:21], v[138:139]
	v_pk_mul_f32 v[18:19], v[18:19], v[142:143]
; #define PG8_BAR __builtin_amdgcn_s_barrier()
; __device__ __forceinline__ unsigned pkbf(float lo, float hi) { const f32x2_t v = {lo, hi}; const bf16x2_t b = __builtin_convertvector(v, bf16x2_t); return __builtin_bit_cast(unsigned, b); }
; template <class Epi, class Sched, bool ALIGN_EPI = false, bool SP2 = false>
; __device__ __forceinline__ void gemm_phase(PG8_LAS unsigned char* lds, const Gemm g, const Sched& S, const Epi& E) {
;     ...
;         cur = nxt; cA = nA; cB = nB; ++ui;
;         if constexpr (ALIGN_EPI) { if (wr == 1) PG8_BAR; }
;     }
;     __device__ __forceinline__ void operator()(const f32x4 (&acc)[2][2][4][2], const pg8::Unit& u, int wr, int wc, int fr, int fq) const {
;     ...
; #pragma unroll
;         for (int ai = 0; ai < 2; ++ai)
; #pragma unroll
;             for (int m = 0; m < 4; ++m) {
;                 const int row = row0 + ai * 128 + m * 16;
; #pragma unroll
;                 for (int bj = 0; bj < 2; ++bj) { const f32x4 y0 = acc[ai][bj][m][0] * r[bj][0], y1 = acc[ai][bj][m][1] * r[bj][1];
;                     u32x4 w; w.x = pkbf(y0[0], y0[1]); w.y = pkbf(y0[2], y0[3]); w.z = pkbf(y1[0], y1[1]); w.w = pkbf(y1[2], y1[3]);
;                     *(u32x4*)(O + (size_t)row * MTOK + col0 + bj * 128) = w; }
;             }
	v_or_b32_e32 v74, 48, v132
	v_ashrrev_i32_e32 v75, 31, v74
	v_lshlrev_b64 v[82:83], 17, v[74:75]
	v_pk_mul_f32 v[76:77], v[88:89], v[158:159]
	v_pk_mul_f32 v[74:75], v[86:87], v[156:157]
	v_pk_mul_f32 v[8:9], v[8:9], v[138:139]
	v_cvt_pk_bf16_f32 v74, v74, v75
	v_cvt_pk_bf16_f32 v75, v76, v77
	v_cvt_pk_bf16_f32 v76, v78, v79
	v_lshl_add_u64 v[78:79], s[4:5], 0, v[82:83]
	v_cvt_pk_bf16_f32 v77, v80, v81
	v_lshl_add_u64 v[78:79], v[78:79], 0, v[128:129]
	global_store_dwordx4 v[78:79], v[74:77], off
	v_pk_mul_f32 v[6:7], v[6:7], v[142:143]
	s_nop 0
	v_pk_mul_f32 v[74:75], v[68:69], v[130:131]
	v_pk_mul_f32 v[68:69], v[66:67], v[134:135]
	v_cvt_pk_bf16_f32 v66, v70, v71
	v_cvt_pk_bf16_f32 v67, v72, v73
	v_cvt_pk_bf16_f32 v68, v68, v69
	v_cvt_pk_bf16_f32 v69, v74, v75
	global_store_dwordx4 v[78:79], v[66:69], off offset:256
	s_nop 1
	v_pk_mul_f32 v[66:67], v[60:61], v[162:163]
	v_pk_mul_f32 v[60:61], v[58:59], v[160:161]
	v_cvt_pk_bf16_f32 v58, v62, v63
	v_lshl_add_u64 v[62:63], v[122:123], 0, s[18:19]
	s_mov_b32 s18, 0x1000000
	v_cvt_pk_bf16_f32 v59, v64, v65
	v_add_co_u32_e32 v64, vcc, s18, v122
	v_cvt_pk_bf16_f32 v60, v60, v61
	v_cvt_pk_bf16_f32 v61, v66, v67
	v_addc_co_u32_e32 v65, vcc, 0, v123, vcc
	global_store_dwordx4 v[64:65], v[58:61], off
	s_mov_b64 s[18:19], 0x1200000
	s_nop 0
	v_pk_mul_f32 v[58:59], v[44:45], v[130:131]
	v_pk_mul_f32 v[44:45], v[42:43], v[134:135]
	v_cvt_pk_bf16_f32 v42, v50, v51
	v_cvt_pk_bf16_f32 v43, v52, v53
	v_cvt_pk_bf16_f32 v44, v44, v45
	v_cvt_pk_bf16_f32 v45, v58, v59
	global_store_dwordx4 v[62:63], v[42:45], off offset:256
	s_nop 1
	v_pk_mul_f32 v[44:45], v[56:57], v[158:159]
	v_pk_mul_f32 v[42:43], v[54:55], v[156:157]
	s_nop 0
	v_cvt_pk_bf16_f32 v42, v42, v43
	v_cvt_pk_bf16_f32 v43, v44, v45
	v_cvt_pk_bf16_f32 v44, v46, v47
	v_lshl_add_u64 v[46:47], v[122:123], 0, s[18:19]
	s_mov_b32 s18, 0x1200000
	v_cvt_pk_bf16_f32 v45, v48, v49
	v_add_co_u32_e32 v48, vcc, s18, v122
	s_mov_b64 s[18:19], 0x1400000
	s_nop 0
	v_addc_co_u32_e32 v49, vcc, 0, v123, vcc
	global_store_dwordx4 v[48:49], v[42:45], off
	s_nop 1
	v_pk_mul_f32 v[42:43], v[28:29], v[130:131]
	v_pk_mul_f32 v[28:29], v[26:27], v[134:135]
	v_cvt_pk_bf16_f32 v26, v34, v35
	v_cvt_pk_bf16_f32 v27, v36, v37
	v_cvt_pk_bf16_f32 v28, v28, v29
	v_cvt_pk_bf16_f32 v29, v42, v43
	global_store_dwordx4 v[46:47], v[26:29], off offset:256
	s_nop 1
	v_pk_mul_f32 v[28:29], v[40:41], v[158:159]
	v_pk_mul_f32 v[26:27], v[38:39], v[156:157]
	s_nop 0
	v_cvt_pk_bf16_f32 v26, v26, v27
	v_cvt_pk_bf16_f32 v27, v28, v29
	v_cvt_pk_bf16_f32 v28, v30, v31
	v_lshl_add_u64 v[30:31], v[122:123], 0, s[18:19]
	s_mov_b32 s18, 0x1400000
	v_cvt_pk_bf16_f32 v29, v32, v33
	v_add_co_u32_e32 v32, vcc, s18, v122
	s_mov_b64 s[18:19], 0x1600000
	s_nop 0
	v_addc_co_u32_e32 v33, vcc, 0, v123, vcc
	global_store_dwordx4 v[32:33], v[26:29], off
	s_nop 1
	v_pk_mul_f32 v[26:27], v[12:13], v[130:131]
	v_pk_mul_f32 v[12:13], v[10:11], v[134:135]
	v_cvt_pk_bf16_f32 v10, v18, v19
	v_cvt_pk_bf16_f32 v11, v20, v21
	v_cvt_pk_bf16_f32 v12, v12, v13
	v_cvt_pk_bf16_f32 v13, v26, v27
	global_store_dwordx4 v[30:31], v[10:13], off offset:256
	s_nop 1
	v_pk_mul_f32 v[12:13], v[24:25], v[158:159]
	v_pk_mul_f32 v[10:11], v[22:23], v[156:157]
	s_nop 0
	v_cvt_pk_bf16_f32 v10, v10, v11
	v_cvt_pk_bf16_f32 v11, v12, v13
	v_cvt_pk_bf16_f32 v12, v14, v15
	v_lshl_add_u64 v[14:15], v[122:123], 0, s[18:19]
	s_mov_b32 s18, 0x1600000
	v_cvt_pk_bf16_f32 v13, v16, v17
	v_add_co_u32_e32 v16, vcc, s18, v122
	s_mov_b64 s[18:19], -1
	s_nop 0
	v_addc_co_u32_e32 v17, vcc, 0, v123, vcc
	global_store_dwordx4 v[16:17], v[10:13], off
	s_andn2_b64 vcc, exec, s[48:49]
	s_nop 0
	v_pk_mul_f32 v[10:11], v[4:5], v[130:131]
	v_pk_mul_f32 v[4:5], v[2:3], v[134:135]
	v_cvt_pk_bf16_f32 v2, v6, v7
	v_cvt_pk_bf16_f32 v3, v8, v9
	v_cvt_pk_bf16_f32 v4, v4, v5
	v_cvt_pk_bf16_f32 v5, v10, v11
	global_store_dwordx4 v[14:15], v[2:5], off offset:256
	s_cbranch_vccnz .LBB0_279
	s_andn2_b64 vcc, exec, s[0:1]
	s_cbranch_vccnz .LBB0_278
	s_barrier
	s_branch .LBB0_278

; #define PG8_STAGE(bufoff, gbase, voff) do { _Pragma("unroll") for (int _i = 0; _i < 2; ++_i) \
;         __builtin_amdgcn_global_load_lds((const unsigned*)((const char*)(gbase) + (voff)[_i]), (PG8_LAS unsigned*)(lds + (bufoff) + ldsw + _i * 8192), 16, 0, 0); } while (0)
; #define PG8_LDA(dst, b, h) do { _Pragma("unroll") for (int m = 0; m < 4; ++m) _Pragma("unroll") for (int k = 0; k < 2; ++k) dst[m][k] = *(const PG8_LAS bf16x8*)(lds + PG8_SA(b, h) + aoff + m * 2048 + k * 1024); } while (0)
; #define PG8_LDB(dst, b, h) do { _Pragma("unroll") for (int n = 0; n < 2; ++n) _Pragma("unroll") for (int k = 0; k < 2; ++k) dst[n][k] = *(const PG8_LAS bf16x8*)(lds + PG8_SB(b, h) + boff + n * 2048 + k * 1024); } while (0)
; #define PG8_MMA(ai, bj, At, Bt) do { __builtin_amdgcn_s_setprio(1); _Pragma("unroll") for (int m = 0; m < 4; ++m) _Pragma("unroll") for (int n = 0; n < 2; ++n) _Pragma("unroll") for (int k = 0; k < 2; ++k) \
;         acc[ai][bj][m][n] = __builtin_amdgcn_mfma_f32_16x16x32_bf16(Bt[n][k], At[m][k], acc[ai][bj][m][n], 0, 0, 0); __builtin_amdgcn_s_setprio(0); } while (0)
; #define PG8_WAIT_V(n) asm volatile("s_waitcnt vmcnt(" #n ")" ::: "memory")
; #define PG8_WAIT_L(n) asm volatile("s_waitcnt lgkmcnt(" #n ")" ::: "memory")
; #define PG8_BAR __builtin_amdgcn_s_barrier()
; #define PG8_SCHED __builtin_amdgcn_sched_barrier(0)
; template <class Epi, class Sched, bool ALIGN_EPI = false, bool SP2 = false>
; __device__ __forceinline__ void gemm_phase(PG8_LAS unsigned char* lds, const Gemm g, const Sched& S, const Epi& E) {
;     ...
;             PG8_LDB(B0, 0, 0); PG8_LDB(B1, 0, 1); PG8_SCHED; PG8_LDA(At, 0, 0); PG8_STAGE(PG8_SA(1, 1), a1 + hstep, voffA);
;             PG8_WAIT_V(8); PG8_WAIT_L(0); PG8_BAR; PG8_MMA(0, 0, At, B0); PG8_MMA(0, 1, At, B1); PG8_BAR; PG8_SCHED;
;             PG8_LDA(At, 0, 1); PG8_STAGE(PG8_SB(0, 0), b2, voffB); PG8_STAGE(PG8_SB(0, 1), b2 + hstep, voffB); PG8_STAGE(PG8_SA(0, 0), a2, voffA);
;             PG8_WAIT_V(8); PG8_WAIT_L(0); PG8_BAR; PG8_MMA(1, 0, At, B0); PG8_MMA(1, 1, At, B1); PG8_BAR; PG8_SCHED;
.LBB0_487:
	s_add_u32 s53, s18, 0xfffc0080
	s_addc_u32 s60, s19, -1
	s_add_i32 s64, 0, 0x10000
	s_cmp_eq_u32 s52, 12
	s_cselect_b32 s63, s30, s60
	s_cselect_b32 s62, s31, s53
	s_cselect_b32 s61, s34, s47
	s_cselect_b32 s60, s35, s45
	s_add_i32 s53, 0, 0x14000
	v_add_u32_e32 v134, s64, v239
	v_add_u32_e32 v158, s53, v239
	ds_read_b128 v[122:125], v134
	ds_read_b128 v[126:129], v134 offset:1024
	ds_read_b128 v[130:133], v134 offset:2048
	ds_read_b128 v[134:137], v134 offset:3072
	ds_read_b128 v[138:141], v158
	ds_read_b128 v[142:145], v158 offset:1024
	ds_read_b128 v[146:149], v158 offset:2048
	ds_read_b128 v[158:161], v158 offset:3072
	v_lshl_add_u64 v[212:213], s[18:19], 0, v[204:205]
	s_add_i32 m0, s25, 0xc000
	ds_read_b128 v[162:165], v241
	ds_read_b128 v[166:169], v241 offset:1024
	ds_read_b128 v[170:173], v241 offset:2048
	ds_read_b128 v[174:177], v241 offset:3072
	ds_read_b128 v[178:181], v241 offset:4096
	ds_read_b128 v[182:185], v241 offset:5120
	ds_read_b128 v[186:189], v241 offset:6144
	ds_read_b128 v[208:211], v241 offset:7168
	global_load_lds_dwordx4 v[212:213], off
	v_lshl_add_u64 v[212:213], s[18:19], 0, v[206:207]
	s_add_i32 m0, s25, 0xe000
	s_nop 0
	global_load_lds_dwordx4 v[212:213], off
	s_waitcnt vmcnt(8)
	s_waitcnt lgkmcnt(0)
	s_barrier
	s_setprio 1
	s_waitcnt lgkmcnt(0)
	v_mfma_f32_16x16x32_bf16 v[154:157], v[122:125], v[162:165], v[154:157]
	v_mfma_f32_16x16x32_bf16 v[150:153], v[130:133], v[162:165], v[150:153]
	v_mfma_f32_16x16x32_bf16 v[110:113], v[122:125], v[170:173], v[110:113]
	v_mfma_f32_16x16x32_bf16 v[106:109], v[130:133], v[170:173], v[106:109]
	v_mfma_f32_16x16x32_bf16 v[94:97], v[122:125], v[178:181], v[94:97]
	v_mfma_f32_16x16x32_bf16 v[90:93], v[130:133], v[178:181], v[90:93]
	v_mfma_f32_16x16x32_bf16 v[78:81], v[122:125], v[186:189], v[78:81]
	v_mfma_f32_16x16x32_bf16 v[74:77], v[130:133], v[186:189], v[74:77]
	v_mfma_f32_16x16x32_bf16 v[154:157], v[126:129], v[166:169], v[154:157]
	v_mfma_f32_16x16x32_bf16 v[150:153], v[134:137], v[166:169], v[150:153]
	v_mfma_f32_16x16x32_bf16 v[110:113], v[126:129], v[174:177], v[110:113]
	v_mfma_f32_16x16x32_bf16 v[106:109], v[134:137], v[174:177], v[106:109]
	v_mfma_f32_16x16x32_bf16 v[94:97], v[126:129], v[182:185], v[94:97]
	v_mfma_f32_16x16x32_bf16 v[90:93], v[134:137], v[182:185], v[90:93]
	v_mfma_f32_16x16x32_bf16 v[78:81], v[126:129], v[208:211], v[78:81]
	v_mfma_f32_16x16x32_bf16 v[74:77], v[134:137], v[208:211], v[74:77]
	s_setprio 0
	s_setprio 1
	v_mfma_f32_16x16x32_bf16 v[118:121], v[138:141], v[162:165], v[118:121]
	v_mfma_f32_16x16x32_bf16 v[114:117], v[146:149], v[162:165], v[114:117]
	v_mfma_f32_16x16x32_bf16 v[102:105], v[138:141], v[170:173], v[102:105]
	v_mfma_f32_16x16x32_bf16 v[98:101], v[146:149], v[170:173], v[98:101]
	v_mfma_f32_16x16x32_bf16 v[86:89], v[138:141], v[178:181], v[86:89]
	v_mfma_f32_16x16x32_bf16 v[82:85], v[146:149], v[178:181], v[82:85]
	v_mfma_f32_16x16x32_bf16 v[70:73], v[138:141], v[186:189], v[70:73]
	v_mfma_f32_16x16x32_bf16 v[66:69], v[146:149], v[186:189], v[66:69]
	v_mfma_f32_16x16x32_bf16 v[118:121], v[142:145], v[166:169], v[118:121]
	v_mfma_f32_16x16x32_bf16 v[114:117], v[158:161], v[166:169], v[114:117]
	v_mfma_f32_16x16x32_bf16 v[102:105], v[142:145], v[174:177], v[102:105]
	v_mfma_f32_16x16x32_bf16 v[98:101], v[158:161], v[174:177], v[98:101]
	v_mfma_f32_16x16x32_bf16 v[86:89], v[142:145], v[182:185], v[86:89]
	v_mfma_f32_16x16x32_bf16 v[82:85], v[158:161], v[182:185], v[82:85]
	v_mfma_f32_16x16x32_bf16 v[70:73], v[142:145], v[208:211], v[70:73]
	v_mfma_f32_16x16x32_bf16 v[66:69], v[158:161], v[208:211], v[66:69]
	s_setprio 0
	s_barrier
	s_add_i32 s64, s64, s24
	v_lshl_add_u64 v[212:213], s[60:61], 0, v[0:1]
	s_mov_b32 m0, s64
	ds_read_b128 v[162:165], v241 offset:16384
	ds_read_b128 v[166:169], v241 offset:17408
	ds_read_b128 v[170:173], v241 offset:18432
	ds_read_b128 v[174:177], v241 offset:19456
	ds_read_b128 v[178:181], v241 offset:20480
	ds_read_b128 v[182:185], v241 offset:21504
	ds_read_b128 v[186:189], v241 offset:22528
	ds_read_b128 v[208:211], v241 offset:23552
	global_load_lds_dwordx4 v[212:213], off
	s_add_i32 m0, s64, 0x2000
	s_add_u32 s64, s60, 0x40000
	v_lshl_add_u64 v[214:215], s[60:61], 0, v[198:199]
	s_addc_u32 s65, s61, 0
	s_add_i32 s53, s53, s24
	global_load_lds_dwordx4 v[214:215], off
	v_lshl_add_u64 v[216:217], s[64:65], 0, v[0:1]
	s_mov_b32 m0, s53
	v_lshl_add_u64 v[218:219], s[62:63], 0, v[196:197]
	global_load_lds_dwordx4 v[216:217], off
	v_lshl_add_u64 v[216:217], s[64:65], 0, v[198:199]
	s_add_i32 m0, s53, 0x2000
	s_nop 0
	global_load_lds_dwordx4 v[216:217], off
	v_lshl_add_u64 v[216:217], s[62:63], 0, v[194:195]
	s_mov_b32 m0, s25
	s_nop 0
	global_load_lds_dwordx4 v[216:217], off
	s_mov_b32 m0, s26
	s_nop 0
	global_load_lds_dwordx4 v[218:219], off
	s_waitcnt vmcnt(8)
	s_waitcnt lgkmcnt(0)
	s_barrier
; #define PG8_STAGE(bufoff, gbase, voff) do { _Pragma("unroll") for (int _i = 0; _i < 2; ++_i) \
;         __builtin_amdgcn_global_load_lds((const unsigned*)((const char*)(gbase) + (voff)[_i]), (PG8_LAS unsigned*)(lds + (bufoff) + ldsw + _i * 8192), 16, 0, 0); } while (0)
; #define PG8_LDA(dst, b, h) do { _Pragma("unroll") for (int m = 0; m < 4; ++m) _Pragma("unroll") for (int k = 0; k < 2; ++k) dst[m][k] = *(const PG8_LAS bf16x8*)(lds + PG8_SA(b, h) + aoff + m * 2048 + k * 1024); } while (0)
; #define PG8_LDB(dst, b, h) do { _Pragma("unroll") for (int n = 0; n < 2; ++n) _Pragma("unroll") for (int k = 0; k < 2; ++k) dst[n][k] = *(const PG8_LAS bf16x8*)(lds + PG8_SB(b, h) + boff + n * 2048 + k * 1024); } while (0)
; #define PG8_MMA(ai, bj, At, Bt) do { __builtin_amdgcn_s_setprio(1); _Pragma("unroll") for (int m = 0; m < 4; ++m) _Pragma("unroll") for (int n = 0; n < 2; ++n) _Pragma("unroll") for (int k = 0; k < 2; ++k) \
;         acc[ai][bj][m][n] = __builtin_amdgcn_mfma_f32_16x16x32_bf16(Bt[n][k], At[m][k], acc[ai][bj][m][n], 0, 0, 0); __builtin_amdgcn_s_setprio(0); } while (0)
; #define PG8_WAIT_V(n) asm volatile("s_waitcnt vmcnt(" #n ")" ::: "memory")
; #define PG8_WAIT_L(n) asm volatile("s_waitcnt lgkmcnt(" #n ")" ::: "memory")
; #define PG8_BAR __builtin_amdgcn_s_barrier()
; #define PG8_SCHED __builtin_amdgcn_sched_barrier(0)
; template <class Epi, class Sched, bool ALIGN_EPI = false, bool SP2 = false>
; __device__ __forceinline__ void gemm_phase(PG8_LAS unsigned char* lds, const Gemm g, const Sched& S, const Epi& E) {
;     ...
;             PG8_WAIT_V(8); PG8_WAIT_L(0); PG8_BAR; PG8_MMA(1, 0, At, B0); PG8_MMA(1, 1, At, B1); PG8_BAR; PG8_SCHED;
;             PG8_LDB(B0, 1, 0); PG8_LDB(B1, 1, 1); PG8_SCHED; PG8_LDA(At, 1, 0); PG8_STAGE(PG8_SA(0, 1), a2 + hstep, voffA);
;             PG8_WAIT_V(8); PG8_WAIT_L(0); PG8_BAR; PG8_MMA(0, 0, At, B0); PG8_MMA(0, 1, At, B1); PG8_BAR; PG8_SCHED;
	s_setprio 1
	s_waitcnt lgkmcnt(0)
	v_mfma_f32_16x16x32_bf16 v[62:65], v[122:125], v[162:165], v[62:65]
	v_mfma_f32_16x16x32_bf16 v[58:61], v[130:133], v[162:165], v[58:61]
	v_mfma_f32_16x16x32_bf16 v[46:49], v[122:125], v[170:173], v[46:49]
	v_mfma_f32_16x16x32_bf16 v[42:45], v[130:133], v[170:173], v[42:45]
	v_mfma_f32_16x16x32_bf16 v[30:33], v[122:125], v[178:181], v[30:33]
	v_mfma_f32_16x16x32_bf16 v[26:29], v[130:133], v[178:181], v[26:29]
	v_mfma_f32_16x16x32_bf16 v[14:17], v[122:125], v[186:189], v[14:17]
	v_mfma_f32_16x16x32_bf16 v[10:13], v[130:133], v[186:189], v[10:13]
	v_mfma_f32_16x16x32_bf16 v[62:65], v[126:129], v[166:169], v[62:65]
	v_mfma_f32_16x16x32_bf16 v[58:61], v[134:137], v[166:169], v[58:61]
	v_mfma_f32_16x16x32_bf16 v[46:49], v[126:129], v[174:177], v[46:49]
	v_mfma_f32_16x16x32_bf16 v[42:45], v[134:137], v[174:177], v[42:45]
	v_mfma_f32_16x16x32_bf16 v[30:33], v[126:129], v[182:185], v[30:33]
	v_mfma_f32_16x16x32_bf16 v[26:29], v[134:137], v[182:185], v[26:29]
	v_mfma_f32_16x16x32_bf16 v[14:17], v[126:129], v[208:211], v[14:17]
	v_mfma_f32_16x16x32_bf16 v[10:13], v[134:137], v[208:211], v[10:13]
	s_setprio 0
	s_setprio 1
	v_mfma_f32_16x16x32_bf16 v[54:57], v[138:141], v[162:165], v[54:57]
	v_mfma_f32_16x16x32_bf16 v[50:53], v[146:149], v[162:165], v[50:53]
	v_mfma_f32_16x16x32_bf16 v[38:41], v[138:141], v[170:173], v[38:41]
	v_mfma_f32_16x16x32_bf16 v[34:37], v[146:149], v[170:173], v[34:37]
	v_mfma_f32_16x16x32_bf16 v[22:25], v[138:141], v[178:181], v[22:25]
	v_mfma_f32_16x16x32_bf16 v[18:21], v[146:149], v[178:181], v[18:21]
	v_mfma_f32_16x16x32_bf16 v[6:9], v[138:141], v[186:189], v[6:9]
	v_mfma_f32_16x16x32_bf16 v[2:5], v[146:149], v[186:189], v[2:5]
	v_mfma_f32_16x16x32_bf16 v[54:57], v[142:145], v[166:169], v[54:57]
	v_mfma_f32_16x16x32_bf16 v[50:53], v[158:161], v[166:169], v[50:53]
	v_mfma_f32_16x16x32_bf16 v[38:41], v[142:145], v[174:177], v[38:41]
	v_mfma_f32_16x16x32_bf16 v[34:37], v[158:161], v[174:177], v[34:37]
	v_mfma_f32_16x16x32_bf16 v[22:25], v[142:145], v[182:185], v[22:25]
	v_mfma_f32_16x16x32_bf16 v[18:21], v[158:161], v[182:185], v[18:21]
	v_mfma_f32_16x16x32_bf16 v[6:9], v[142:145], v[208:211], v[6:9]
	v_mfma_f32_16x16x32_bf16 v[2:5], v[158:161], v[208:211], v[2:5]
	s_setprio 0
	s_barrier
	s_add_i32 s53, 0, 0x18000
	s_add_i32 s64, 0, 0x1c000
	v_add_u32_e32 v134, s53, v239
	v_add_u32_e32 v158, s64, v239
	ds_read_b128 v[122:125], v134
	ds_read_b128 v[126:129], v134 offset:1024
	ds_read_b128 v[130:133], v134 offset:2048
	ds_read_b128 v[134:137], v134 offset:3072
	ds_read_b128 v[138:141], v158
	ds_read_b128 v[142:145], v158 offset:1024
	ds_read_b128 v[146:149], v158 offset:2048
	ds_read_b128 v[158:161], v158 offset:3072
	s_add_u32 s62, s62, 0x40000
	s_addc_u32 s63, s63, 0
	s_mov_b32 m0, s27
	v_lshl_add_u64 v[220:221], s[62:63], 0, v[194:195]
	ds_read_b128 v[162:165], v241 offset:32768
	ds_read_b128 v[166:169], v241 offset:33792
	ds_read_b128 v[170:173], v241 offset:34816
	ds_read_b128 v[174:177], v241 offset:35840
	ds_read_b128 v[178:181], v241 offset:36864
	ds_read_b128 v[182:185], v241 offset:37888
	ds_read_b128 v[186:189], v241 offset:38912
	ds_read_b128 v[208:211], v241 offset:39936
	global_load_lds_dwordx4 v[220:221], off
	v_lshl_add_u64 v[220:221], s[62:63], 0, v[196:197]
	s_mov_b32 m0, s28
	s_nop 0
	global_load_lds_dwordx4 v[220:221], off
	s_waitcnt vmcnt(8)
	s_waitcnt lgkmcnt(0)
	s_barrier
	s_setprio 1
	s_waitcnt lgkmcnt(0)
	v_mfma_f32_16x16x32_bf16 v[154:157], v[122:125], v[162:165], v[154:157]
	v_mfma_f32_16x16x32_bf16 v[150:153], v[130:133], v[162:165], v[150:153]
	v_mfma_f32_16x16x32_bf16 v[110:113], v[122:125], v[170:173], v[110:113]
	v_mfma_f32_16x16x32_bf16 v[106:109], v[130:133], v[170:173], v[106:109]
	v_mfma_f32_16x16x32_bf16 v[94:97], v[122:125], v[178:181], v[94:97]
	v_mfma_f32_16x16x32_bf16 v[90:93], v[130:133], v[178:181], v[90:93]
	v_mfma_f32_16x16x32_bf16 v[78:81], v[122:125], v[186:189], v[78:81]
	v_mfma_f32_16x16x32_bf16 v[74:77], v[130:133], v[186:189], v[74:77]
	v_mfma_f32_16x16x32_bf16 v[154:157], v[126:129], v[166:169], v[154:157]
	v_mfma_f32_16x16x32_bf16 v[150:153], v[134:137], v[166:169], v[150:153]
	v_mfma_f32_16x16x32_bf16 v[110:113], v[126:129], v[174:177], v[110:113]
	v_mfma_f32_16x16x32_bf16 v[106:109], v[134:137], v[174:177], v[106:109]
	v_mfma_f32_16x16x32_bf16 v[94:97], v[126:129], v[182:185], v[94:97]
	v_mfma_f32_16x16x32_bf16 v[90:93], v[134:137], v[182:185], v[90:93]
	v_mfma_f32_16x16x32_bf16 v[78:81], v[126:129], v[208:211], v[78:81]
	v_mfma_f32_16x16x32_bf16 v[74:77], v[134:137], v[208:211], v[74:77]
	s_setprio 0
	s_setprio 1
	v_mfma_f32_16x16x32_bf16 v[118:121], v[138:141], v[162:165], v[118:121]
	v_mfma_f32_16x16x32_bf16 v[114:117], v[146:149], v[162:165], v[114:117]
	v_mfma_f32_16x16x32_bf16 v[102:105], v[138:141], v[170:173], v[102:105]
	v_mfma_f32_16x16x32_bf16 v[98:101], v[146:149], v[170:173], v[98:101]
	v_mfma_f32_16x16x32_bf16 v[86:89], v[138:141], v[178:181], v[86:89]
	v_mfma_f32_16x16x32_bf16 v[82:85], v[146:149], v[178:181], v[82:85]
	v_mfma_f32_16x16x32_bf16 v[70:73], v[138:141], v[186:189], v[70:73]
	v_mfma_f32_16x16x32_bf16 v[66:69], v[146:149], v[186:189], v[66:69]
	v_mfma_f32_16x16x32_bf16 v[118:121], v[142:145], v[166:169], v[118:121]
	v_mfma_f32_16x16x32_bf16 v[114:117], v[158:161], v[166:169], v[114:117]
	v_mfma_f32_16x16x32_bf16 v[102:105], v[142:145], v[174:177], v[102:105]
	v_mfma_f32_16x16x32_bf16 v[98:101], v[158:161], v[174:177], v[98:101]
	v_mfma_f32_16x16x32_bf16 v[86:89], v[142:145], v[182:185], v[86:89]
	v_mfma_f32_16x16x32_bf16 v[82:85], v[158:161], v[182:185], v[82:85]
	v_mfma_f32_16x16x32_bf16 v[70:73], v[142:145], v[208:211], v[70:73]
	v_mfma_f32_16x16x32_bf16 v[66:69], v[158:161], v[208:211], v[66:69]
	s_setprio 0
	s_barrier
; #define PG8_STAGE(bufoff, gbase, voff) do { _Pragma("unroll") for (int _i = 0; _i < 2; ++_i) \
;         __builtin_amdgcn_global_load_lds((const unsigned*)((const char*)(gbase) + (voff)[_i]), (PG8_LAS unsigned*)(lds + (bufoff) + ldsw + _i * 8192), 16, 0, 0); } while (0)
; #define PG8_LDA(dst, b, h) do { _Pragma("unroll") for (int m = 0; m < 4; ++m) _Pragma("unroll") for (int k = 0; k < 2; ++k) dst[m][k] = *(const PG8_LAS bf16x8*)(lds + PG8_SA(b, h) + aoff + m * 2048 + k * 1024); } while (0)
; #define PG8_MMA(ai, bj, At, Bt) do { __builtin_amdgcn_s_setprio(1); _Pragma("unroll") for (int m = 0; m < 4; ++m) _Pragma("unroll") for (int n = 0; n < 2; ++n) _Pragma("unroll") for (int k = 0; k < 2; ++k) \
;         acc[ai][bj][m][n] = __builtin_amdgcn_mfma_f32_16x16x32_bf16(Bt[n][k], At[m][k], acc[ai][bj][m][n], 0, 0, 0); __builtin_amdgcn_s_setprio(0); } while (0)
; #define PG8_WAIT_V(n) asm volatile("s_waitcnt vmcnt(" #n ")" ::: "memory")
; #define PG8_WAIT_L(n) asm volatile("s_waitcnt lgkmcnt(" #n ")" ::: "memory")
; #define PG8_BAR __builtin_amdgcn_s_barrier()
; #define PG8_SCHED __builtin_amdgcn_sched_barrier(0)
; template <class Epi, class Sched, bool ALIGN_EPI = false, bool SP2 = false>
; __device__ __forceinline__ void gemm_phase(PG8_LAS unsigned char* lds, const Gemm g, const Sched& S, const Epi& E) {
;     ...
;             PG8_LDA(At, 1, 1); PG8_STAGE(PG8_SB(1, 0), b3, voffB); PG8_STAGE(PG8_SB(1, 1), b3 + hstep, voffB); PG8_STAGE(PG8_SA(1, 0), a3, voffA);
;             PG8_WAIT_V(8); PG8_WAIT_L(0); PG8_BAR; PG8_MMA(1, 0, At, B0); PG8_MMA(1, 1, At, B1); PG8_BAR; PG8_SCHED;
;     ...
;         if constexpr (ALIGN_EPI) { if (wr == 0) PG8_BAR; }
	s_add_i32 s53, s53, s24
	v_lshl_add_u64 v[212:213], v[212:213], 0, s[8:9]
	s_mov_b32 m0, s53
	ds_read_b128 v[162:165], v241 offset:49152
	ds_read_b128 v[166:169], v241 offset:50176
	ds_read_b128 v[170:173], v241 offset:51200
	ds_read_b128 v[174:177], v241 offset:52224
	ds_read_b128 v[178:181], v241 offset:53248
	ds_read_b128 v[182:185], v241 offset:54272
	ds_read_b128 v[186:189], v241 offset:55296
	ds_read_b128 v[208:211], v241 offset:56320
	global_load_lds_dwordx4 v[212:213], off
	s_add_i32 m0, s53, 0x2000
	s_add_u32 s60, s60, 0x40080
	v_lshl_add_u64 v[212:213], v[214:215], 0, s[8:9]
	s_addc_u32 s61, s61, 0
	s_add_i32 s53, s64, s24
	global_load_lds_dwordx4 v[212:213], off
	v_lshl_add_u64 v[212:213], s[60:61], 0, v[0:1]
	s_mov_b32 m0, s53
	s_nop 0
	global_load_lds_dwordx4 v[212:213], off
	v_lshl_add_u64 v[212:213], s[60:61], 0, v[198:199]
	s_add_i32 m0, s53, 0x2000
	s_nop 0
	global_load_lds_dwordx4 v[212:213], off
	v_lshl_add_u64 v[212:213], v[216:217], 0, s[8:9]
	s_mov_b32 m0, s29
	s_nop 0
	global_load_lds_dwordx4 v[212:213], off
	v_lshl_add_u64 v[212:213], v[218:219], 0, s[8:9]
	s_mov_b32 m0, s57
	s_nop 0
	global_load_lds_dwordx4 v[212:213], off
	s_waitcnt vmcnt(8)
	s_waitcnt lgkmcnt(0)
	s_barrier
	s_setprio 1
	s_waitcnt lgkmcnt(0)
	v_mfma_f32_16x16x32_bf16 v[62:65], v[122:125], v[162:165], v[62:65]
	v_mfma_f32_16x16x32_bf16 v[58:61], v[130:133], v[162:165], v[58:61]
	v_mfma_f32_16x16x32_bf16 v[46:49], v[122:125], v[170:173], v[46:49]
	v_mfma_f32_16x16x32_bf16 v[42:45], v[130:133], v[170:173], v[42:45]
	v_mfma_f32_16x16x32_bf16 v[30:33], v[122:125], v[178:181], v[30:33]
	v_mfma_f32_16x16x32_bf16 v[26:29], v[130:133], v[178:181], v[26:29]
	v_mfma_f32_16x16x32_bf16 v[14:17], v[122:125], v[186:189], v[14:17]
	v_mfma_f32_16x16x32_bf16 v[10:13], v[130:133], v[186:189], v[10:13]
	v_mfma_f32_16x16x32_bf16 v[62:65], v[126:129], v[166:169], v[62:65]
	v_mfma_f32_16x16x32_bf16 v[58:61], v[134:137], v[166:169], v[58:61]
	v_mfma_f32_16x16x32_bf16 v[46:49], v[126:129], v[174:177], v[46:49]
	v_mfma_f32_16x16x32_bf16 v[42:45], v[134:137], v[174:177], v[42:45]
	v_mfma_f32_16x16x32_bf16 v[30:33], v[126:129], v[182:185], v[30:33]
	v_mfma_f32_16x16x32_bf16 v[26:29], v[134:137], v[182:185], v[26:29]
	v_mfma_f32_16x16x32_bf16 v[14:17], v[126:129], v[208:211], v[14:17]
	v_mfma_f32_16x16x32_bf16 v[10:13], v[134:137], v[208:211], v[10:13]
	s_setprio 0
	s_setprio 1
	v_mfma_f32_16x16x32_bf16 v[54:57], v[138:141], v[162:165], v[54:57]
	v_mfma_f32_16x16x32_bf16 v[50:53], v[146:149], v[162:165], v[50:53]
	v_mfma_f32_16x16x32_bf16 v[38:41], v[138:141], v[170:173], v[38:41]
	v_mfma_f32_16x16x32_bf16 v[34:37], v[146:149], v[170:173], v[34:37]
	v_mfma_f32_16x16x32_bf16 v[22:25], v[138:141], v[178:181], v[22:25]
	v_mfma_f32_16x16x32_bf16 v[18:21], v[146:149], v[178:181], v[18:21]
	v_mfma_f32_16x16x32_bf16 v[6:9], v[138:141], v[186:189], v[6:9]
	v_mfma_f32_16x16x32_bf16 v[2:5], v[146:149], v[186:189], v[2:5]
	v_mfma_f32_16x16x32_bf16 v[54:57], v[142:145], v[166:169], v[54:57]
	v_mfma_f32_16x16x32_bf16 v[50:53], v[158:161], v[166:169], v[50:53]
	v_mfma_f32_16x16x32_bf16 v[38:41], v[142:145], v[174:177], v[38:41]
	v_mfma_f32_16x16x32_bf16 v[34:37], v[158:161], v[174:177], v[34:37]
	v_mfma_f32_16x16x32_bf16 v[22:25], v[142:145], v[182:185], v[22:25]
	v_mfma_f32_16x16x32_bf16 v[18:21], v[158:161], v[182:185], v[18:21]
	v_mfma_f32_16x16x32_bf16 v[6:9], v[142:145], v[208:211], v[6:9]
	v_mfma_f32_16x16x32_bf16 v[2:5], v[158:161], v[208:211], v[2:5]
	s_setprio 0
	s_barrier
	s_add_i32 s52, s52, 2
	s_add_u32 s18, s18, 0x100
	s_addc_u32 s19, s19, 0
	s_add_u32 s45, s45, 0x100
	s_addc_u32 s47, s47, 0
	s_cmp_gt_u32 s52, 13
	s_cbranch_scc0 .LBB0_487


; #define PG8_BAR __builtin_amdgcn_s_barrier()
; template <class Epi, class Sched, bool ALIGN_EPI = false, bool SP2 = false>
; __device__ __forceinline__ void gemm_phase(PG8_LAS unsigned char* lds, const Gemm g, const Sched& S, const Epi& E) {
;     ...
;         if constexpr (ALIGN_EPI) { if (wr == 0) PG8_BAR; }
;     __device__ __forceinline__ void operator()(const f32x4 (&acc)[2][2][4][2], const pg8::Unit& u, int wr, int wc, int fr, int fq) const {
;     ...
;             u32x4 w[2][4][2];
; #pragma unroll
;             for (int ai = 0; ai < 2; ++ai)
; #pragma unroll
;                 for (int m = 0; m < 4; ++m)
; #pragma unroll
;                     for (int bj = 0; bj < 2; ++bj) w[ai][m][bj] = *(const u32x4*)(xb + (size_t)(row0 + ai * 128 + m * 16) * DM + col0 + bj * 128);
; #pragma unroll
;             for (int ai = 0; ai < 2; ++ai)
; #pragma unroll
;                 for (int m = 0; m < 4; ++m) { float q = 0.f;
; #pragma unroll
;                     for (int bj = 0; bj < 2; ++bj) { const u32x4 t = w[ai][m][bj];
;                         const f32x4 b0 = {__uint_as_float(t.x << 16), __uint_as_float(t.x & 0xffff0000u), __uint_as_float(t.y << 16), __uint_as_float(t.y & 0xffff0000u)};
;                         const f32x4 b1 = {__uint_as_float(t.z << 16), __uint_as_float(t.z & 0xffff0000u), __uint_as_float(t.w << 16), __uint_as_float(t.w & 0xffff0000u)};
;                         q += emit(b0 + acc[ai][bj][m][0] * alpha, b1 + acc[ai][bj][m][1] * alpha, (size_t)(row0 + ai * 128 + m * 16) * DM + col0 + bj * 128); }
.LBB0_490:
	v_lshl_or_b32 v122, s56, 8, v240
	v_lshl_add_u32 v208, s58, 8, v238
	v_ashrrev_i32_e32 v123, 31, v122
	v_lshlrev_b64 v[210:211], 1, v[122:123]
	v_ashrrev_i32_e32 v209, 31, v208
	v_lshl_add_u64 v[122:123], s[96:97], 0, v[210:211]
	v_lshlrev_b64 v[226:227], 11, v[208:209]
	v_lshl_add_u64 v[124:125], v[122:123], 0, v[226:227]
	global_load_dwordx4 v[242:245], v[124:125], off
	global_load_dwordx4 v[186:189], v[124:125], off offset:256
	v_or_b32_e32 v124, 16, v208
	v_ashrrev_i32_e32 v125, 31, v124
	v_lshlrev_b64 v[224:225], 11, v[124:125]
	v_lshl_add_u64 v[124:125], v[122:123], 0, v[224:225]
	global_load_dwordx4 v[182:185], v[124:125], off
	global_load_dwordx4 v[178:181], v[124:125], off offset:256
	v_or_b32_e32 v124, 32, v208
	v_ashrrev_i32_e32 v125, 31, v124
	v_lshlrev_b64 v[222:223], 11, v[124:125]
	v_lshl_add_u64 v[124:125], v[122:123], 0, v[222:223]
	global_load_dwordx4 v[174:177], v[124:125], off
	global_load_dwordx4 v[170:173], v[124:125], off offset:256
	v_or_b32_e32 v124, 48, v208
	v_ashrrev_i32_e32 v125, 31, v124
	v_lshlrev_b64 v[220:221], 11, v[124:125]
	v_lshl_add_u64 v[124:125], v[122:123], 0, v[220:221]
	global_load_dwordx4 v[166:169], v[124:125], off
	global_load_dwordx4 v[162:165], v[124:125], off offset:256
	s_mov_b64 s[18:19], 0x40000
	v_lshl_add_u64 v[218:219], v[226:227], 0, s[18:19]
	v_lshl_add_u64 v[124:125], v[122:123], 0, v[218:219]
	global_load_dwordx4 v[158:161], v[124:125], off
	global_load_dwordx4 v[146:149], v[124:125], off offset:256
	s_mov_b64 s[18:19], 0x48000
	v_lshl_add_u64 v[216:217], v[226:227], 0, s[18:19]
	s_mov_b64 s[18:19], 0x50000
	v_lshl_add_u64 v[214:215], v[226:227], 0, s[18:19]
	s_mov_b64 s[18:19], 0x58000
	v_mov_b32_e32 v201, v200
	v_lshl_add_u64 v[124:125], v[122:123], 0, v[216:217]
	v_lshl_add_u64 v[212:213], v[226:227], 0, s[18:19]
	v_lshl_add_u64 v[226:227], s[96:97], 0, v[226:227]
	global_load_dwordx4 v[142:145], v[124:125], off
	global_load_dwordx4 v[138:141], v[124:125], off offset:256
	v_lshl_add_u64 v[124:125], v[122:123], 0, v[214:215]
	v_lshl_add_u64 v[122:123], v[122:123], 0, v[212:213]
	v_lshl_add_u64 v[226:227], v[226:227], 0, v[210:211]
	global_load_dwordx4 v[134:137], v[124:125], off
	global_load_dwordx4 v[130:133], v[124:125], off offset:256
	global_load_dwordx4 v[126:129], v[122:123], off
	s_nop 0
	global_load_dwordx4 v[122:125], v[122:123], off offset:256
	s_and_b64 vcc, exec, s[16:17]
	s_cbranch_vccz .Lalign_go_3
	s_barrier
.Lalign_go_3:
	s_waitcnt vmcnt(0)
	v_lshlrev_b32_e32 v246, 16, v242
	v_and_b32_e32 v247, 0xffff0000, v242
	v_lshlrev_b32_e32 v242, 16, v243
	v_and_b32_e32 v243, 0xffff0000, v243
	v_lshlrev_b32_e32 v248, 16, v244
	v_and_b32_e32 v249, 0xffff0000, v244
	v_lshlrev_b32_e32 v244, 16, v245
	v_and_b32_e32 v245, 0xffff0000, v245
	v_pk_fma_f32 v[156:157], v[200:201], v[156:157], v[242:243]
	v_pk_fma_f32 v[154:155], v[202:203], v[154:155], v[246:247]
	v_pk_fma_f32 v[242:243], v[200:201], v[152:153], v[244:245]
	v_pk_fma_f32 v[244:245], v[202:203], v[150:151], v[248:249]
	v_cvt_pk_bf16_f32 v150, v154, v155
	v_cvt_pk_bf16_f32 v151, v156, v157
	v_cvt_pk_bf16_f32 v152, v244, v245
	v_cvt_pk_bf16_f32 v153, v242, v243
	global_store_dwordx4 v[226:227], v[150:153], off
	s_nop 1
	v_mul_f32_e32 v150, v155, v155
	v_mul_f32_e32 v151, v157, v157
	v_fmac_f32_e32 v150, v154, v154
	v_fmac_f32_e32 v151, v156, v156
	v_add_f32_e32 v150, v150, v151
	v_mul_f32_e32 v151, v245, v245
	v_fmac_f32_e32 v151, v244, v244
	v_add_f32_e32 v150, v151, v150
	v_mul_f32_e32 v151, v243, v243
	v_fmac_f32_e32 v151, v242, v242
	v_add_f32_e32 v242, v151, v150
	v_lshlrev_b32_e32 v150, 16, v186
	v_and_b32_e32 v151, 0xffff0000, v186
	v_lshlrev_b32_e32 v152, 16, v187
	v_and_b32_e32 v153, 0xffff0000, v187
	v_lshlrev_b32_e32 v154, 16, v188
	v_and_b32_e32 v155, 0xffff0000, v188
	v_lshlrev_b32_e32 v156, 16, v189
	v_and_b32_e32 v157, 0xffff0000, v189
	v_pk_fma_f32 v[120:121], v[200:201], v[120:121], v[152:153]
	v_pk_fma_f32 v[118:119], v[202:203], v[118:119], v[150:151]
	v_pk_fma_f32 v[150:151], v[200:201], v[116:117], v[156:157]
	v_pk_fma_f32 v[152:153], v[202:203], v[114:115], v[154:155]
	v_cvt_pk_bf16_f32 v114, v118, v119
	v_cvt_pk_bf16_f32 v115, v120, v121
	v_cvt_pk_bf16_f32 v116, v152, v153
	v_cvt_pk_bf16_f32 v117, v150, v151
	global_store_dwordx4 v[226:227], v[114:117], off offset:256
	s_nop 1
	v_mul_f32_e32 v114, v119, v119
	v_mul_f32_e32 v115, v121, v121
	v_fmac_f32_e32 v114, v118, v118
	v_fmac_f32_e32 v115, v120, v120
	v_add_f32_e32 v114, v114, v115
	v_mul_f32_e32 v115, v153, v153
	v_fmac_f32_e32 v115, v152, v152
	v_add_f32_e32 v114, v115, v114
	v_mul_f32_e32 v115, v151, v151
	v_fmac_f32_e32 v115, v150, v150
	v_lshlrev_b32_e32 v116, 16, v182
	v_and_b32_e32 v117, 0xffff0000, v182
	v_lshlrev_b32_e32 v118, 16, v183
	v_and_b32_e32 v119, 0xffff0000, v183
	v_lshlrev_b32_e32 v120, 16, v184
	v_and_b32_e32 v121, 0xffff0000, v184
	v_lshlrev_b32_e32 v150, 16, v185
	v_and_b32_e32 v151, 0xffff0000, v185
	v_pk_fma_f32 v[112:113], v[200:201], v[112:113], v[118:119]
	v_pk_fma_f32 v[110:111], v[202:203], v[110:111], v[116:117]
	v_pk_fma_f32 v[116:117], v[200:201], v[108:109], v[150:151]
	v_pk_fma_f32 v[118:119], v[202:203], v[106:107], v[120:121]
	v_lshl_add_u64 v[120:121], s[96:97], 0, v[224:225]
	v_cvt_pk_bf16_f32 v106, v110, v111
	v_cvt_pk_bf16_f32 v107, v112, v113
	v_cvt_pk_bf16_f32 v108, v118, v119
	v_cvt_pk_bf16_f32 v109, v116, v117
	v_lshl_add_u64 v[120:121], v[120:121], 0, v[210:211]
	global_store_dwordx4 v[120:121], v[106:109], off
	v_add_f32_e32 v114, v115, v114
	v_add_f32_e32 v114, v242, v114
	v_mul_f32_e32 v106, v111, v111
	v_mul_f32_e32 v107, v113, v113
	v_fmac_f32_e32 v106, v110, v110
; __device__ __forceinline__ unsigned pkbf(float lo, float hi) { const f32x2_t v = {lo, hi}; const bf16x2_t b = __builtin_convertvector(v, bf16x2_t); return __builtin_bit_cast(unsigned, b); }
;     __device__ __forceinline__ void operator()(const f32x4 (&acc)[2][2][4][2], const pg8::Unit& u, int wr, int wc, int fr, int fq) const {
;     ...
;             for (int ai = 0; ai < 2; ++ai)
; #pragma unroll
;                 for (int m = 0; m < 4; ++m) { float q = 0.f;
; #pragma unroll
;                     for (int bj = 0; bj < 2; ++bj) { const u32x4 t = w[ai][m][bj];
;                         const f32x4 b0 = {__uint_as_float(t.x << 16), __uint_as_float(t.x & 0xffff0000u), __uint_as_float(t.y << 16), __uint_as_float(t.y & 0xffff0000u)};
;                         const f32x4 b1 = {__uint_as_float(t.z << 16), __uint_as_float(t.z & 0xffff0000u), __uint_as_float(t.w << 16), __uint_as_float(t.w & 0xffff0000u)};
;                         q += emit(b0 + acc[ai][bj][m][0] * alpha, b1 + acc[ai][bj][m][1] * alpha, (size_t)(row0 + ai * 128 + m * 16) * DM + col0 + bj * 128); }
;                     sq[ai][m] = q; }
;     __device__ __forceinline__ float emit(const f32x4 v0, const f32x4 v1, size_t off) const {
;         if (MODE == 2) { *(f32x4*)(out + off) = v0; *(f32x4*)(out + off + 4) = v1; return 0.f; }
;         u32x4 w; w.x = pkbf(v0[0], v0[1]); w.y = pkbf(v0[2], v0[3]); w.z = pkbf(v1[0], v1[1]); w.w = pkbf(v1[2], v1[3]);
;         *(u32x4*)(xb + off) = w;
;         return (v0[0] * v0[0] + v0[1] * v0[1]) + (v0[2] * v0[2] + v0[3] * v0[3]) + (v1[0] * v1[0] + v1[1] * v1[1]) + (v1[2] * v1[2] + v1[3] * v1[3]);
	v_fmac_f32_e32 v107, v112, v112
	v_add_f32_e32 v106, v106, v107
	v_mul_f32_e32 v107, v119, v119
	v_fmac_f32_e32 v107, v118, v118
	v_add_f32_e32 v106, v107, v106
	v_mul_f32_e32 v107, v117, v117
	v_fmac_f32_e32 v107, v116, v116
	v_add_f32_e32 v115, v107, v106
	v_lshlrev_b32_e32 v106, 16, v178
	v_and_b32_e32 v107, 0xffff0000, v178
	v_lshlrev_b32_e32 v108, 16, v179
	v_and_b32_e32 v109, 0xffff0000, v179
	v_lshlrev_b32_e32 v110, 16, v180
	v_and_b32_e32 v111, 0xffff0000, v180
	v_lshlrev_b32_e32 v112, 16, v181
	v_and_b32_e32 v113, 0xffff0000, v181
	v_pk_fma_f32 v[104:105], v[200:201], v[104:105], v[108:109]
	v_pk_fma_f32 v[102:103], v[202:203], v[102:103], v[106:107]
	v_pk_fma_f32 v[106:107], v[200:201], v[100:101], v[112:113]
	v_pk_fma_f32 v[108:109], v[202:203], v[98:99], v[110:111]
	v_cvt_pk_bf16_f32 v98, v102, v103
	v_cvt_pk_bf16_f32 v99, v104, v105
	v_cvt_pk_bf16_f32 v100, v108, v109
	v_cvt_pk_bf16_f32 v101, v106, v107
	global_store_dwordx4 v[120:121], v[98:101], off offset:256
	s_nop 1
	v_mul_f32_e32 v98, v103, v103
	v_mul_f32_e32 v99, v105, v105
	v_fmac_f32_e32 v98, v102, v102
	v_fmac_f32_e32 v99, v104, v104
	v_add_f32_e32 v98, v98, v99
	v_mul_f32_e32 v99, v109, v109
	v_fmac_f32_e32 v99, v108, v108
	v_add_f32_e32 v98, v99, v98
	v_mul_f32_e32 v99, v107, v107
	v_fmac_f32_e32 v99, v106, v106
	v_lshlrev_b32_e32 v100, 16, v174
	v_and_b32_e32 v101, 0xffff0000, v174
	v_lshlrev_b32_e32 v102, 16, v175
	v_and_b32_e32 v103, 0xffff0000, v175
	v_lshlrev_b32_e32 v104, 16, v176
	v_and_b32_e32 v105, 0xffff0000, v176
	v_lshlrev_b32_e32 v106, 16, v177
	v_and_b32_e32 v107, 0xffff0000, v177
	v_pk_fma_f32 v[96:97], v[200:201], v[96:97], v[102:103]
	v_pk_fma_f32 v[94:95], v[202:203], v[94:95], v[100:101]
	v_pk_fma_f32 v[100:101], v[200:201], v[92:93], v[106:107]
	v_pk_fma_f32 v[102:103], v[202:203], v[90:91], v[104:105]
	v_lshl_add_u64 v[104:105], s[96:97], 0, v[222:223]
	v_cvt_pk_bf16_f32 v90, v94, v95
	v_cvt_pk_bf16_f32 v91, v96, v97
	v_cvt_pk_bf16_f32 v92, v102, v103
	v_cvt_pk_bf16_f32 v93, v100, v101
	v_lshl_add_u64 v[104:105], v[104:105], 0, v[210:211]
	global_store_dwordx4 v[104:105], v[90:93], off
	v_add_f32_e32 v98, v99, v98
	v_add_f32_e32 v98, v115, v98
	v_mul_f32_e32 v90, v95, v95
	v_mul_f32_e32 v91, v97, v97
	v_fmac_f32_e32 v90, v94, v94
	v_fmac_f32_e32 v91, v96, v96
	v_add_f32_e32 v90, v90, v91
	v_mul_f32_e32 v91, v103, v103
	v_fmac_f32_e32 v91, v102, v102
	v_add_f32_e32 v90, v91, v90
	v_mul_f32_e32 v91, v101, v101
	v_fmac_f32_e32 v91, v100, v100
	v_add_f32_e32 v99, v91, v90
	v_lshlrev_b32_e32 v90, 16, v170
	v_and_b32_e32 v91, 0xffff0000, v170
	v_lshlrev_b32_e32 v92, 16, v171
	v_and_b32_e32 v93, 0xffff0000, v171
	v_lshlrev_b32_e32 v94, 16, v172
	v_and_b32_e32 v95, 0xffff0000, v172
	v_lshlrev_b32_e32 v96, 16, v173
	v_and_b32_e32 v97, 0xffff0000, v173
	v_pk_fma_f32 v[88:89], v[200:201], v[88:89], v[92:93]
	v_pk_fma_f32 v[86:87], v[202:203], v[86:87], v[90:91]
	v_pk_fma_f32 v[90:91], v[200:201], v[84:85], v[96:97]
	v_pk_fma_f32 v[92:93], v[202:203], v[82:83], v[94:95]
	v_cvt_pk_bf16_f32 v82, v86, v87
	v_cvt_pk_bf16_f32 v83, v88, v89
	v_cvt_pk_bf16_f32 v84, v92, v93
	v_cvt_pk_bf16_f32 v85, v90, v91
	global_store_dwordx4 v[104:105], v[82:85], off offset:256
	s_nop 1
	v_mul_f32_e32 v82, v87, v87
	v_mul_f32_e32 v83, v89, v89
	v_fmac_f32_e32 v82, v86, v86
	v_fmac_f32_e32 v83, v88, v88
	v_add_f32_e32 v82, v82, v83
	v_mul_f32_e32 v83, v93, v93
	v_fmac_f32_e32 v83, v92, v92
	v_add_f32_e32 v82, v83, v82
	v_mul_f32_e32 v83, v91, v91
	v_fmac_f32_e32 v83, v90, v90
	v_lshlrev_b32_e32 v84, 16, v166
	v_and_b32_e32 v85, 0xffff0000, v166
	v_lshlrev_b32_e32 v86, 16, v167
	v_and_b32_e32 v87, 0xffff0000, v167
	v_lshlrev_b32_e32 v88, 16, v168
	v_and_b32_e32 v89, 0xffff0000, v168
	v_lshlrev_b32_e32 v90, 16, v169
	v_and_b32_e32 v91, 0xffff0000, v169
	v_pk_fma_f32 v[80:81], v[200:201], v[80:81], v[86:87]
	v_pk_fma_f32 v[78:79], v[202:203], v[78:79], v[84:85]
	v_pk_fma_f32 v[84:85], v[200:201], v[76:77], v[90:91]
	v_pk_fma_f32 v[86:87], v[202:203], v[74:75], v[88:89]
	v_lshl_add_u64 v[88:89], s[96:97], 0, v[220:221]
	v_cvt_pk_bf16_f32 v74, v78, v79
	v_cvt_pk_bf16_f32 v75, v80, v81
	v_cvt_pk_bf16_f32 v76, v86, v87
	v_cvt_pk_bf16_f32 v77, v84, v85
	v_lshl_add_u64 v[88:89], v[88:89], 0, v[210:211]
	global_store_dwordx4 v[88:89], v[74:77], off
	v_add_f32_e32 v82, v83, v82
	v_add_f32_e32 v82, v99, v82
	v_mul_f32_e32 v74, v79, v79
	v_mul_f32_e32 v75, v81, v81
	v_fmac_f32_e32 v74, v78, v78
	v_fmac_f32_e32 v75, v80, v80
	v_add_f32_e32 v74, v74, v75
	v_mul_f32_e32 v75, v87, v87
	v_fmac_f32_e32 v75, v86, v86
	v_add_f32_e32 v74, v75, v74
	v_mul_f32_e32 v75, v85, v85
	v_fmac_f32_e32 v75, v84, v84
	v_add_f32_e32 v83, v75, v74
	v_lshlrev_b32_e32 v74, 16, v162
	v_and_b32_e32 v75, 0xffff0000, v162
	v_lshlrev_b32_e32 v76, 16, v163
	v_and_b32_e32 v77, 0xffff0000, v163
	v_lshlrev_b32_e32 v78, 16, v164
	v_and_b32_e32 v79, 0xffff0000, v164
	v_lshlrev_b32_e32 v80, 16, v165
	v_and_b32_e32 v81, 0xffff0000, v165
	v_pk_fma_f32 v[72:73], v[200:201], v[72:73], v[76:77]
	v_pk_fma_f32 v[70:71], v[202:203], v[70:71], v[74:75]
	v_pk_fma_f32 v[74:75], v[200:201], v[68:69], v[80:81]
	v_pk_fma_f32 v[76:77], v[202:203], v[66:67], v[78:79]
	v_cvt_pk_bf16_f32 v66, v70, v71
	v_cvt_pk_bf16_f32 v67, v72, v73
	v_cvt_pk_bf16_f32 v68, v76, v77
	v_cvt_pk_bf16_f32 v69, v74, v75
	global_store_dwordx4 v[88:89], v[66:69], off offset:256
	s_nop 1
	v_mul_f32_e32 v66, v71, v71
	v_mul_f32_e32 v67, v73, v73
	v_fmac_f32_e32 v66, v70, v70
	v_fmac_f32_e32 v67, v72, v72
	v_add_f32_e32 v66, v66, v67
	v_mul_f32_e32 v67, v77, v77
	v_fmac_f32_e32 v67, v76, v76
	v_add_f32_e32 v66, v67, v66
	v_mul_f32_e32 v67, v75, v75
; __device__ __forceinline__ unsigned pkbf(float lo, float hi) { const f32x2_t v = {lo, hi}; const bf16x2_t b = __builtin_convertvector(v, bf16x2_t); return __builtin_bit_cast(unsigned, b); }
;     __device__ __forceinline__ void operator()(const f32x4 (&acc)[2][2][4][2], const pg8::Unit& u, int wr, int wc, int fr, int fq) const {
;     ...
;                     for (int bj = 0; bj < 2; ++bj) { const u32x4 t = w[ai][m][bj];
;                         const f32x4 b0 = {__uint_as_float(t.x << 16), __uint_as_float(t.x & 0xffff0000u), __uint_as_float(t.y << 16), __uint_as_float(t.y & 0xffff0000u)};
;                         const f32x4 b1 = {__uint_as_float(t.z << 16), __uint_as_float(t.z & 0xffff0000u), __uint_as_float(t.w << 16), __uint_as_float(t.w & 0xffff0000u)};
;                         q += emit(b0 + acc[ai][bj][m][0] * alpha, b1 + acc[ai][bj][m][1] * alpha, (size_t)(row0 + ai * 128 + m * 16) * DM + col0 + bj * 128); }
;                     sq[ai][m] = q; }
;     __device__ __forceinline__ float emit(const f32x4 v0, const f32x4 v1, size_t off) const {
;         if (MODE == 2) { *(f32x4*)(out + off) = v0; *(f32x4*)(out + off + 4) = v1; return 0.f; }
;         u32x4 w; w.x = pkbf(v0[0], v0[1]); w.y = pkbf(v0[2], v0[3]); w.z = pkbf(v1[0], v1[1]); w.w = pkbf(v1[2], v1[3]);
;         *(u32x4*)(xb + off) = w;
;         return (v0[0] * v0[0] + v0[1] * v0[1]) + (v0[2] * v0[2] + v0[3] * v0[3]) + (v1[0] * v1[0] + v1[1] * v1[1]) + (v1[2] * v1[2] + v1[3] * v1[3]);
	v_fmac_f32_e32 v67, v74, v74
	v_add_f32_e32 v66, v67, v66
	v_add_f32_e32 v74, v83, v66
	v_lshlrev_b32_e32 v66, 16, v158
	v_and_b32_e32 v67, 0xffff0000, v158
	v_lshlrev_b32_e32 v68, 16, v159
	v_and_b32_e32 v69, 0xffff0000, v159
	v_lshlrev_b32_e32 v70, 16, v160
	v_and_b32_e32 v71, 0xffff0000, v160
	v_lshlrev_b32_e32 v72, 16, v161
	v_and_b32_e32 v73, 0xffff0000, v161
	v_pk_fma_f32 v[64:65], v[200:201], v[64:65], v[68:69]
	v_pk_fma_f32 v[62:63], v[202:203], v[62:63], v[66:67]
	v_pk_fma_f32 v[66:67], v[200:201], v[60:61], v[72:73]
	v_pk_fma_f32 v[68:69], v[202:203], v[58:59], v[70:71]
	v_lshl_add_u64 v[70:71], s[96:97], 0, v[218:219]
	v_cvt_pk_bf16_f32 v58, v62, v63
	v_cvt_pk_bf16_f32 v59, v64, v65
	v_cvt_pk_bf16_f32 v60, v68, v69
	v_cvt_pk_bf16_f32 v61, v66, v67
	v_lshl_add_u64 v[70:71], v[70:71], 0, v[210:211]
	global_store_dwordx4 v[70:71], v[58:61], off
	s_nop 1
	v_mul_f32_e32 v58, v63, v63
	v_mul_f32_e32 v59, v65, v65
	v_fmac_f32_e32 v58, v62, v62
	v_fmac_f32_e32 v59, v64, v64
	v_add_f32_e32 v58, v58, v59
	v_mul_f32_e32 v59, v69, v69
	v_fmac_f32_e32 v59, v68, v68
	v_add_f32_e32 v58, v59, v58
	v_mul_f32_e32 v59, v67, v67
	v_fmac_f32_e32 v59, v66, v66
	v_add_f32_e32 v66, v59, v58
	v_lshlrev_b32_e32 v58, 16, v146
	v_and_b32_e32 v59, 0xffff0000, v146
	v_lshlrev_b32_e32 v60, 16, v147
	v_and_b32_e32 v61, 0xffff0000, v147
	v_lshlrev_b32_e32 v62, 16, v148
	v_and_b32_e32 v63, 0xffff0000, v148
	v_lshlrev_b32_e32 v64, 16, v149
	v_and_b32_e32 v65, 0xffff0000, v149
	v_pk_fma_f32 v[56:57], v[200:201], v[56:57], v[60:61]
	v_pk_fma_f32 v[54:55], v[202:203], v[54:55], v[58:59]
	v_pk_fma_f32 v[58:59], v[200:201], v[52:53], v[64:65]
	v_pk_fma_f32 v[60:61], v[202:203], v[50:51], v[62:63]
	v_cvt_pk_bf16_f32 v50, v54, v55
	v_cvt_pk_bf16_f32 v51, v56, v57
	v_cvt_pk_bf16_f32 v52, v60, v61
	v_cvt_pk_bf16_f32 v53, v58, v59
	global_store_dwordx4 v[70:71], v[50:53], off offset:256
	s_nop 1
	v_mul_f32_e32 v50, v55, v55
	v_mul_f32_e32 v51, v57, v57
	v_fmac_f32_e32 v50, v54, v54
	v_fmac_f32_e32 v51, v56, v56
	v_add_f32_e32 v50, v50, v51
	v_mul_f32_e32 v51, v61, v61
	v_fmac_f32_e32 v51, v60, v60
	v_add_f32_e32 v50, v51, v50
	v_mul_f32_e32 v51, v59, v59
	v_fmac_f32_e32 v51, v58, v58
	v_add_f32_e32 v50, v51, v50
	v_add_f32_e32 v58, v66, v50
	v_lshlrev_b32_e32 v50, 16, v142
	v_and_b32_e32 v51, 0xffff0000, v142
	v_lshlrev_b32_e32 v52, 16, v143
	v_and_b32_e32 v53, 0xffff0000, v143
	v_lshlrev_b32_e32 v54, 16, v144
	v_and_b32_e32 v55, 0xffff0000, v144
	v_lshlrev_b32_e32 v56, 16, v145
	v_and_b32_e32 v57, 0xffff0000, v145
	v_pk_fma_f32 v[48:49], v[200:201], v[48:49], v[52:53]
	v_pk_fma_f32 v[46:47], v[202:203], v[46:47], v[50:51]
	v_pk_fma_f32 v[50:51], v[200:201], v[44:45], v[56:57]
	v_pk_fma_f32 v[52:53], v[202:203], v[42:43], v[54:55]
	v_lshl_add_u64 v[54:55], s[96:97], 0, v[216:217]
	v_cvt_pk_bf16_f32 v42, v46, v47
	v_cvt_pk_bf16_f32 v43, v48, v49
	v_cvt_pk_bf16_f32 v44, v52, v53
	v_cvt_pk_bf16_f32 v45, v50, v51
	v_lshl_add_u64 v[54:55], v[54:55], 0, v[210:211]
	global_store_dwordx4 v[54:55], v[42:45], off
	s_nop 1
	v_mul_f32_e32 v42, v47, v47
	v_mul_f32_e32 v43, v49, v49
	v_fmac_f32_e32 v42, v46, v46
	v_fmac_f32_e32 v43, v48, v48
	v_add_f32_e32 v42, v42, v43
	v_mul_f32_e32 v43, v53, v53
	v_fmac_f32_e32 v43, v52, v52
	v_add_f32_e32 v42, v43, v42
	v_mul_f32_e32 v43, v51, v51
	v_fmac_f32_e32 v43, v50, v50
	v_add_f32_e32 v50, v43, v42
	v_lshlrev_b32_e32 v42, 16, v138
	v_and_b32_e32 v43, 0xffff0000, v138
	v_lshlrev_b32_e32 v44, 16, v139
	v_and_b32_e32 v45, 0xffff0000, v139
	v_lshlrev_b32_e32 v46, 16, v140
	v_and_b32_e32 v47, 0xffff0000, v140
	v_lshlrev_b32_e32 v48, 16, v141
	v_and_b32_e32 v49, 0xffff0000, v141
	v_pk_fma_f32 v[40:41], v[200:201], v[40:41], v[44:45]
	v_pk_fma_f32 v[38:39], v[202:203], v[38:39], v[42:43]
	v_pk_fma_f32 v[42:43], v[200:201], v[36:37], v[48:49]
	v_pk_fma_f32 v[44:45], v[202:203], v[34:35], v[46:47]
	v_cvt_pk_bf16_f32 v34, v38, v39
	v_cvt_pk_bf16_f32 v35, v40, v41
	v_cvt_pk_bf16_f32 v36, v44, v45
	v_cvt_pk_bf16_f32 v37, v42, v43
	global_store_dwordx4 v[54:55], v[34:37], off offset:256
	s_nop 1
	v_mul_f32_e32 v34, v39, v39
	v_mul_f32_e32 v35, v41, v41
	v_fmac_f32_e32 v34, v38, v38
	v_fmac_f32_e32 v35, v40, v40
	v_add_f32_e32 v34, v34, v35
	v_mul_f32_e32 v35, v45, v45
	v_fmac_f32_e32 v35, v44, v44
	v_add_f32_e32 v34, v35, v34
	v_mul_f32_e32 v35, v43, v43
	v_fmac_f32_e32 v35, v42, v42
	v_add_f32_e32 v34, v35, v34
	v_add_f32_e32 v42, v50, v34
	v_lshlrev_b32_e32 v34, 16, v134
	v_and_b32_e32 v35, 0xffff0000, v134
	v_lshlrev_b32_e32 v36, 16, v135
	v_and_b32_e32 v37, 0xffff0000, v135
	v_lshlrev_b32_e32 v38, 16, v136
	v_and_b32_e32 v39, 0xffff0000, v136
	v_lshlrev_b32_e32 v40, 16, v137
	v_and_b32_e32 v41, 0xffff0000, v137
	v_pk_fma_f32 v[32:33], v[200:201], v[32:33], v[36:37]
	v_pk_fma_f32 v[30:31], v[202:203], v[30:31], v[34:35]
	v_pk_fma_f32 v[34:35], v[200:201], v[28:29], v[40:41]
	v_pk_fma_f32 v[36:37], v[202:203], v[26:27], v[38:39]
	v_lshl_add_u64 v[38:39], s[96:97], 0, v[214:215]
	v_cvt_pk_bf16_f32 v26, v30, v31
	v_cvt_pk_bf16_f32 v27, v32, v33
	v_cvt_pk_bf16_f32 v28, v36, v37
	v_cvt_pk_bf16_f32 v29, v34, v35
	v_lshl_add_u64 v[38:39], v[38:39], 0, v[210:211]
	global_store_dwordx4 v[38:39], v[26:29], off
	s_nop 1
	v_mul_f32_e32 v26, v31, v31
	v_mul_f32_e32 v27, v33, v33
	v_fmac_f32_e32 v26, v30, v30
	v_fmac_f32_e32 v27, v32, v32
	v_add_f32_e32 v26, v26, v27
	v_mul_f32_e32 v27, v37, v37
	v_fmac_f32_e32 v27, v36, v36
	v_add_f32_e32 v26, v27, v26
	v_mul_f32_e32 v27, v35, v35
	v_fmac_f32_e32 v27, v34, v34
	v_add_f32_e32 v34, v27, v26
	v_lshlrev_b32_e32 v26, 16, v130
	v_and_b32_e32 v27, 0xffff0000, v130
	v_lshlrev_b32_e32 v28, 16, v131
	v_and_b32_e32 v29, 0xffff0000, v131
;     __device__ __forceinline__ void operator()(const f32x4 (&acc)[2][2][4][2], const pg8::Unit& u, int wr, int wc, int fr, int fq) const {
;     ...
;                     for (int bj = 0; bj < 2; ++bj) { const u32x4 t = w[ai][m][bj];
;                         const f32x4 b0 = {__uint_as_float(t.x << 16), __uint_as_float(t.x & 0xffff0000u), __uint_as_float(t.y << 16), __uint_as_float(t.y & 0xffff0000u)};
;                         const f32x4 b1 = {__uint_as_float(t.z << 16), __uint_as_float(t.z & 0xffff0000u), __uint_as_float(t.w << 16), __uint_as_float(t.w & 0xffff0000u)};
;                         q += emit(b0 + acc[ai][bj][m][0] * alpha, b1 + acc[ai][bj][m][1] * alpha, (size_t)(row0 + ai * 128 + m * 16) * DM + col0 + bj * 128); }
;                     sq[ai][m] = q; }
;         }
;         if (MODE != 2) {
; #pragma unroll
;             for (int ai = 0; ai < 2; ++ai)
; #pragma unroll
;                 for (int m = 0; m < 4; ++m) sq[ai][m] += __shfl_xor(sq[ai][m], 16);
; #pragma unroll
;             for (int ai = 0; ai < 2; ++ai)
; #pragma unroll
;                 for (int m = 0; m < 4; ++m) sq[ai][m] += __shfl_xor(sq[ai][m], 32);
;             if (fq == 0) {
; #pragma unroll
;                 for (int ai = 0; ai < 2; ++ai)
; #pragma unroll
;                     for (int m = 0; m < 4; ++m) atomicAdd(ssn + row0 + ai * 128 + m * 16, (u64)(sq[ai][m] * SS_SCALE + 0.5f)); }
	v_lshlrev_b32_e32 v30, 16, v132
	v_and_b32_e32 v31, 0xffff0000, v132
	v_lshlrev_b32_e32 v32, 16, v133
	v_and_b32_e32 v33, 0xffff0000, v133
	v_pk_fma_f32 v[24:25], v[200:201], v[24:25], v[28:29]
	v_pk_fma_f32 v[22:23], v[202:203], v[22:23], v[26:27]
	v_pk_fma_f32 v[26:27], v[200:201], v[20:21], v[32:33]
	v_pk_fma_f32 v[28:29], v[202:203], v[18:19], v[30:31]
	v_cvt_pk_bf16_f32 v18, v22, v23
	v_cvt_pk_bf16_f32 v19, v24, v25
	v_cvt_pk_bf16_f32 v20, v28, v29
	v_cvt_pk_bf16_f32 v21, v26, v27
	global_store_dwordx4 v[38:39], v[18:21], off offset:256
	s_nop 1
	v_mul_f32_e32 v18, v23, v23
	v_mul_f32_e32 v19, v25, v25
	v_fmac_f32_e32 v18, v22, v22
	v_fmac_f32_e32 v19, v24, v24
	v_add_f32_e32 v18, v18, v19
	v_mul_f32_e32 v19, v29, v29
	v_fmac_f32_e32 v19, v28, v28
	v_add_f32_e32 v18, v19, v18
	v_mul_f32_e32 v19, v27, v27
	v_fmac_f32_e32 v19, v26, v26
	v_add_f32_e32 v18, v19, v18
	v_add_f32_e32 v26, v34, v18
	v_lshlrev_b32_e32 v18, 16, v126
	v_and_b32_e32 v19, 0xffff0000, v126
	v_lshlrev_b32_e32 v20, 16, v127
	v_and_b32_e32 v21, 0xffff0000, v127
	v_lshlrev_b32_e32 v22, 16, v128
	v_and_b32_e32 v23, 0xffff0000, v128
	v_lshlrev_b32_e32 v24, 16, v129
	v_and_b32_e32 v25, 0xffff0000, v129
	v_pk_fma_f32 v[16:17], v[200:201], v[16:17], v[20:21]
	v_pk_fma_f32 v[14:15], v[202:203], v[14:15], v[18:19]
	v_pk_fma_f32 v[18:19], v[200:201], v[12:13], v[24:25]
	v_pk_fma_f32 v[20:21], v[202:203], v[10:11], v[22:23]
	v_lshl_add_u64 v[22:23], s[96:97], 0, v[212:213]
	v_cvt_pk_bf16_f32 v10, v14, v15
	v_cvt_pk_bf16_f32 v11, v16, v17
	v_cvt_pk_bf16_f32 v12, v20, v21
	v_cvt_pk_bf16_f32 v13, v18, v19
	v_lshl_add_u64 v[22:23], v[22:23], 0, v[210:211]
	global_store_dwordx4 v[22:23], v[10:13], off
	s_nop 1
	v_mul_f32_e32 v10, v15, v15
	v_mul_f32_e32 v11, v17, v17
	v_fmac_f32_e32 v10, v14, v14
	v_fmac_f32_e32 v11, v16, v16
	v_add_f32_e32 v10, v10, v11
	v_mul_f32_e32 v11, v21, v21
	v_fmac_f32_e32 v11, v20, v20
	v_add_f32_e32 v10, v11, v10
	v_mul_f32_e32 v11, v19, v19
	v_fmac_f32_e32 v11, v18, v18
	v_add_f32_e32 v18, v11, v10
	v_lshlrev_b32_e32 v10, 16, v122
	v_and_b32_e32 v11, 0xffff0000, v122
	v_lshlrev_b32_e32 v12, 16, v123
	v_and_b32_e32 v13, 0xffff0000, v123
	v_lshlrev_b32_e32 v14, 16, v124
	v_and_b32_e32 v15, 0xffff0000, v124
	v_lshlrev_b32_e32 v16, 16, v125
	v_and_b32_e32 v17, 0xffff0000, v125
	v_pk_fma_f32 v[8:9], v[200:201], v[8:9], v[12:13]
	v_pk_fma_f32 v[6:7], v[202:203], v[6:7], v[10:11]
	v_pk_fma_f32 v[10:11], v[200:201], v[4:5], v[16:17]
	v_pk_fma_f32 v[12:13], v[202:203], v[2:3], v[14:15]
	v_cvt_pk_bf16_f32 v2, v6, v7
	v_cvt_pk_bf16_f32 v3, v8, v9
	v_cvt_pk_bf16_f32 v4, v12, v13
	v_cvt_pk_bf16_f32 v5, v10, v11
	global_store_dwordx4 v[22:23], v[2:5], off offset:256
	s_nop 1
	v_mul_f32_e32 v2, v7, v7
	v_mul_f32_e32 v3, v9, v9
	v_fmac_f32_e32 v2, v6, v6
	v_fmac_f32_e32 v3, v8, v8
	v_add_f32_e32 v2, v2, v3
	v_mul_f32_e32 v3, v13, v13
	v_fmac_f32_e32 v3, v12, v12
	v_add_f32_e32 v2, v3, v2
	v_mul_f32_e32 v3, v11, v11
	v_fmac_f32_e32 v3, v10, v10
	v_add_f32_e32 v2, v3, v2
	v_and_b32_e32 v3, 64, v236
	v_add_f32_e32 v9, v18, v2
	v_xor_b32_e32 v2, 16, v236
	v_add_u32_e32 v11, 64, v3
	v_cmp_lt_i32_e32 vcc, v2, v11
	s_nop 1
	v_cndmask_b32_e32 v2, v236, v2, vcc
	v_lshlrev_b32_e32 v10, 2, v2
	ds_bpermute_b32 v2, v10, v114
	ds_bpermute_b32 v3, v10, v98
	ds_bpermute_b32 v4, v10, v82
	ds_bpermute_b32 v5, v10, v74
	ds_bpermute_b32 v6, v10, v58
	ds_bpermute_b32 v7, v10, v42
	ds_bpermute_b32 v8, v10, v26
	ds_bpermute_b32 v10, v10, v9
	s_waitcnt lgkmcnt(7)
	v_add_f32_e32 v2, v114, v2
	s_waitcnt lgkmcnt(6)
	v_add_f32_e32 v3, v98, v3
	s_waitcnt lgkmcnt(5)
	v_add_f32_e32 v4, v82, v4
	s_waitcnt lgkmcnt(4)
	v_add_f32_e32 v5, v74, v5
	s_waitcnt lgkmcnt(0)
	v_add_f32_e32 v10, v9, v10
	v_xor_b32_e32 v9, 32, v236
	v_cmp_lt_i32_e32 vcc, v9, v11
	v_add_f32_e32 v6, v58, v6
	v_add_f32_e32 v7, v42, v7
	v_cndmask_b32_e32 v9, v236, v9, vcc
	v_add_f32_e32 v8, v26, v8
	v_lshlrev_b32_e32 v17, 2, v9
	ds_bpermute_b32 v9, v17, v2
	ds_bpermute_b32 v11, v17, v3
	ds_bpermute_b32 v12, v17, v4
	ds_bpermute_b32 v13, v17, v5
	ds_bpermute_b32 v14, v17, v6
	ds_bpermute_b32 v15, v17, v7
	ds_bpermute_b32 v16, v17, v8
	ds_bpermute_b32 v17, v17, v10
	s_and_saveexec_b64 s[18:19], s[0:1]
	s_cbranch_execz .LBB0_492
	s_waitcnt lgkmcnt(5)
	v_add_f32_e32 v12, v4, v12
	v_add_f32_e32 v4, v2, v9
	v_fma_f32 v4, v4, s21, 0.5
	v_trunc_f32_e32 v4, v4
	s_waitcnt lgkmcnt(4)
	v_add_f32_e32 v13, v5, v13
	v_mul_f32_e32 v5, 0x2f800000, v4
	v_floor_f32_e32 v5, v5
	v_fmac_f32_e32 v4, 0xcf800000, v5
	v_cvt_u32_f32_e32 v4, v4
	v_cvt_u32_f32_e32 v5, v5
	v_add_f32_e32 v11, v3, v11
	v_lshl_add_u64 v[2:3], v[208:209], 3, s[38:39]
	s_waitcnt lgkmcnt(3)
	v_add_f32_e32 v6, v6, v14
	global_atomic_add_x2 v[2:3], v[4:5], off
	v_fma_f32 v4, v11, s21, 0.5
	v_trunc_f32_e32 v4, v4
	v_mul_f32_e32 v5, 0x2f800000, v4
	v_floor_f32_e32 v5, v5
	v_fmac_f32_e32 v4, 0xcf800000, v5
	v_cvt_u32_f32_e32 v4, v4
	v_cvt_u32_f32_e32 v5, v5
	s_waitcnt lgkmcnt(2)
	v_add_f32_e32 v7, v7, v15
	s_waitcnt lgkmcnt(1)
	v_add_f32_e32 v8, v8, v16
	s_waitcnt lgkmcnt(0)
	v_add_f32_e32 v10, v10, v17
	global_atomic_add_x2 v[2:3], v[4:5], off offset:128
	v_fma_f32 v4, v12, s21, 0.5
	v_trunc_f32_e32 v4, v4
	v_mul_f32_e32 v5, 0x2f800000, v4
	v_floor_f32_e32 v5, v5
	v_fmac_f32_e32 v4, 0xcf800000, v5
	v_cvt_u32_f32_e32 v4, v4
	v_cvt_u32_f32_e32 v5, v5
	global_atomic_add_x2 v[2:3], v[4:5], off offset:256
	v_fma_f32 v4, v13, s21, 0.5
	v_trunc_f32_e32 v4, v4
	v_mul_f32_e32 v5, 0x2f800000, v4
	v_floor_f32_e32 v5, v5
	v_fmac_f32_e32 v4, 0xcf800000, v5
	v_cvt_u32_f32_e32 v4, v4
	v_cvt_u32_f32_e32 v5, v5
	global_atomic_add_x2 v[2:3], v[4:5], off offset:384
	v_fma_f32 v4, v6, s21, 0.5
	v_trunc_f32_e32 v4, v4
	v_mul_f32_e32 v5, 0x2f800000, v4
	v_floor_f32_e32 v5, v5
	v_fmac_f32_e32 v4, 0xcf800000, v5
	v_cvt_u32_f32_e32 v4, v4
	v_cvt_u32_f32_e32 v5, v5
	global_atomic_add_x2 v[2:3], v[4:5], off offset:1024
	v_fma_f32 v4, v7, s21, 0.5
	v_trunc_f32_e32 v4, v4
	v_mul_f32_e32 v5, 0x2f800000, v4
	v_floor_f32_e32 v5, v5
	v_fmac_f32_e32 v4, 0xcf800000, v5
	v_cvt_u32_f32_e32 v4, v4
	v_cvt_u32_f32_e32 v5, v5
	global_atomic_add_x2 v[2:3], v[4:5], off offset:1152
	v_fma_f32 v4, v8, s21, 0.5
	v_trunc_f32_e32 v4, v4
	v_mul_f32_e32 v5, 0x2f800000, v4
	v_floor_f32_e32 v5, v5
	v_fmac_f32_e32 v4, 0xcf800000, v5
	v_cvt_u32_f32_e32 v4, v4
	v_cvt_u32_f32_e32 v5, v5
	global_atomic_add_x2 v[2:3], v[4:5], off offset:1280
	v_fma_f32 v4, v10, s21, 0.5
	v_trunc_f32_e32 v4, v4
	v_mul_f32_e32 v5, 0x2f800000, v4
	v_floor_f32_e32 v5, v5
	v_fmac_f32_e32 v4, 0xcf800000, v5
	v_cvt_u32_f32_e32 v4, v4
	v_cvt_u32_f32_e32 v5, v5
	global_atomic_add_x2 v[2:3], v[4:5], off offset:1408

; #define PG8_STAGE(bufoff, gbase, voff) do { _Pragma("unroll") for (int _i = 0; _i < 2; ++_i) \
;         __builtin_amdgcn_global_load_lds((const unsigned*)((const char*)(gbase) + (voff)[_i]), (PG8_LAS unsigned*)(lds + (bufoff) + ldsw + _i * 8192), 16, 0, 0); } while (0)
; #define PG8_LDA(dst, b, h) do { _Pragma("unroll") for (int m = 0; m < 4; ++m) _Pragma("unroll") for (int k = 0; k < 2; ++k) dst[m][k] = *(const PG8_LAS bf16x8*)(lds + PG8_SA(b, h) + aoff + m * 2048 + k * 1024); } while (0)
; #define PG8_LDB(dst, b, h) do { _Pragma("unroll") for (int n = 0; n < 2; ++n) _Pragma("unroll") for (int k = 0; k < 2; ++k) dst[n][k] = *(const PG8_LAS bf16x8*)(lds + PG8_SB(b, h) + boff + n * 2048 + k * 1024); } while (0)
; #define PG8_MMA(ai, bj, At, Bt) do { __builtin_amdgcn_s_setprio(1); _Pragma("unroll") for (int m = 0; m < 4; ++m) _Pragma("unroll") for (int n = 0; n < 2; ++n) _Pragma("unroll") for (int k = 0; k < 2; ++k) \
;         acc[ai][bj][m][n] = __builtin_amdgcn_mfma_f32_16x16x32_bf16(Bt[n][k], At[m][k], acc[ai][bj][m][n], 0, 0, 0); __builtin_amdgcn_s_setprio(0); } while (0)
; #define PG8_WAIT_V(n) asm volatile("s_waitcnt vmcnt(" #n ")" ::: "memory")
; #define PG8_WAIT_L(n) asm volatile("s_waitcnt lgkmcnt(" #n ")" ::: "memory")
; template <class Epi, class Sched, bool ALIGN_EPI = false, bool SP2 = false>
; __device__ __forceinline__ void gemm_phase(PG8_LAS unsigned char* lds, const Gemm g, const Sched& S, const Epi& E) {
;     ...
;             const bool last = (t == nt - 2);
;             const char* a1 = cA + (size_t)(t + 1) * kstep;
;             const char* a2 = last ? nA : cA + (size_t)(t + 2) * kstep; const char* b2 = last ? nB : cB + (size_t)(t + 2) * kstep;
;             const char* a3 = a2 + kstep; const char* b3 = b2 + kstep;
;             if (last && has_next) S.a_ready(nxt);
;             if constexpr (SP2) {
;             PG8_LDB(B0, 0, 0); PG8_LDB(B1, 0, 1); PG8_SCHED; PG8_LDA(At, 0, 0); PG8_STAGE(PG8_SA(1, 1), a1 + hstep, voffA);
;             PG8_WAIT_V(8); PG8_WAIT_L(0); PG8_BAR; PG8_MMA(0, 0, At, B0); PG8_MMA(0, 1, At, B1); PG8_BAR; PG8_SCHED;
;             PG8_LDA(At, 0, 1); PG8_STAGE(PG8_SB(0, 0), b2, voffB); PG8_STAGE(PG8_SB(0, 1), b2 + hstep, voffB); PG8_STAGE(PG8_SA(0, 0), a2, voffA);
;             PG8_WAIT_V(8); PG8_WAIT_L(0); PG8_BAR; PG8_MMA(1, 0, At, B0); PG8_MMA(1, 1, At, B1); PG8_BAR; PG8_SCHED;
.LBB0_522:
	s_add_u32 s53, s18, 0xfffc0080
	s_addc_u32 s58, s19, -1
	s_add_i32 s62, 0, 0x10000
	s_cmp_eq_u32 s52, 12
	s_cselect_b32 s61, s30, s58
	s_cselect_b32 s60, s31, s53
	s_cselect_b32 s59, s34, s45
	s_cselect_b32 s58, s35, s43
	s_add_i32 s53, 0, 0x14000
	v_add_u32_e32 v156, s62, v149
	v_add_u32_e32 v172, s53, v149
	ds_read_b128 v[140:143], v156
	ds_read_b128 v[144:147], v156 offset:1024
	ds_read_b128 v[152:155], v156 offset:2048
	ds_read_b128 v[156:159], v156 offset:3072
	ds_read_b128 v[160:163], v172
	ds_read_b128 v[164:167], v172 offset:1024
	ds_read_b128 v[168:171], v172 offset:2048
	ds_read_b128 v[172:175], v172 offset:3072
	v_lshl_add_u64 v[188:189], s[18:19], 0, v[136:137]
	s_add_i32 m0, s25, 0xc000
	ds_read_b128 v[176:179], v151
	ds_read_b128 v[180:183], v151 offset:1024
	ds_read_b128 v[184:187], v151 offset:2048
	ds_read_b128 v[194:197], v151 offset:3072
	ds_read_b128 v[198:201], v151 offset:4096
	ds_read_b128 v[202:205], v151 offset:5120
	ds_read_b128 v[206:209], v151 offset:6144
	ds_read_b128 v[210:213], v151 offset:7168
	global_load_lds_dwordx4 v[188:189], off
	v_lshl_add_u64 v[188:189], s[18:19], 0, v[138:139]
	s_add_i32 m0, s25, 0xe000
	s_nop 0
	global_load_lds_dwordx4 v[188:189], off
	s_waitcnt vmcnt(8)
	s_waitcnt lgkmcnt(0)
	s_barrier
	s_setprio 1
	s_waitcnt lgkmcnt(0)
	v_mfma_f32_16x16x32_bf16 v[126:129], v[140:143], v[176:179], v[126:129]
	v_mfma_f32_16x16x32_bf16 v[122:125], v[152:155], v[176:179], v[122:125]
	v_mfma_f32_16x16x32_bf16 v[118:121], v[140:143], v[184:187], v[118:121]
	v_mfma_f32_16x16x32_bf16 v[110:113], v[152:155], v[184:187], v[110:113]
	v_mfma_f32_16x16x32_bf16 v[94:97], v[140:143], v[198:201], v[94:97]
	v_mfma_f32_16x16x32_bf16 v[90:93], v[152:155], v[198:201], v[90:93]
	v_mfma_f32_16x16x32_bf16 v[78:81], v[140:143], v[206:209], v[78:81]
	v_mfma_f32_16x16x32_bf16 v[74:77], v[152:155], v[206:209], v[74:77]
	v_mfma_f32_16x16x32_bf16 v[126:129], v[144:147], v[180:183], v[126:129]
	v_mfma_f32_16x16x32_bf16 v[122:125], v[156:159], v[180:183], v[122:125]
	v_mfma_f32_16x16x32_bf16 v[118:121], v[144:147], v[194:197], v[118:121]
	v_mfma_f32_16x16x32_bf16 v[110:113], v[156:159], v[194:197], v[110:113]
	v_mfma_f32_16x16x32_bf16 v[94:97], v[144:147], v[202:205], v[94:97]
	v_mfma_f32_16x16x32_bf16 v[90:93], v[156:159], v[202:205], v[90:93]
	v_mfma_f32_16x16x32_bf16 v[78:81], v[144:147], v[210:213], v[78:81]
	v_mfma_f32_16x16x32_bf16 v[74:77], v[156:159], v[210:213], v[74:77]
	s_setprio 0
	s_setprio 1
	v_mfma_f32_16x16x32_bf16 v[114:117], v[160:163], v[176:179], v[114:117]
	v_mfma_f32_16x16x32_bf16 v[106:109], v[168:171], v[176:179], v[106:109]
	v_mfma_f32_16x16x32_bf16 v[102:105], v[160:163], v[184:187], v[102:105]
	v_mfma_f32_16x16x32_bf16 v[98:101], v[168:171], v[184:187], v[98:101]
	v_mfma_f32_16x16x32_bf16 v[86:89], v[160:163], v[198:201], v[86:89]
	v_mfma_f32_16x16x32_bf16 v[82:85], v[168:171], v[198:201], v[82:85]
	v_mfma_f32_16x16x32_bf16 v[70:73], v[160:163], v[206:209], v[70:73]
	v_mfma_f32_16x16x32_bf16 v[66:69], v[168:171], v[206:209], v[66:69]
	v_mfma_f32_16x16x32_bf16 v[114:117], v[164:167], v[180:183], v[114:117]
	v_mfma_f32_16x16x32_bf16 v[106:109], v[172:175], v[180:183], v[106:109]
	v_mfma_f32_16x16x32_bf16 v[102:105], v[164:167], v[194:197], v[102:105]
	v_mfma_f32_16x16x32_bf16 v[98:101], v[172:175], v[194:197], v[98:101]
	v_mfma_f32_16x16x32_bf16 v[86:89], v[164:167], v[202:205], v[86:89]
	v_mfma_f32_16x16x32_bf16 v[82:85], v[172:175], v[202:205], v[82:85]
	v_mfma_f32_16x16x32_bf16 v[70:73], v[164:167], v[210:213], v[70:73]
	v_mfma_f32_16x16x32_bf16 v[66:69], v[172:175], v[210:213], v[66:69]
	s_setprio 0
	s_barrier
	s_add_i32 s62, s62, s24
	v_lshl_add_u64 v[188:189], s[58:59], 0, v[0:1]
	s_mov_b32 m0, s62
	ds_read_b128 v[176:179], v151 offset:16384
	ds_read_b128 v[180:183], v151 offset:17408
	ds_read_b128 v[184:187], v151 offset:18432
	ds_read_b128 v[194:197], v151 offset:19456
	ds_read_b128 v[198:201], v151 offset:20480
	ds_read_b128 v[202:205], v151 offset:21504
	ds_read_b128 v[206:209], v151 offset:22528
	ds_read_b128 v[210:213], v151 offset:23552
	global_load_lds_dwordx4 v[188:189], off
	s_add_i32 m0, s62, 0x2000
	s_add_u32 s62, s58, 0x40000
	v_lshl_add_u64 v[214:215], s[58:59], 0, v[134:135]
	s_addc_u32 s63, s59, 0
	s_add_i32 s53, s53, s24
	global_load_lds_dwordx4 v[214:215], off
	v_lshl_add_u64 v[216:217], s[62:63], 0, v[0:1]
	s_mov_b32 m0, s53
	v_lshl_add_u64 v[218:219], s[60:61], 0, v[132:133]
	global_load_lds_dwordx4 v[216:217], off
	v_lshl_add_u64 v[216:217], s[62:63], 0, v[134:135]
	s_add_i32 m0, s53, 0x2000
	s_nop 0
	global_load_lds_dwordx4 v[216:217], off
	v_lshl_add_u64 v[216:217], s[60:61], 0, v[130:131]
	s_mov_b32 m0, s25
	s_nop 0
	global_load_lds_dwordx4 v[216:217], off
	s_mov_b32 m0, s26
	s_nop 0
	global_load_lds_dwordx4 v[218:219], off
	s_waitcnt vmcnt(8)
	s_waitcnt lgkmcnt(0)
	s_barrier
; #define PG8_STAGE(bufoff, gbase, voff) do { _Pragma("unroll") for (int _i = 0; _i < 2; ++_i) \
;         __builtin_amdgcn_global_load_lds((const unsigned*)((const char*)(gbase) + (voff)[_i]), (PG8_LAS unsigned*)(lds + (bufoff) + ldsw + _i * 8192), 16, 0, 0); } while (0)
; #define PG8_LDA(dst, b, h) do { _Pragma("unroll") for (int m = 0; m < 4; ++m) _Pragma("unroll") for (int k = 0; k < 2; ++k) dst[m][k] = *(const PG8_LAS bf16x8*)(lds + PG8_SA(b, h) + aoff + m * 2048 + k * 1024); } while (0)
; #define PG8_LDB(dst, b, h) do { _Pragma("unroll") for (int n = 0; n < 2; ++n) _Pragma("unroll") for (int k = 0; k < 2; ++k) dst[n][k] = *(const PG8_LAS bf16x8*)(lds + PG8_SB(b, h) + boff + n * 2048 + k * 1024); } while (0)
; #define PG8_MMA(ai, bj, At, Bt) do { __builtin_amdgcn_s_setprio(1); _Pragma("unroll") for (int m = 0; m < 4; ++m) _Pragma("unroll") for (int n = 0; n < 2; ++n) _Pragma("unroll") for (int k = 0; k < 2; ++k) \
;         acc[ai][bj][m][n] = __builtin_amdgcn_mfma_f32_16x16x32_bf16(Bt[n][k], At[m][k], acc[ai][bj][m][n], 0, 0, 0); __builtin_amdgcn_s_setprio(0); } while (0)
; #define PG8_WAIT_V(n) asm volatile("s_waitcnt vmcnt(" #n ")" ::: "memory")
; #define PG8_WAIT_L(n) asm volatile("s_waitcnt lgkmcnt(" #n ")" ::: "memory")
; #define PG8_BAR __builtin_amdgcn_s_barrier()
; #define PG8_SCHED __builtin_amdgcn_sched_barrier(0)
; template <class Epi, class Sched, bool ALIGN_EPI = false, bool SP2 = false>
; __device__ __forceinline__ void gemm_phase(PG8_LAS unsigned char* lds, const Gemm g, const Sched& S, const Epi& E) {
;     ...
;             PG8_WAIT_V(8); PG8_WAIT_L(0); PG8_BAR; PG8_MMA(1, 0, At, B0); PG8_MMA(1, 1, At, B1); PG8_BAR; PG8_SCHED;
;             PG8_LDB(B0, 1, 0); PG8_LDB(B1, 1, 1); PG8_SCHED; PG8_LDA(At, 1, 0); PG8_STAGE(PG8_SA(0, 1), a2 + hstep, voffA);
;             PG8_WAIT_V(8); PG8_WAIT_L(0); PG8_BAR; PG8_MMA(0, 0, At, B0); PG8_MMA(0, 1, At, B1); PG8_BAR; PG8_SCHED;
	s_setprio 1
	s_waitcnt lgkmcnt(0)
	v_mfma_f32_16x16x32_bf16 v[62:65], v[140:143], v[176:179], v[62:65]
	v_mfma_f32_16x16x32_bf16 v[58:61], v[152:155], v[176:179], v[58:61]
	v_mfma_f32_16x16x32_bf16 v[46:49], v[140:143], v[184:187], v[46:49]
	v_mfma_f32_16x16x32_bf16 v[42:45], v[152:155], v[184:187], v[42:45]
	v_mfma_f32_16x16x32_bf16 v[30:33], v[140:143], v[198:201], v[30:33]
	v_mfma_f32_16x16x32_bf16 v[26:29], v[152:155], v[198:201], v[26:29]
	v_mfma_f32_16x16x32_bf16 v[14:17], v[140:143], v[206:209], v[14:17]
	v_mfma_f32_16x16x32_bf16 v[10:13], v[152:155], v[206:209], v[10:13]
	v_mfma_f32_16x16x32_bf16 v[62:65], v[144:147], v[180:183], v[62:65]
	v_mfma_f32_16x16x32_bf16 v[58:61], v[156:159], v[180:183], v[58:61]
	v_mfma_f32_16x16x32_bf16 v[46:49], v[144:147], v[194:197], v[46:49]
	v_mfma_f32_16x16x32_bf16 v[42:45], v[156:159], v[194:197], v[42:45]
	v_mfma_f32_16x16x32_bf16 v[30:33], v[144:147], v[202:205], v[30:33]
	v_mfma_f32_16x16x32_bf16 v[26:29], v[156:159], v[202:205], v[26:29]
	v_mfma_f32_16x16x32_bf16 v[14:17], v[144:147], v[210:213], v[14:17]
	v_mfma_f32_16x16x32_bf16 v[10:13], v[156:159], v[210:213], v[10:13]
	s_setprio 0
	s_setprio 1
	v_mfma_f32_16x16x32_bf16 v[54:57], v[160:163], v[176:179], v[54:57]
	v_mfma_f32_16x16x32_bf16 v[50:53], v[168:171], v[176:179], v[50:53]
	v_mfma_f32_16x16x32_bf16 v[38:41], v[160:163], v[184:187], v[38:41]
	v_mfma_f32_16x16x32_bf16 v[34:37], v[168:171], v[184:187], v[34:37]
	v_mfma_f32_16x16x32_bf16 v[22:25], v[160:163], v[198:201], v[22:25]
	v_mfma_f32_16x16x32_bf16 v[18:21], v[168:171], v[198:201], v[18:21]
	v_mfma_f32_16x16x32_bf16 v[6:9], v[160:163], v[206:209], v[6:9]
	v_mfma_f32_16x16x32_bf16 v[2:5], v[168:171], v[206:209], v[2:5]
	v_mfma_f32_16x16x32_bf16 v[54:57], v[164:167], v[180:183], v[54:57]
	v_mfma_f32_16x16x32_bf16 v[50:53], v[172:175], v[180:183], v[50:53]
	v_mfma_f32_16x16x32_bf16 v[38:41], v[164:167], v[194:197], v[38:41]
	v_mfma_f32_16x16x32_bf16 v[34:37], v[172:175], v[194:197], v[34:37]
	v_mfma_f32_16x16x32_bf16 v[22:25], v[164:167], v[202:205], v[22:25]
	v_mfma_f32_16x16x32_bf16 v[18:21], v[172:175], v[202:205], v[18:21]
	v_mfma_f32_16x16x32_bf16 v[6:9], v[164:167], v[210:213], v[6:9]
	v_mfma_f32_16x16x32_bf16 v[2:5], v[172:175], v[210:213], v[2:5]
	s_setprio 0
	s_barrier
	s_add_i32 s53, 0, 0x18000
	s_add_i32 s62, 0, 0x1c000
	v_add_u32_e32 v156, s53, v149
	v_add_u32_e32 v172, s62, v149
	ds_read_b128 v[140:143], v156
	ds_read_b128 v[144:147], v156 offset:1024
	ds_read_b128 v[152:155], v156 offset:2048
	ds_read_b128 v[156:159], v156 offset:3072
	ds_read_b128 v[160:163], v172
	ds_read_b128 v[164:167], v172 offset:1024
	ds_read_b128 v[168:171], v172 offset:2048
	ds_read_b128 v[172:175], v172 offset:3072
	s_add_u32 s60, s60, 0x40000
	s_addc_u32 s61, s61, 0
	s_mov_b32 m0, s27
	v_lshl_add_u64 v[220:221], s[60:61], 0, v[130:131]
	ds_read_b128 v[176:179], v151 offset:32768
	ds_read_b128 v[180:183], v151 offset:33792
	ds_read_b128 v[184:187], v151 offset:34816
	ds_read_b128 v[194:197], v151 offset:35840
	ds_read_b128 v[198:201], v151 offset:36864
	ds_read_b128 v[202:205], v151 offset:37888
	ds_read_b128 v[206:209], v151 offset:38912
	ds_read_b128 v[210:213], v151 offset:39936
	global_load_lds_dwordx4 v[220:221], off
	v_lshl_add_u64 v[220:221], s[60:61], 0, v[132:133]
	s_mov_b32 m0, s28
	s_nop 0
	global_load_lds_dwordx4 v[220:221], off
	s_waitcnt vmcnt(8)
	s_waitcnt lgkmcnt(0)
	s_barrier
	s_setprio 1
	s_waitcnt lgkmcnt(0)
	v_mfma_f32_16x16x32_bf16 v[126:129], v[140:143], v[176:179], v[126:129]
	v_mfma_f32_16x16x32_bf16 v[122:125], v[152:155], v[176:179], v[122:125]
	v_mfma_f32_16x16x32_bf16 v[118:121], v[140:143], v[184:187], v[118:121]
	v_mfma_f32_16x16x32_bf16 v[110:113], v[152:155], v[184:187], v[110:113]
	v_mfma_f32_16x16x32_bf16 v[94:97], v[140:143], v[198:201], v[94:97]
	v_mfma_f32_16x16x32_bf16 v[90:93], v[152:155], v[198:201], v[90:93]
	v_mfma_f32_16x16x32_bf16 v[78:81], v[140:143], v[206:209], v[78:81]
	v_mfma_f32_16x16x32_bf16 v[74:77], v[152:155], v[206:209], v[74:77]
	v_mfma_f32_16x16x32_bf16 v[126:129], v[144:147], v[180:183], v[126:129]
	v_mfma_f32_16x16x32_bf16 v[122:125], v[156:159], v[180:183], v[122:125]
	v_mfma_f32_16x16x32_bf16 v[118:121], v[144:147], v[194:197], v[118:121]
	v_mfma_f32_16x16x32_bf16 v[110:113], v[156:159], v[194:197], v[110:113]
	v_mfma_f32_16x16x32_bf16 v[94:97], v[144:147], v[202:205], v[94:97]
	v_mfma_f32_16x16x32_bf16 v[90:93], v[156:159], v[202:205], v[90:93]
	v_mfma_f32_16x16x32_bf16 v[78:81], v[144:147], v[210:213], v[78:81]
	v_mfma_f32_16x16x32_bf16 v[74:77], v[156:159], v[210:213], v[74:77]
	s_setprio 0
	s_setprio 1
	v_mfma_f32_16x16x32_bf16 v[114:117], v[160:163], v[176:179], v[114:117]
	v_mfma_f32_16x16x32_bf16 v[106:109], v[168:171], v[176:179], v[106:109]
	v_mfma_f32_16x16x32_bf16 v[102:105], v[160:163], v[184:187], v[102:105]
	v_mfma_f32_16x16x32_bf16 v[98:101], v[168:171], v[184:187], v[98:101]
	v_mfma_f32_16x16x32_bf16 v[86:89], v[160:163], v[198:201], v[86:89]
	v_mfma_f32_16x16x32_bf16 v[82:85], v[168:171], v[198:201], v[82:85]
	v_mfma_f32_16x16x32_bf16 v[70:73], v[160:163], v[206:209], v[70:73]
	v_mfma_f32_16x16x32_bf16 v[66:69], v[168:171], v[206:209], v[66:69]
	v_mfma_f32_16x16x32_bf16 v[114:117], v[164:167], v[180:183], v[114:117]
	v_mfma_f32_16x16x32_bf16 v[106:109], v[172:175], v[180:183], v[106:109]
	v_mfma_f32_16x16x32_bf16 v[102:105], v[164:167], v[194:197], v[102:105]
	v_mfma_f32_16x16x32_bf16 v[98:101], v[172:175], v[194:197], v[98:101]
	v_mfma_f32_16x16x32_bf16 v[86:89], v[164:167], v[202:205], v[86:89]
	v_mfma_f32_16x16x32_bf16 v[82:85], v[172:175], v[202:205], v[82:85]
	v_mfma_f32_16x16x32_bf16 v[70:73], v[164:167], v[210:213], v[70:73]
	v_mfma_f32_16x16x32_bf16 v[66:69], v[172:175], v[210:213], v[66:69]
	s_setprio 0
	s_barrier
; #define PG8_STAGE(bufoff, gbase, voff) do { _Pragma("unroll") for (int _i = 0; _i < 2; ++_i) \
;         __builtin_amdgcn_global_load_lds((const unsigned*)((const char*)(gbase) + (voff)[_i]), (PG8_LAS unsigned*)(lds + (bufoff) + ldsw + _i * 8192), 16, 0, 0); } while (0)
; #define PG8_LDA(dst, b, h) do { _Pragma("unroll") for (int m = 0; m < 4; ++m) _Pragma("unroll") for (int k = 0; k < 2; ++k) dst[m][k] = *(const PG8_LAS bf16x8*)(lds + PG8_SA(b, h) + aoff + m * 2048 + k * 1024); } while (0)
; #define PG8_MMA(ai, bj, At, Bt) do { __builtin_amdgcn_s_setprio(1); _Pragma("unroll") for (int m = 0; m < 4; ++m) _Pragma("unroll") for (int n = 0; n < 2; ++n) _Pragma("unroll") for (int k = 0; k < 2; ++k) \
;         acc[ai][bj][m][n] = __builtin_amdgcn_mfma_f32_16x16x32_bf16(Bt[n][k], At[m][k], acc[ai][bj][m][n], 0, 0, 0); __builtin_amdgcn_s_setprio(0); } while (0)
; #define PG8_WAIT_V(n) asm volatile("s_waitcnt vmcnt(" #n ")" ::: "memory")
; #define PG8_WAIT_L(n) asm volatile("s_waitcnt lgkmcnt(" #n ")" ::: "memory")
; #define PG8_BAR __builtin_amdgcn_s_barrier()
; #define PG8_SCHED __builtin_amdgcn_sched_barrier(0)
; template <class Epi, class Sched, bool ALIGN_EPI = false, bool SP2 = false>
; __device__ __forceinline__ void gemm_phase(PG8_LAS unsigned char* lds, const Gemm g, const Sched& S, const Epi& E) {
;     ...
;             PG8_LDA(At, 1, 1); PG8_STAGE(PG8_SB(1, 0), b3, voffB); PG8_STAGE(PG8_SB(1, 1), b3 + hstep, voffB); PG8_STAGE(PG8_SA(1, 0), a3, voffA);
;             PG8_WAIT_V(8); PG8_WAIT_L(0); PG8_BAR; PG8_MMA(1, 0, At, B0); PG8_MMA(1, 1, At, B1); PG8_BAR; PG8_SCHED;
;     ...
;         if constexpr (ALIGN_EPI) { if (wr == 0) PG8_BAR; }
	s_add_i32 s53, s53, s24
	v_lshl_add_u64 v[188:189], v[188:189], 0, s[8:9]
	s_mov_b32 m0, s53
	ds_read_b128 v[176:179], v151 offset:49152
	ds_read_b128 v[180:183], v151 offset:50176
	ds_read_b128 v[184:187], v151 offset:51200
	ds_read_b128 v[194:197], v151 offset:52224
	ds_read_b128 v[198:201], v151 offset:53248
	ds_read_b128 v[202:205], v151 offset:54272
	ds_read_b128 v[206:209], v151 offset:55296
	ds_read_b128 v[210:213], v151 offset:56320
	global_load_lds_dwordx4 v[188:189], off
	s_add_i32 m0, s53, 0x2000
	s_add_u32 s58, s58, 0x40080
	v_lshl_add_u64 v[188:189], v[214:215], 0, s[8:9]
	s_addc_u32 s59, s59, 0
	s_add_i32 s53, s62, s24
	global_load_lds_dwordx4 v[188:189], off
	v_lshl_add_u64 v[188:189], s[58:59], 0, v[0:1]
	s_mov_b32 m0, s53
	s_nop 0
	global_load_lds_dwordx4 v[188:189], off
	v_lshl_add_u64 v[188:189], s[58:59], 0, v[134:135]
	s_add_i32 m0, s53, 0x2000
	s_nop 0
	global_load_lds_dwordx4 v[188:189], off
	v_lshl_add_u64 v[188:189], v[216:217], 0, s[8:9]
	s_mov_b32 m0, s29
	s_nop 0
	global_load_lds_dwordx4 v[188:189], off
	v_lshl_add_u64 v[188:189], v[218:219], 0, s[8:9]
	s_mov_b32 m0, s55
	s_nop 0
	global_load_lds_dwordx4 v[188:189], off
	s_waitcnt vmcnt(8)
	s_waitcnt lgkmcnt(0)
	s_barrier
	s_setprio 1
	s_waitcnt lgkmcnt(0)
	v_mfma_f32_16x16x32_bf16 v[62:65], v[140:143], v[176:179], v[62:65]
	v_mfma_f32_16x16x32_bf16 v[58:61], v[152:155], v[176:179], v[58:61]
	v_mfma_f32_16x16x32_bf16 v[46:49], v[140:143], v[184:187], v[46:49]
	v_mfma_f32_16x16x32_bf16 v[42:45], v[152:155], v[184:187], v[42:45]
	v_mfma_f32_16x16x32_bf16 v[30:33], v[140:143], v[198:201], v[30:33]
	v_mfma_f32_16x16x32_bf16 v[26:29], v[152:155], v[198:201], v[26:29]
	v_mfma_f32_16x16x32_bf16 v[14:17], v[140:143], v[206:209], v[14:17]
	v_mfma_f32_16x16x32_bf16 v[10:13], v[152:155], v[206:209], v[10:13]
	v_mfma_f32_16x16x32_bf16 v[62:65], v[144:147], v[180:183], v[62:65]
	v_mfma_f32_16x16x32_bf16 v[58:61], v[156:159], v[180:183], v[58:61]
	v_mfma_f32_16x16x32_bf16 v[46:49], v[144:147], v[194:197], v[46:49]
	v_mfma_f32_16x16x32_bf16 v[42:45], v[156:159], v[194:197], v[42:45]
	v_mfma_f32_16x16x32_bf16 v[30:33], v[144:147], v[202:205], v[30:33]
	v_mfma_f32_16x16x32_bf16 v[26:29], v[156:159], v[202:205], v[26:29]
	v_mfma_f32_16x16x32_bf16 v[14:17], v[144:147], v[210:213], v[14:17]
	v_mfma_f32_16x16x32_bf16 v[10:13], v[156:159], v[210:213], v[10:13]
	s_setprio 0
	s_setprio 1
	v_mfma_f32_16x16x32_bf16 v[54:57], v[160:163], v[176:179], v[54:57]
	v_mfma_f32_16x16x32_bf16 v[50:53], v[168:171], v[176:179], v[50:53]
	v_mfma_f32_16x16x32_bf16 v[38:41], v[160:163], v[184:187], v[38:41]
	v_mfma_f32_16x16x32_bf16 v[34:37], v[168:171], v[184:187], v[34:37]
	v_mfma_f32_16x16x32_bf16 v[22:25], v[160:163], v[198:201], v[22:25]
	v_mfma_f32_16x16x32_bf16 v[18:21], v[168:171], v[198:201], v[18:21]
	v_mfma_f32_16x16x32_bf16 v[6:9], v[160:163], v[206:209], v[6:9]
	v_mfma_f32_16x16x32_bf16 v[2:5], v[168:171], v[206:209], v[2:5]
	v_mfma_f32_16x16x32_bf16 v[54:57], v[164:167], v[180:183], v[54:57]
	v_mfma_f32_16x16x32_bf16 v[50:53], v[172:175], v[180:183], v[50:53]
	v_mfma_f32_16x16x32_bf16 v[38:41], v[164:167], v[194:197], v[38:41]
	v_mfma_f32_16x16x32_bf16 v[34:37], v[172:175], v[194:197], v[34:37]
	v_mfma_f32_16x16x32_bf16 v[22:25], v[164:167], v[202:205], v[22:25]
	v_mfma_f32_16x16x32_bf16 v[18:21], v[172:175], v[202:205], v[18:21]
	v_mfma_f32_16x16x32_bf16 v[6:9], v[164:167], v[210:213], v[6:9]
	v_mfma_f32_16x16x32_bf16 v[2:5], v[172:175], v[210:213], v[2:5]
	s_setprio 0
	s_barrier
	s_add_i32 s52, s52, 2
	s_add_u32 s18, s18, 0x100
	s_addc_u32 s19, s19, 0
	s_add_u32 s43, s43, 0x100
	s_addc_u32 s45, s45, 0
	s_cmp_gt_u32 s52, 13
	s_cbranch_scc0 .LBB0_522


; #define PG8_BAR __builtin_amdgcn_s_barrier()
; template <class Epi, class Sched, bool ALIGN_EPI = false, bool SP2 = false>
; __device__ __forceinline__ void gemm_phase(PG8_LAS unsigned char* lds, const Gemm g, const Sched& S, const Epi& E) {
;     ...
;         if constexpr (ALIGN_EPI) { if (wr == 0) PG8_BAR; }
;     __device__ __forceinline__ void operator()(const f32x4 (&acc)[2][2][4][2], const pg8::Unit& u, int wr, int wc, int fr, int fq) const {
;         const int row0 = u.pm * 256 + wr * 64 + fr, col0 = u.pn * 256 + wc * 32 + 8 * fq;
;         float sq[2][4];
;         if (MODE == 1) {
; #pragma unroll
;             for (int ai = 0; ai < 2; ++ai) { f32x4 b[4][2][2];
; #pragma unroll
;                 for (int m = 0; m < 4; ++m)
; #pragma unroll
;                     for (int bj = 0; bj < 2; ++bj) { const size_t off = (size_t)(row0 + ai * 128 + m * 16) * DM + col0 + bj * 128;
;                         b[m][bj][0] = *(const f32x4*)(x32 + off); b[m][bj][1] = *(const f32x4*)(x32 + off + 4); }
; #pragma unroll
;                 for (int m = 0; m < 4; ++m) { float q = 0.f;
; #pragma unroll
;                     for (int bj = 0; bj < 2; ++bj) q += emit(b[m][bj][0] + acc[ai][bj][m][0] * alpha, b[m][bj][1] + acc[ai][bj][m][1] * alpha, (size_t)(row0 + ai * 128 + m * 16) * DM + col0 + bj * 128);
;                     sq[ai][m] = q; } }
.LBB0_525:
	v_lshl_add_u32 v140, s56, 8, v148
	v_lshl_or_b32 v142, s54, 8, v150
	v_ashrrev_i32_e32 v143, 31, v142
	v_ashrrev_i32_e32 v141, 31, v140
	v_lshl_add_u64 v[144:145], v[142:143], 2, s[74:75]
	v_lshlrev_b64 v[146:147], 12, v[140:141]
	v_lshl_add_u64 v[146:147], v[144:145], 0, v[146:147]
	v_or_b32_e32 v184, 16, v140
	global_load_dwordx4 v[152:155], v[146:147], off
	global_load_dwordx4 v[156:159], v[146:147], off offset:16
	global_load_dwordx4 v[160:163], v[146:147], off offset:512
	global_load_dwordx4 v[164:167], v[146:147], off offset:528
	v_ashrrev_i32_e32 v185, 31, v184
	v_lshlrev_b64 v[146:147], 12, v[184:185]
	v_lshl_add_u64 v[180:181], v[144:145], 0, v[146:147]
	global_load_dwordx4 v[168:171], v[180:181], off
	global_load_dwordx4 v[172:175], v[180:181], off offset:16
	global_load_dwordx4 v[176:179], v[180:181], off offset:528
	s_nop 0
	global_load_dwordx4 v[180:183], v[180:181], off offset:512
	v_or_b32_e32 v188, 32, v140
	v_or_b32_e32 v146, 48, v140
	v_ashrrev_i32_e32 v189, 31, v188
	v_ashrrev_i32_e32 v147, 31, v146
	v_lshlrev_b64 v[186:187], 11, v[140:141]
	v_lshlrev_b64 v[194:195], 12, v[188:189]
	v_lshlrev_b64 v[196:197], 12, v[146:147]
	v_lshlrev_b64 v[142:143], 1, v[142:143]
	v_lshl_add_u64 v[186:187], s[96:97], 0, v[186:187]
	v_lshlrev_b64 v[184:185], 11, v[184:185]
	v_lshl_add_u64 v[202:203], v[144:145], 0, v[194:195]
	v_lshl_add_u64 v[218:219], v[144:145], 0, v[196:197]
	v_lshl_add_u64 v[222:223], v[186:187], 0, v[142:143]
	v_lshl_add_u64 v[224:225], s[96:97], 0, v[184:185]
	global_load_dwordx4 v[184:187], v[202:203], off offset:16
	global_load_dwordx4 v[194:197], v[202:203], off
	global_load_dwordx4 v[198:201], v[202:203], off offset:528
	s_nop 0
	global_load_dwordx4 v[202:205], v[202:203], off offset:512
	s_nop 0
	global_load_dwordx4 v[206:209], v[218:219], off offset:16
	global_load_dwordx4 v[210:213], v[218:219], off
	global_load_dwordx4 v[214:217], v[218:219], off offset:528
	s_nop 0
	global_load_dwordx4 v[218:221], v[218:219], off offset:512
	v_lshl_add_u64 v[224:225], v[224:225], 0, v[142:143]
	s_and_b64 vcc, exec, s[40:41]
	s_cbranch_vccz .Lalign_go_4
	s_barrier
.Lalign_go_4:
	s_waitcnt vmcnt(0)
	v_pk_fma_f32 v[128:129], v[128:129], 0.5, v[154:155] op_sel_hi:[1,0,1]
	v_pk_fma_f32 v[126:127], v[126:127], 0.5, v[152:153] op_sel_hi:[1,0,1]
	v_pk_fma_f32 v[152:153], v[116:117], 0.5, v[162:163] op_sel_hi:[1,0,1]
	v_pk_fma_f32 v[154:155], v[114:115], 0.5, v[160:161] op_sel_hi:[1,0,1]
	v_pk_fma_f32 v[124:125], v[124:125], 0.5, v[158:159] op_sel_hi:[1,0,1]
	v_pk_fma_f32 v[122:123], v[122:123], 0.5, v[156:157] op_sel_hi:[1,0,1]
	v_pk_fma_f32 v[158:159], v[106:107], 0.5, v[164:165] op_sel_hi:[1,0,1]
	v_cvt_pk_bf16_f32 v106, v126, v127
	v_cvt_pk_bf16_f32 v107, v128, v129
	v_mul_f32_e32 v127, v127, v127
	v_mul_f32_e32 v129, v129, v129
	v_cvt_pk_bf16_f32 v114, v154, v155
	v_cvt_pk_bf16_f32 v115, v152, v153
	v_mul_f32_e32 v155, v155, v155
	v_mul_f32_e32 v153, v153, v153
	v_pk_fma_f32 v[156:157], v[108:109], 0.5, v[166:167] op_sel_hi:[1,0,1]
	v_cvt_pk_bf16_f32 v108, v122, v123
	v_cvt_pk_bf16_f32 v109, v124, v125
	v_mul_f32_e32 v123, v123, v123
	v_cvt_pk_bf16_f32 v116, v158, v159
	v_mul_f32_e32 v159, v159, v159
	v_fmac_f32_e32 v127, v126, v126
	v_fmac_f32_e32 v129, v128, v128
	v_fmac_f32_e32 v155, v154, v154
	v_fmac_f32_e32 v153, v152, v152
	v_mul_f32_e32 v125, v125, v125
	v_cvt_pk_bf16_f32 v117, v156, v157
	v_mul_f32_e32 v157, v157, v157
	global_store_dwordx4 v[222:223], v[106:109], off
	v_fmac_f32_e32 v123, v122, v122
	v_fmac_f32_e32 v159, v158, v158
	v_add_f32_e32 v106, v127, v129
	v_add_f32_e32 v107, v155, v153
	v_pk_fma_f32 v[120:121], v[120:121], 0.5, v[170:171] op_sel_hi:[1,0,1]
	v_pk_fma_f32 v[118:119], v[118:119], 0.5, v[168:169] op_sel_hi:[1,0,1]
	v_pk_fma_f32 v[112:113], v[112:113], 0.5, v[174:175] op_sel_hi:[1,0,1]
	v_pk_fma_f32 v[160:161], v[110:111], 0.5, v[172:173] op_sel_hi:[1,0,1]
	v_fmac_f32_e32 v125, v124, v124
	v_fmac_f32_e32 v157, v156, v156
	v_add_f32_e32 v106, v123, v106
	v_add_f32_e32 v107, v159, v107
	v_cvt_pk_bf16_f32 v108, v118, v119
	v_cvt_pk_bf16_f32 v109, v120, v121
	v_cvt_pk_bf16_f32 v110, v160, v161
	v_cvt_pk_bf16_f32 v111, v112, v113
	v_add_f32_e32 v106, v125, v106
	v_add_f32_e32 v107, v157, v107
	v_add_f32_e32 v106, v106, v107
	global_store_dwordx4 v[224:225], v[108:111], off
	v_mul_f32_e32 v107, v119, v119
	v_fmac_f32_e32 v107, v118, v118
	v_mul_f32_e32 v108, v121, v121
	v_fmac_f32_e32 v108, v120, v120
	v_add_f32_e32 v107, v107, v108
	v_mul_f32_e32 v108, v161, v161
	v_fmac_f32_e32 v108, v160, v160
	v_add_f32_e32 v107, v108, v107
	v_mul_f32_e32 v108, v113, v113
	v_fmac_f32_e32 v108, v112, v112
	v_add_f32_e32 v107, v108, v107
	v_pk_fma_f32 v[104:105], v[104:105], 0.5, v[182:183] op_sel_hi:[1,0,1]
	v_pk_fma_f32 v[102:103], v[102:103], 0.5, v[180:181] op_sel_hi:[1,0,1]
	v_pk_fma_f32 v[108:109], v[100:101], 0.5, v[178:179] op_sel_hi:[1,0,1]
	v_pk_fma_f32 v[110:111], v[98:99], 0.5, v[176:177] op_sel_hi:[1,0,1]
	v_cvt_pk_bf16_f32 v98, v102, v103
	v_cvt_pk_bf16_f32 v99, v104, v105
	v_cvt_pk_bf16_f32 v100, v110, v111
	v_cvt_pk_bf16_f32 v101, v108, v109
	global_store_dwordx4 v[224:225], v[98:101], off offset:256
	v_pk_fma_f32 v[96:97], v[96:97], 0.5, v[196:197] op_sel_hi:[1,0,1]
	v_pk_fma_f32 v[94:95], v[94:95], 0.5, v[194:195] op_sel_hi:[1,0,1]
	v_mul_f32_e32 v98, v103, v103
	v_mul_f32_e32 v99, v105, v105
	v_fmac_f32_e32 v98, v102, v102
	v_fmac_f32_e32 v99, v104, v104
	v_add_f32_e32 v122, v98, v99
	v_lshlrev_b64 v[98:99], 11, v[188:189]
	v_pk_fma_f32 v[100:101], v[92:93], 0.5, v[186:187] op_sel_hi:[1,0,1]
	v_pk_fma_f32 v[102:103], v[90:91], 0.5, v[184:185] op_sel_hi:[1,0,1]
; __device__ __forceinline__ unsigned pkbf(float lo, float hi) { const f32x2_t v = {lo, hi}; const bf16x2_t b = __builtin_convertvector(v, bf16x2_t); return __builtin_bit_cast(unsigned, b); }
;     __device__ __forceinline__ void operator()(const f32x4 (&acc)[2][2][4][2], const pg8::Unit& u, int wr, int wc, int fr, int fq) const {
;     ...
;             for (int ai = 0; ai < 2; ++ai) { f32x4 b[4][2][2];
; #pragma unroll
;                 for (int m = 0; m < 4; ++m)
; #pragma unroll
;                     for (int bj = 0; bj < 2; ++bj) { const size_t off = (size_t)(row0 + ai * 128 + m * 16) * DM + col0 + bj * 128;
;                         b[m][bj][0] = *(const f32x4*)(x32 + off); b[m][bj][1] = *(const f32x4*)(x32 + off + 4); }
; #pragma unroll
;                 for (int m = 0; m < 4; ++m) { float q = 0.f;
; #pragma unroll
;                     for (int bj = 0; bj < 2; ++bj) q += emit(b[m][bj][0] + acc[ai][bj][m][0] * alpha, b[m][bj][1] + acc[ai][bj][m][1] * alpha, (size_t)(row0 + ai * 128 + m * 16) * DM + col0 + bj * 128);
;                     sq[ai][m] = q; } }
;     __device__ __forceinline__ float emit(const f32x4 v0, const f32x4 v1, size_t off) const {
;         if (MODE == 2) { *(f32x4*)(out + off) = v0; *(f32x4*)(out + off + 4) = v1; return 0.f; }
;         u32x4 w; w.x = pkbf(v0[0], v0[1]); w.y = pkbf(v0[2], v0[3]); w.z = pkbf(v1[0], v1[1]); w.w = pkbf(v1[2], v1[3]);
;         *(u32x4*)(xb + off) = w;
;         return (v0[0] * v0[0] + v0[1] * v0[1]) + (v0[2] * v0[2] + v0[3] * v0[3]) + (v1[0] * v1[0] + v1[1] * v1[1]) + (v1[2] * v1[2] + v1[3] * v1[3]);
	v_lshl_add_u64 v[98:99], s[96:97], 0, v[98:99]
	v_cvt_pk_bf16_f32 v90, v94, v95
	v_cvt_pk_bf16_f32 v91, v96, v97
	v_cvt_pk_bf16_f32 v92, v102, v103
	v_cvt_pk_bf16_f32 v93, v100, v101
	v_lshl_add_u64 v[98:99], v[98:99], 0, v[142:143]
	global_store_dwordx4 v[98:99], v[90:93], off
	v_pk_fma_f32 v[86:87], v[86:87], 0.5, v[202:203] op_sel_hi:[1,0,1]
	v_pk_fma_f32 v[104:105], v[82:83], 0.5, v[198:199] op_sel_hi:[1,0,1]
	v_pk_fma_f32 v[90:91], v[88:89], 0.5, v[204:205] op_sel_hi:[1,0,1]
	v_pk_fma_f32 v[92:93], v[84:85], 0.5, v[200:201] op_sel_hi:[1,0,1]
	v_cvt_pk_bf16_f32 v82, v86, v87
	v_cvt_pk_bf16_f32 v83, v90, v91
	v_cvt_pk_bf16_f32 v84, v104, v105
	v_cvt_pk_bf16_f32 v85, v92, v93
	global_store_dwordx4 v[98:99], v[82:85], off offset:256
	v_pk_fma_f32 v[112:113], v[78:79], 0.5, v[210:211] op_sel_hi:[1,0,1]
	v_pk_fma_f32 v[72:73], v[72:73], 0.5, v[220:221] op_sel_hi:[1,0,1]
	v_lshlrev_b64 v[82:83], 11, v[146:147]
	v_lshl_add_u64 v[78:79], s[96:97], 0, v[82:83]
	v_pk_fma_f32 v[70:71], v[70:71], 0.5, v[218:219] op_sel_hi:[1,0,1]
	v_pk_fma_f32 v[118:119], v[68:69], 0.5, v[216:217] op_sel_hi:[1,0,1]
	v_pk_fma_f32 v[120:121], v[66:67], 0.5, v[214:215] op_sel_hi:[1,0,1]
	v_add_u32_e32 v128, 0x80, v140
	global_store_dwordx4 v[222:223], v[114:117], off offset:256
	v_mul_f32_e32 v111, v111, v111
	v_pk_fma_f32 v[98:99], v[80:81], 0.5, v[212:213] op_sel_hi:[1,0,1]
	v_pk_fma_f32 v[114:115], v[76:77], 0.5, v[208:209] op_sel_hi:[1,0,1]
	v_pk_fma_f32 v[116:117], v[74:75], 0.5, v[206:207] op_sel_hi:[1,0,1]
	v_lshl_add_u64 v[78:79], v[78:79], 0, v[142:143]
	v_cvt_pk_bf16_f32 v66, v70, v71
	v_cvt_pk_bf16_f32 v67, v72, v73
	v_cvt_pk_bf16_f32 v68, v120, v121
	v_cvt_pk_bf16_f32 v69, v118, v119
	v_ashrrev_i32_e32 v129, 31, v128
	v_cvt_pk_bf16_f32 v74, v112, v113
	v_cvt_pk_bf16_f32 v75, v98, v99
	v_cvt_pk_bf16_f32 v76, v116, v117
	v_cvt_pk_bf16_f32 v77, v114, v115
	global_store_dwordx4 v[78:79], v[66:69], off offset:256
	v_fmac_f32_e32 v111, v110, v110
	global_store_dwordx4 v[78:79], v[74:77], off
	v_lshlrev_b64 v[66:67], 12, v[128:129]
	v_mul_f32_e32 v69, v109, v109
	v_lshl_add_u64 v[66:67], v[144:145], 0, v[66:67]
	v_add_f32_e32 v68, v111, v122
	v_fmac_f32_e32 v69, v108, v108
	global_load_dwordx4 v[74:77], v[66:67], off offset:16
	global_load_dwordx4 v[78:81], v[66:67], off
	v_add_f32_e32 v68, v69, v68
	v_add_f32_e32 v107, v107, v68
	v_mul_f32_e32 v68, v95, v95
	v_mul_f32_e32 v69, v97, v97
	v_fmac_f32_e32 v68, v94, v94
	v_fmac_f32_e32 v69, v96, v96
	v_add_f32_e32 v68, v68, v69
	v_mul_f32_e32 v69, v103, v103
	v_fmac_f32_e32 v69, v102, v102
	v_add_f32_e32 v68, v69, v68
	v_mul_f32_e32 v69, v101, v101
	v_fmac_f32_e32 v69, v100, v100
	v_add_f32_e32 v68, v69, v68
	v_mul_f32_e32 v69, v87, v87
	v_fmac_f32_e32 v69, v86, v86
	v_mul_f32_e32 v91, v91, v91
	global_load_dwordx4 v[82:85], v[66:67], off offset:528
	global_load_dwordx4 v[86:89], v[66:67], off offset:512
	v_fmac_f32_e32 v91, v90, v90
	v_mul_f32_e32 v67, v105, v105
	v_add_f32_e32 v66, v69, v91
	v_fmac_f32_e32 v67, v104, v104
	v_add_f32_e32 v66, v67, v66
	v_mul_f32_e32 v67, v93, v93
	v_fmac_f32_e32 v67, v92, v92
	v_add_f32_e32 v66, v67, v66
	v_add_f32_e32 v158, v68, v66
	v_mul_f32_e32 v66, v113, v113
	v_mul_f32_e32 v67, v99, v99
	v_add_u32_e32 v152, 0x90, v140
	v_fmac_f32_e32 v66, v112, v112
	v_fmac_f32_e32 v67, v98, v98
	v_ashrrev_i32_e32 v153, 31, v152
	v_add_f32_e32 v68, v66, v67
	v_lshlrev_b64 v[66:67], 12, v[152:153]
	v_lshl_add_u64 v[66:67], v[144:145], 0, v[66:67]
	global_load_dwordx4 v[90:93], v[66:67], off offset:16
	global_load_dwordx4 v[94:97], v[66:67], off
	global_load_dwordx4 v[98:101], v[66:67], off offset:528
	global_load_dwordx4 v[102:105], v[66:67], off offset:512
	v_mul_f32_e32 v69, v117, v117
	v_fmac_f32_e32 v69, v116, v116
	v_add_f32_e32 v68, v69, v68
	v_mul_f32_e32 v69, v115, v115
	v_fmac_f32_e32 v69, v114, v114
	v_add_f32_e32 v68, v69, v68
	v_mul_f32_e32 v69, v71, v71
	v_fmac_f32_e32 v69, v70, v70
	v_mul_f32_e32 v70, v73, v73
	v_fmac_f32_e32 v70, v72, v72
	v_add_u32_e32 v154, 0xa0, v140
	v_add_f32_e32 v69, v69, v70
	v_mul_f32_e32 v70, v121, v121
	v_ashrrev_i32_e32 v155, 31, v154
	v_fmac_f32_e32 v70, v120, v120
	v_lshlrev_b64 v[66:67], 12, v[154:155]
	v_add_f32_e32 v69, v70, v69
	v_mul_f32_e32 v70, v119, v119
	v_lshl_add_u64 v[66:67], v[144:145], 0, v[66:67]
	v_fmac_f32_e32 v70, v118, v118
	global_load_dwordx4 v[108:111], v[66:67], off offset:16
	global_load_dwordx4 v[112:115], v[66:67], off
	global_load_dwordx4 v[116:119], v[66:67], off offset:528
	global_load_dwordx4 v[120:123], v[66:67], off offset:512
	v_add_u32_e32 v156, 0xb0, v140
	v_ashrrev_i32_e32 v157, 31, v156
	v_lshlrev_b64 v[66:67], 12, v[156:157]
	v_add_f32_e32 v69, v70, v69
	v_lshl_add_u64 v[70:71], v[144:145], 0, v[66:67]
	v_add_f32_e32 v159, v68, v69
	global_load_dwordx4 v[124:127], v[70:71], off offset:16
	global_load_dwordx4 v[144:147], v[70:71], off
	global_load_dwordx4 v[66:69], v[70:71], off offset:528
	s_nop 0
	global_load_dwordx4 v[70:73], v[70:71], off offset:512
	v_lshlrev_b64 v[128:129], 11, v[128:129]
	s_waitcnt vmcnt(15)
	v_pk_fma_f32 v[76:77], v[60:61], 0.5, v[76:77] op_sel_hi:[1,0,1]
	s_waitcnt vmcnt(14)
	v_pk_fma_f32 v[64:65], v[64:65], 0.5, v[80:81] op_sel_hi:[1,0,1]
	v_pk_fma_f32 v[62:63], v[62:63], 0.5, v[78:79] op_sel_hi:[1,0,1]
	v_pk_fma_f32 v[74:75], v[58:59], 0.5, v[74:75] op_sel_hi:[1,0,1]
	v_lshl_add_u64 v[78:79], s[96:97], 0, v[128:129]
	v_cvt_pk_bf16_f32 v58, v62, v63
	v_cvt_pk_bf16_f32 v59, v64, v65
	v_cvt_pk_bf16_f32 v60, v74, v75
	v_cvt_pk_bf16_f32 v61, v76, v77
	v_lshl_add_u64 v[78:79], v[78:79], 0, v[142:143]
	global_store_dwordx4 v[78:79], v[58:61], off
	s_waitcnt vmcnt(13)
; __device__ __forceinline__ unsigned pkbf(float lo, float hi) { const f32x2_t v = {lo, hi}; const bf16x2_t b = __builtin_convertvector(v, bf16x2_t); return __builtin_bit_cast(unsigned, b); }
;     __device__ __forceinline__ void operator()(const f32x4 (&acc)[2][2][4][2], const pg8::Unit& u, int wr, int wc, int fr, int fq) const {
;     ...
;                 for (int m = 0; m < 4; ++m) { float q = 0.f;
; #pragma unroll
;                     for (int bj = 0; bj < 2; ++bj) q += emit(b[m][bj][0] + acc[ai][bj][m][0] * alpha, b[m][bj][1] + acc[ai][bj][m][1] * alpha, (size_t)(row0 + ai * 128 + m * 16) * DM + col0 + bj * 128);
;                     sq[ai][m] = q; } }
;     __device__ __forceinline__ float emit(const f32x4 v0, const f32x4 v1, size_t off) const {
;         if (MODE == 2) { *(f32x4*)(out + off) = v0; *(f32x4*)(out + off + 4) = v1; return 0.f; }
;         u32x4 w; w.x = pkbf(v0[0], v0[1]); w.y = pkbf(v0[2], v0[3]); w.z = pkbf(v1[0], v1[1]); w.w = pkbf(v1[2], v1[3]);
;         *(u32x4*)(xb + off) = w;
;         return (v0[0] * v0[0] + v0[1] * v0[1]) + (v0[2] * v0[2] + v0[3] * v0[3]) + (v1[0] * v1[0] + v1[1] * v1[1]) + (v1[2] * v1[2] + v1[3] * v1[3]);
	v_pk_fma_f32 v[56:57], v[56:57], 0.5, v[88:89] op_sel_hi:[1,0,1]
	v_mul_f32_e32 v58, v63, v63
	v_mul_f32_e32 v59, v65, v65
	v_fmac_f32_e32 v58, v62, v62
	v_fmac_f32_e32 v59, v64, v64
	v_add_f32_e32 v58, v58, v59
	v_mul_f32_e32 v59, v75, v75
	v_fmac_f32_e32 v59, v74, v74
	v_add_f32_e32 v58, v59, v58
	v_mul_f32_e32 v59, v77, v77
	v_fmac_f32_e32 v59, v76, v76
	v_add_f32_e32 v62, v59, v58
	v_pk_fma_f32 v[54:55], v[54:55], 0.5, v[86:87] op_sel_hi:[1,0,1]
	v_pk_fma_f32 v[58:59], v[52:53], 0.5, v[84:85] op_sel_hi:[1,0,1]
	v_pk_fma_f32 v[60:61], v[50:51], 0.5, v[82:83] op_sel_hi:[1,0,1]
	v_cvt_pk_bf16_f32 v50, v54, v55
	v_cvt_pk_bf16_f32 v51, v56, v57
	v_cvt_pk_bf16_f32 v52, v60, v61
	v_cvt_pk_bf16_f32 v53, v58, v59
	global_store_dwordx4 v[78:79], v[50:53], off offset:256
	s_waitcnt vmcnt(12)
	v_pk_fma_f32 v[48:49], v[48:49], 0.5, v[96:97] op_sel_hi:[1,0,1]
	v_pk_fma_f32 v[46:47], v[46:47], 0.5, v[94:95] op_sel_hi:[1,0,1]
	v_mul_f32_e32 v50, v55, v55
	v_mul_f32_e32 v51, v57, v57
	v_fmac_f32_e32 v50, v54, v54
	v_fmac_f32_e32 v51, v56, v56
	v_add_f32_e32 v50, v50, v51
	v_mul_f32_e32 v51, v61, v61
	v_fmac_f32_e32 v51, v60, v60
	v_add_f32_e32 v50, v51, v50
	v_mul_f32_e32 v51, v59, v59
	v_fmac_f32_e32 v51, v58, v58
	v_add_f32_e32 v50, v51, v50
	v_add_f32_e32 v56, v62, v50
	v_lshlrev_b64 v[50:51], 11, v[152:153]
	v_pk_fma_f32 v[52:53], v[44:45], 0.5, v[92:93] op_sel_hi:[1,0,1]
	v_pk_fma_f32 v[54:55], v[42:43], 0.5, v[90:91] op_sel_hi:[1,0,1]
	v_lshl_add_u64 v[50:51], s[96:97], 0, v[50:51]
	v_cvt_pk_bf16_f32 v42, v46, v47
	v_cvt_pk_bf16_f32 v43, v48, v49
	v_cvt_pk_bf16_f32 v44, v54, v55
	v_cvt_pk_bf16_f32 v45, v52, v53
	v_lshl_add_u64 v[50:51], v[50:51], 0, v[142:143]
	global_store_dwordx4 v[50:51], v[42:45], off
	s_waitcnt vmcnt(11)
	v_pk_fma_f32 v[40:41], v[40:41], 0.5, v[104:105] op_sel_hi:[1,0,1]
	v_pk_fma_f32 v[38:39], v[38:39], 0.5, v[102:103] op_sel_hi:[1,0,1]
	v_mul_f32_e32 v42, v47, v47
	v_mul_f32_e32 v43, v49, v49
	v_fmac_f32_e32 v42, v46, v46
	v_fmac_f32_e32 v43, v48, v48
	v_add_f32_e32 v42, v42, v43
	v_mul_f32_e32 v43, v55, v55
	v_fmac_f32_e32 v43, v54, v54
	v_add_f32_e32 v42, v43, v42
	v_mul_f32_e32 v43, v53, v53
	v_fmac_f32_e32 v43, v52, v52
	v_add_f32_e32 v46, v43, v42
	v_pk_fma_f32 v[42:43], v[36:37], 0.5, v[100:101] op_sel_hi:[1,0,1]
	v_pk_fma_f32 v[44:45], v[34:35], 0.5, v[98:99] op_sel_hi:[1,0,1]
	v_cvt_pk_bf16_f32 v34, v38, v39
	v_cvt_pk_bf16_f32 v35, v40, v41
	v_cvt_pk_bf16_f32 v36, v44, v45
	v_cvt_pk_bf16_f32 v37, v42, v43
	global_store_dwordx4 v[50:51], v[34:37], off offset:256
	s_waitcnt vmcnt(10)
	v_pk_fma_f32 v[32:33], v[32:33], 0.5, v[114:115] op_sel_hi:[1,0,1]
	v_pk_fma_f32 v[30:31], v[30:31], 0.5, v[112:113] op_sel_hi:[1,0,1]
	v_mul_f32_e32 v34, v39, v39
	v_mul_f32_e32 v35, v41, v41
	v_fmac_f32_e32 v34, v38, v38
	v_fmac_f32_e32 v35, v40, v40
	v_add_f32_e32 v34, v34, v35
	v_mul_f32_e32 v35, v45, v45
	v_fmac_f32_e32 v35, v44, v44
	v_add_f32_e32 v34, v35, v34
	v_mul_f32_e32 v35, v43, v43
	v_fmac_f32_e32 v35, v42, v42
	v_add_f32_e32 v34, v35, v34
	v_add_f32_e32 v40, v46, v34
	v_lshlrev_b64 v[34:35], 11, v[154:155]
	v_pk_fma_f32 v[36:37], v[28:29], 0.5, v[110:111] op_sel_hi:[1,0,1]
	v_pk_fma_f32 v[38:39], v[26:27], 0.5, v[108:109] op_sel_hi:[1,0,1]
	v_lshl_add_u64 v[34:35], s[96:97], 0, v[34:35]
	v_cvt_pk_bf16_f32 v26, v30, v31
	v_cvt_pk_bf16_f32 v27, v32, v33
	v_cvt_pk_bf16_f32 v28, v38, v39
	v_cvt_pk_bf16_f32 v29, v36, v37
	v_lshl_add_u64 v[34:35], v[34:35], 0, v[142:143]
	global_store_dwordx4 v[34:35], v[26:29], off
	s_waitcnt vmcnt(9)
	v_pk_fma_f32 v[24:25], v[24:25], 0.5, v[122:123] op_sel_hi:[1,0,1]
	v_pk_fma_f32 v[22:23], v[22:23], 0.5, v[120:121] op_sel_hi:[1,0,1]
	v_mul_f32_e32 v26, v31, v31
	v_mul_f32_e32 v27, v33, v33
	v_fmac_f32_e32 v26, v30, v30
	v_fmac_f32_e32 v27, v32, v32
	v_add_f32_e32 v26, v26, v27
	v_mul_f32_e32 v27, v39, v39
	v_fmac_f32_e32 v27, v38, v38
	v_add_f32_e32 v26, v27, v26
	v_mul_f32_e32 v27, v37, v37
	v_fmac_f32_e32 v27, v36, v36
	v_add_f32_e32 v30, v27, v26
	v_pk_fma_f32 v[26:27], v[20:21], 0.5, v[118:119] op_sel_hi:[1,0,1]
	v_pk_fma_f32 v[28:29], v[18:19], 0.5, v[116:117] op_sel_hi:[1,0,1]
	v_cvt_pk_bf16_f32 v18, v22, v23
	v_cvt_pk_bf16_f32 v19, v24, v25
	v_cvt_pk_bf16_f32 v20, v28, v29
	v_cvt_pk_bf16_f32 v21, v26, v27
	global_store_dwordx4 v[34:35], v[18:21], off offset:256
	s_waitcnt vmcnt(8)
	v_pk_fma_f32 v[16:17], v[16:17], 0.5, v[146:147] op_sel_hi:[1,0,1]
	v_pk_fma_f32 v[14:15], v[14:15], 0.5, v[144:145] op_sel_hi:[1,0,1]
	v_mul_f32_e32 v18, v23, v23
	v_mul_f32_e32 v19, v25, v25
	v_fmac_f32_e32 v18, v22, v22
	v_fmac_f32_e32 v19, v24, v24
	v_add_f32_e32 v18, v18, v19
	v_mul_f32_e32 v19, v29, v29
	v_fmac_f32_e32 v19, v28, v28
	v_add_f32_e32 v18, v19, v18
	v_mul_f32_e32 v19, v27, v27
	v_fmac_f32_e32 v19, v26, v26
	v_add_f32_e32 v18, v19, v18
	v_add_f32_e32 v28, v30, v18
	v_lshlrev_b64 v[18:19], 11, v[156:157]
	v_pk_fma_f32 v[20:21], v[12:13], 0.5, v[126:127] op_sel_hi:[1,0,1]
	v_pk_fma_f32 v[22:23], v[10:11], 0.5, v[124:125] op_sel_hi:[1,0,1]
	v_lshl_add_u64 v[18:19], s[96:97], 0, v[18:19]
	v_cvt_pk_bf16_f32 v10, v14, v15
	v_cvt_pk_bf16_f32 v11, v16, v17
	v_cvt_pk_bf16_f32 v12, v22, v23
	v_cvt_pk_bf16_f32 v13, v20, v21
	v_lshl_add_u64 v[24:25], v[18:19], 0, v[142:143]
	global_store_dwordx4 v[24:25], v[10:13], off
	s_waitcnt vmcnt(7)
;     __device__ __forceinline__ void operator()(const f32x4 (&acc)[2][2][4][2], const pg8::Unit& u, int wr, int wc, int fr, int fq) const {
;     ...
;         if (MODE != 2) {
; #pragma unroll
;             for (int ai = 0; ai < 2; ++ai)
; #pragma unroll
;                 for (int m = 0; m < 4; ++m) sq[ai][m] += __shfl_xor(sq[ai][m], 16);
; #pragma unroll
;             for (int ai = 0; ai < 2; ++ai)
; #pragma unroll
;                 for (int m = 0; m < 4; ++m) sq[ai][m] += __shfl_xor(sq[ai][m], 32);
;             if (fq == 0) {
; #pragma unroll
;                 for (int ai = 0; ai < 2; ++ai)
; #pragma unroll
;                     for (int m = 0; m < 4; ++m) atomicAdd(ssn + row0 + ai * 128 + m * 16, (u64)(sq[ai][m] * SS_SCALE + 0.5f)); }
	v_pk_fma_f32 v[6:7], v[6:7], 0.5, v[70:71] op_sel_hi:[1,0,1]
	v_pk_fma_f32 v[26:27], v[2:3], 0.5, v[66:67] op_sel_hi:[1,0,1]
	v_mul_f32_e32 v10, v15, v15
	v_mul_f32_e32 v11, v17, v17
	v_fmac_f32_e32 v10, v14, v14
	v_fmac_f32_e32 v11, v16, v16
	v_add_f32_e32 v10, v10, v11
	v_mul_f32_e32 v11, v23, v23
	v_fmac_f32_e32 v11, v22, v22
	v_add_f32_e32 v10, v11, v10
	v_mul_f32_e32 v11, v21, v21
	v_pk_fma_f32 v[22:23], v[4:5], 0.5, v[68:69] op_sel_hi:[1,0,1]
	v_and_b32_e32 v5, 64, v236
	v_fmac_f32_e32 v11, v20, v20
	v_pk_fma_f32 v[20:21], v[8:9], 0.5, v[72:73] op_sel_hi:[1,0,1]
	v_xor_b32_e32 v4, 16, v236
	v_add_u32_e32 v9, 64, v5
	v_cmp_lt_i32_e32 vcc, v4, v9
	v_mul_f32_e32 v2, v7, v7
	v_mul_f32_e32 v3, v21, v21
	v_cndmask_b32_e32 v4, v236, v4, vcc
	v_fmac_f32_e32 v2, v6, v6
	v_fmac_f32_e32 v3, v20, v20
	v_lshlrev_b32_e32 v5, 2, v4
	v_cvt_pk_bf16_f32 v18, v6, v7
	v_add_f32_e32 v2, v2, v3
	v_mul_f32_e32 v3, v27, v27
	ds_bpermute_b32 v4, v5, v106
	ds_bpermute_b32 v6, v5, v107
	ds_bpermute_b32 v7, v5, v158
	v_fmac_f32_e32 v3, v26, v26
	v_add_f32_e32 v2, v3, v2
	v_mul_f32_e32 v3, v23, v23
	v_fmac_f32_e32 v3, v22, v22
	v_add_f32_e32 v10, v11, v10
	v_add_f32_e32 v2, v3, v2
	v_add_f32_e32 v10, v10, v2
	s_waitcnt lgkmcnt(2)
	v_add_f32_e32 v2, v106, v4
	s_waitcnt lgkmcnt(1)
	v_add_f32_e32 v3, v107, v6
	s_waitcnt lgkmcnt(0)
	v_add_f32_e32 v4, v158, v7
	ds_bpermute_b32 v6, v5, v159
	ds_bpermute_b32 v7, v5, v56
	ds_bpermute_b32 v8, v5, v40
	ds_bpermute_b32 v11, v5, v28
	ds_bpermute_b32 v12, v5, v10
	s_waitcnt lgkmcnt(4)
	v_add_f32_e32 v5, v159, v6
	s_waitcnt lgkmcnt(3)
	v_add_f32_e32 v6, v56, v7
	s_waitcnt lgkmcnt(2)
	v_add_f32_e32 v7, v40, v8
	s_waitcnt lgkmcnt(1)
	v_add_f32_e32 v8, v28, v11
	v_xor_b32_e32 v11, 32, v236
	v_cmp_lt_i32_e32 vcc, v11, v9
	s_waitcnt lgkmcnt(0)
	v_add_f32_e32 v10, v10, v12
	v_cvt_pk_bf16_f32 v19, v20, v21
	v_cndmask_b32_e32 v9, v236, v11, vcc
	v_lshlrev_b32_e32 v17, 2, v9
	ds_bpermute_b32 v9, v17, v2
	ds_bpermute_b32 v11, v17, v3
	ds_bpermute_b32 v12, v17, v4
	ds_bpermute_b32 v13, v17, v5
	ds_bpermute_b32 v14, v17, v6
	ds_bpermute_b32 v15, v17, v7
	ds_bpermute_b32 v16, v17, v8
	ds_bpermute_b32 v17, v17, v10
	v_cvt_pk_bf16_f32 v20, v26, v27
	v_cvt_pk_bf16_f32 v21, v22, v23
	global_store_dwordx4 v[24:25], v[18:21], off offset:256
	s_and_saveexec_b64 s[18:19], s[0:1]
	s_cbranch_execz .LBB0_527
	s_waitcnt lgkmcnt(5)
	v_add_f32_e32 v12, v4, v12
	v_add_f32_e32 v4, v2, v9
	v_fma_f32 v4, v4, s21, 0.5
	v_trunc_f32_e32 v4, v4
	s_waitcnt lgkmcnt(4)
	v_add_f32_e32 v13, v5, v13
	v_mul_f32_e32 v5, 0x2f800000, v4
	v_floor_f32_e32 v5, v5
	v_fmac_f32_e32 v4, 0xcf800000, v5
	v_cvt_u32_f32_e32 v4, v4
	v_cvt_u32_f32_e32 v5, v5
	v_add_f32_e32 v11, v3, v11
	v_lshl_add_u64 v[2:3], v[140:141], 3, s[38:39]
	s_waitcnt lgkmcnt(3)
	v_add_f32_e32 v6, v6, v14
	global_atomic_add_x2 v[2:3], v[4:5], off
	v_fma_f32 v4, v11, s21, 0.5
	v_trunc_f32_e32 v4, v4
	v_mul_f32_e32 v5, 0x2f800000, v4
	v_floor_f32_e32 v5, v5
	v_fmac_f32_e32 v4, 0xcf800000, v5
	v_cvt_u32_f32_e32 v4, v4
	v_cvt_u32_f32_e32 v5, v5
	s_waitcnt lgkmcnt(2)
	v_add_f32_e32 v7, v7, v15
	s_waitcnt lgkmcnt(1)
	v_add_f32_e32 v8, v8, v16
	s_waitcnt lgkmcnt(0)
	v_add_f32_e32 v10, v10, v17
	global_atomic_add_x2 v[2:3], v[4:5], off offset:128
	v_fma_f32 v4, v12, s21, 0.5
	v_trunc_f32_e32 v4, v4
	v_mul_f32_e32 v5, 0x2f800000, v4
	v_floor_f32_e32 v5, v5
	v_fmac_f32_e32 v4, 0xcf800000, v5
	v_cvt_u32_f32_e32 v4, v4
	v_cvt_u32_f32_e32 v5, v5
	global_atomic_add_x2 v[2:3], v[4:5], off offset:256
	v_fma_f32 v4, v13, s21, 0.5
	v_trunc_f32_e32 v4, v4
	v_mul_f32_e32 v5, 0x2f800000, v4
	v_floor_f32_e32 v5, v5
	v_fmac_f32_e32 v4, 0xcf800000, v5
	v_cvt_u32_f32_e32 v4, v4
	v_cvt_u32_f32_e32 v5, v5
	global_atomic_add_x2 v[2:3], v[4:5], off offset:384
	v_fma_f32 v4, v6, s21, 0.5
	v_trunc_f32_e32 v4, v4
	v_mul_f32_e32 v5, 0x2f800000, v4
	v_floor_f32_e32 v5, v5
	v_fmac_f32_e32 v4, 0xcf800000, v5
	v_cvt_u32_f32_e32 v4, v4
	v_cvt_u32_f32_e32 v5, v5
	global_atomic_add_x2 v[2:3], v[4:5], off offset:1024
	v_fma_f32 v4, v7, s21, 0.5
	v_trunc_f32_e32 v4, v4
	v_mul_f32_e32 v5, 0x2f800000, v4
	v_floor_f32_e32 v5, v5
	v_fmac_f32_e32 v4, 0xcf800000, v5
	v_cvt_u32_f32_e32 v4, v4
	v_cvt_u32_f32_e32 v5, v5
	global_atomic_add_x2 v[2:3], v[4:5], off offset:1152
	v_fma_f32 v4, v8, s21, 0.5
	v_trunc_f32_e32 v4, v4
	v_mul_f32_e32 v5, 0x2f800000, v4
	v_floor_f32_e32 v5, v5
	v_fmac_f32_e32 v4, 0xcf800000, v5
	v_cvt_u32_f32_e32 v4, v4
	v_cvt_u32_f32_e32 v5, v5
	global_atomic_add_x2 v[2:3], v[4:5], off offset:1280
	v_fma_f32 v4, v10, s21, 0.5
	v_trunc_f32_e32 v4, v4
	v_mul_f32_e32 v5, 0x2f800000, v4
	v_floor_f32_e32 v5, v5
	v_fmac_f32_e32 v4, 0xcf800000, v5
	v_cvt_u32_f32_e32 v4, v4
	v_cvt_u32_f32_e32 v5, v5
	global_atomic_add_x2 v[2:3], v[4:5], off offset:1408

; #define PG8_STAGE(bufoff, gbase, voff) do { _Pragma("unroll") for (int _i = 0; _i < 2; ++_i) \
;         __builtin_amdgcn_global_load_lds((const unsigned*)((const char*)(gbase) + (voff)[_i]), (PG8_LAS unsigned*)(lds + (bufoff) + ldsw + _i * 8192), 16, 0, 0); } while (0)
; #define PG8_LDA(dst, b, h) do { _Pragma("unroll") for (int m = 0; m < 4; ++m) _Pragma("unroll") for (int k = 0; k < 2; ++k) dst[m][k] = *(const PG8_LAS bf16x8*)(lds + PG8_SA(b, h) + aoff + m * 2048 + k * 1024); } while (0)
; #define PG8_LDB(dst, b, h) do { _Pragma("unroll") for (int n = 0; n < 2; ++n) _Pragma("unroll") for (int k = 0; k < 2; ++k) dst[n][k] = *(const PG8_LAS bf16x8*)(lds + PG8_SB(b, h) + boff + n * 2048 + k * 1024); } while (0)
; #define PG8_MMA(ai, bj, At, Bt) do { __builtin_amdgcn_s_setprio(1); _Pragma("unroll") for (int m = 0; m < 4; ++m) _Pragma("unroll") for (int n = 0; n < 2; ++n) _Pragma("unroll") for (int k = 0; k < 2; ++k) \
;         acc[ai][bj][m][n] = __builtin_amdgcn_mfma_f32_16x16x32_bf16(Bt[n][k], At[m][k], acc[ai][bj][m][n], 0, 0, 0); __builtin_amdgcn_s_setprio(0); } while (0)
; #define PG8_WAIT_V(n) asm volatile("s_waitcnt vmcnt(" #n ")" ::: "memory")
; #define PG8_WAIT_L(n) asm volatile("s_waitcnt lgkmcnt(" #n ")" ::: "memory")
; template <class Epi, class Sched, bool ALIGN_EPI = false, bool SP2 = false>
; __device__ __forceinline__ void gemm_phase(PG8_LAS unsigned char* lds, const Gemm g, const Sched& S, const Epi& E) {
;     ...
;             const bool last = (t == nt - 2);
;             const char* a1 = cA + (size_t)(t + 1) * kstep;
;             const char* a2 = last ? nA : cA + (size_t)(t + 2) * kstep; const char* b2 = last ? nB : cB + (size_t)(t + 2) * kstep;
;             const char* a3 = a2 + kstep; const char* b3 = b2 + kstep;
;             if (last && has_next) S.a_ready(nxt);
;             if constexpr (SP2) {
;             PG8_LDB(B0, 0, 0); PG8_LDB(B1, 0, 1); PG8_SCHED; PG8_LDA(At, 0, 0); PG8_STAGE(PG8_SA(1, 1), a1 + hstep, voffA);
;             PG8_WAIT_V(8); PG8_WAIT_L(0); PG8_BAR; PG8_MMA(0, 0, At, B0); PG8_MMA(0, 1, At, B1); PG8_BAR; PG8_SCHED;
;             PG8_LDA(At, 0, 1); PG8_STAGE(PG8_SB(0, 0), b2, voffB); PG8_STAGE(PG8_SB(0, 1), b2 + hstep, voffB); PG8_STAGE(PG8_SA(0, 0), a2, voffA);
;             PG8_WAIT_V(8); PG8_WAIT_L(0); PG8_BAR; PG8_MMA(1, 0, At, B0); PG8_MMA(1, 1, At, B1); PG8_BAR; PG8_SCHED;
.LBB0_557:
	s_add_u32 s53, s18, 0xfffc0080
	s_addc_u32 s56, s19, -1
	s_add_i32 s60, 0, 0x10000
	s_cmp_eq_u32 s52, 12
	s_cselect_b32 s59, s30, s56
	s_cselect_b32 s58, s31, s53
	s_cselect_b32 s57, s34, s43
	s_cselect_b32 s56, s35, s41
	s_add_i32 s53, 0, 0x14000
	v_add_u32_e32 v152, s60, v161
	v_add_u32_e32 v172, s53, v161
	ds_read_b128 v[140:143], v152
	ds_read_b128 v[144:147], v152 offset:1024
	ds_read_b128 v[148:151], v152 offset:2048
	ds_read_b128 v[152:155], v152 offset:3072
	ds_read_b128 v[156:159], v172
	ds_read_b128 v[164:167], v172 offset:1024
	ds_read_b128 v[168:171], v172 offset:2048
	ds_read_b128 v[172:175], v172 offset:3072
	v_lshl_add_u64 v[188:189], s[18:19], 0, v[136:137]
	s_add_i32 m0, s26, 0xc000
	ds_read_b128 v[176:179], v163
	ds_read_b128 v[180:183], v163 offset:1024
	ds_read_b128 v[184:187], v163 offset:2048
	ds_read_b128 v[194:197], v163 offset:3072
	ds_read_b128 v[198:201], v163 offset:4096
	ds_read_b128 v[202:205], v163 offset:5120
	ds_read_b128 v[206:209], v163 offset:6144
	ds_read_b128 v[210:213], v163 offset:7168
	global_load_lds_dwordx4 v[188:189], off
	v_lshl_add_u64 v[188:189], s[18:19], 0, v[138:139]
	s_add_i32 m0, s26, 0xe000
	s_nop 0
	global_load_lds_dwordx4 v[188:189], off
	s_waitcnt vmcnt(8)
	s_waitcnt lgkmcnt(0)
	s_barrier
	s_setprio 1
	s_waitcnt lgkmcnt(0)
	v_mfma_f32_16x16x32_bf16 v[126:129], v[140:143], v[176:179], v[126:129]
	v_mfma_f32_16x16x32_bf16 v[122:125], v[148:151], v[176:179], v[122:125]
	v_mfma_f32_16x16x32_bf16 v[118:121], v[140:143], v[184:187], v[118:121]
	v_mfma_f32_16x16x32_bf16 v[106:109], v[148:151], v[184:187], v[106:109]
	v_mfma_f32_16x16x32_bf16 v[94:97], v[140:143], v[198:201], v[94:97]
	v_mfma_f32_16x16x32_bf16 v[90:93], v[148:151], v[198:201], v[90:93]
	v_mfma_f32_16x16x32_bf16 v[78:81], v[140:143], v[206:209], v[78:81]
	v_mfma_f32_16x16x32_bf16 v[74:77], v[148:151], v[206:209], v[74:77]
	v_mfma_f32_16x16x32_bf16 v[126:129], v[144:147], v[180:183], v[126:129]
	v_mfma_f32_16x16x32_bf16 v[122:125], v[152:155], v[180:183], v[122:125]
	v_mfma_f32_16x16x32_bf16 v[118:121], v[144:147], v[194:197], v[118:121]
	v_mfma_f32_16x16x32_bf16 v[106:109], v[152:155], v[194:197], v[106:109]
	v_mfma_f32_16x16x32_bf16 v[94:97], v[144:147], v[202:205], v[94:97]
	v_mfma_f32_16x16x32_bf16 v[90:93], v[152:155], v[202:205], v[90:93]
	v_mfma_f32_16x16x32_bf16 v[78:81], v[144:147], v[210:213], v[78:81]
	v_mfma_f32_16x16x32_bf16 v[74:77], v[152:155], v[210:213], v[74:77]
	s_setprio 0
	s_setprio 1
	v_mfma_f32_16x16x32_bf16 v[114:117], v[156:159], v[176:179], v[114:117]
	v_mfma_f32_16x16x32_bf16 v[110:113], v[168:171], v[176:179], v[110:113]
	v_mfma_f32_16x16x32_bf16 v[102:105], v[156:159], v[184:187], v[102:105]
	v_mfma_f32_16x16x32_bf16 v[98:101], v[168:171], v[184:187], v[98:101]
	v_mfma_f32_16x16x32_bf16 v[86:89], v[156:159], v[198:201], v[86:89]
	v_mfma_f32_16x16x32_bf16 v[82:85], v[168:171], v[198:201], v[82:85]
	v_mfma_f32_16x16x32_bf16 v[70:73], v[156:159], v[206:209], v[70:73]
	v_mfma_f32_16x16x32_bf16 v[66:69], v[168:171], v[206:209], v[66:69]
	v_mfma_f32_16x16x32_bf16 v[114:117], v[164:167], v[180:183], v[114:117]
	v_mfma_f32_16x16x32_bf16 v[110:113], v[172:175], v[180:183], v[110:113]
	v_mfma_f32_16x16x32_bf16 v[102:105], v[164:167], v[194:197], v[102:105]
	v_mfma_f32_16x16x32_bf16 v[98:101], v[172:175], v[194:197], v[98:101]
	v_mfma_f32_16x16x32_bf16 v[86:89], v[164:167], v[202:205], v[86:89]
	v_mfma_f32_16x16x32_bf16 v[82:85], v[172:175], v[202:205], v[82:85]
	v_mfma_f32_16x16x32_bf16 v[70:73], v[164:167], v[210:213], v[70:73]
	v_mfma_f32_16x16x32_bf16 v[66:69], v[172:175], v[210:213], v[66:69]
	s_setprio 0
	s_barrier
	s_add_i32 s60, s60, s23
	v_lshl_add_u64 v[188:189], s[56:57], 0, v[0:1]
	s_mov_b32 m0, s60
	ds_read_b128 v[176:179], v163 offset:16384
	ds_read_b128 v[180:183], v163 offset:17408
	ds_read_b128 v[184:187], v163 offset:18432
	ds_read_b128 v[194:197], v163 offset:19456
	ds_read_b128 v[198:201], v163 offset:20480
	ds_read_b128 v[202:205], v163 offset:21504
	ds_read_b128 v[206:209], v163 offset:22528
	ds_read_b128 v[210:213], v163 offset:23552
	global_load_lds_dwordx4 v[188:189], off
	s_add_i32 m0, s60, 0x2000
	s_add_u32 s60, s56, 0x40000
	v_lshl_add_u64 v[214:215], s[56:57], 0, v[134:135]
	s_addc_u32 s61, s57, 0
	s_add_i32 s53, s53, s23
	global_load_lds_dwordx4 v[214:215], off
	v_lshl_add_u64 v[216:217], s[60:61], 0, v[0:1]
	s_mov_b32 m0, s53
	v_lshl_add_u64 v[218:219], s[58:59], 0, v[132:133]
	global_load_lds_dwordx4 v[216:217], off
	v_lshl_add_u64 v[216:217], s[60:61], 0, v[134:135]
	s_add_i32 m0, s53, 0x2000
	s_nop 0
	global_load_lds_dwordx4 v[216:217], off
	v_lshl_add_u64 v[216:217], s[58:59], 0, v[130:131]
	s_mov_b32 m0, s26
	s_nop 0
	global_load_lds_dwordx4 v[216:217], off
	s_mov_b32 m0, s27
	s_nop 0
	global_load_lds_dwordx4 v[218:219], off
	s_waitcnt vmcnt(8)
	s_waitcnt lgkmcnt(0)
	s_barrier
; #define PG8_STAGE(bufoff, gbase, voff) do { _Pragma("unroll") for (int _i = 0; _i < 2; ++_i) \
;         __builtin_amdgcn_global_load_lds((const unsigned*)((const char*)(gbase) + (voff)[_i]), (PG8_LAS unsigned*)(lds + (bufoff) + ldsw + _i * 8192), 16, 0, 0); } while (0)
; #define PG8_LDA(dst, b, h) do { _Pragma("unroll") for (int m = 0; m < 4; ++m) _Pragma("unroll") for (int k = 0; k < 2; ++k) dst[m][k] = *(const PG8_LAS bf16x8*)(lds + PG8_SA(b, h) + aoff + m * 2048 + k * 1024); } while (0)
; #define PG8_LDB(dst, b, h) do { _Pragma("unroll") for (int n = 0; n < 2; ++n) _Pragma("unroll") for (int k = 0; k < 2; ++k) dst[n][k] = *(const PG8_LAS bf16x8*)(lds + PG8_SB(b, h) + boff + n * 2048 + k * 1024); } while (0)
; #define PG8_MMA(ai, bj, At, Bt) do { __builtin_amdgcn_s_setprio(1); _Pragma("unroll") for (int m = 0; m < 4; ++m) _Pragma("unroll") for (int n = 0; n < 2; ++n) _Pragma("unroll") for (int k = 0; k < 2; ++k) \
;         acc[ai][bj][m][n] = __builtin_amdgcn_mfma_f32_16x16x32_bf16(Bt[n][k], At[m][k], acc[ai][bj][m][n], 0, 0, 0); __builtin_amdgcn_s_setprio(0); } while (0)
; #define PG8_WAIT_V(n) asm volatile("s_waitcnt vmcnt(" #n ")" ::: "memory")
; #define PG8_WAIT_L(n) asm volatile("s_waitcnt lgkmcnt(" #n ")" ::: "memory")
; #define PG8_BAR __builtin_amdgcn_s_barrier()
; #define PG8_SCHED __builtin_amdgcn_sched_barrier(0)
; template <class Epi, class Sched, bool ALIGN_EPI = false, bool SP2 = false>
; __device__ __forceinline__ void gemm_phase(PG8_LAS unsigned char* lds, const Gemm g, const Sched& S, const Epi& E) {
;     ...
;             PG8_WAIT_V(8); PG8_WAIT_L(0); PG8_BAR; PG8_MMA(1, 0, At, B0); PG8_MMA(1, 1, At, B1); PG8_BAR; PG8_SCHED;
;             PG8_LDB(B0, 1, 0); PG8_LDB(B1, 1, 1); PG8_SCHED; PG8_LDA(At, 1, 0); PG8_STAGE(PG8_SA(0, 1), a2 + hstep, voffA);
;             PG8_WAIT_V(8); PG8_WAIT_L(0); PG8_BAR; PG8_MMA(0, 0, At, B0); PG8_MMA(0, 1, At, B1); PG8_BAR; PG8_SCHED;
	s_setprio 1
	s_waitcnt lgkmcnt(0)
	v_mfma_f32_16x16x32_bf16 v[62:65], v[140:143], v[176:179], v[62:65]
	v_mfma_f32_16x16x32_bf16 v[58:61], v[148:151], v[176:179], v[58:61]
	v_mfma_f32_16x16x32_bf16 v[46:49], v[140:143], v[184:187], v[46:49]
	v_mfma_f32_16x16x32_bf16 v[42:45], v[148:151], v[184:187], v[42:45]
	v_mfma_f32_16x16x32_bf16 v[30:33], v[140:143], v[198:201], v[30:33]
	v_mfma_f32_16x16x32_bf16 v[26:29], v[148:151], v[198:201], v[26:29]
	v_mfma_f32_16x16x32_bf16 v[14:17], v[140:143], v[206:209], v[14:17]
	v_mfma_f32_16x16x32_bf16 v[10:13], v[148:151], v[206:209], v[10:13]
	v_mfma_f32_16x16x32_bf16 v[62:65], v[144:147], v[180:183], v[62:65]
	v_mfma_f32_16x16x32_bf16 v[58:61], v[152:155], v[180:183], v[58:61]
	v_mfma_f32_16x16x32_bf16 v[46:49], v[144:147], v[194:197], v[46:49]
	v_mfma_f32_16x16x32_bf16 v[42:45], v[152:155], v[194:197], v[42:45]
	v_mfma_f32_16x16x32_bf16 v[30:33], v[144:147], v[202:205], v[30:33]
	v_mfma_f32_16x16x32_bf16 v[26:29], v[152:155], v[202:205], v[26:29]
	v_mfma_f32_16x16x32_bf16 v[14:17], v[144:147], v[210:213], v[14:17]
	v_mfma_f32_16x16x32_bf16 v[10:13], v[152:155], v[210:213], v[10:13]
	s_setprio 0
	s_setprio 1
	v_mfma_f32_16x16x32_bf16 v[54:57], v[156:159], v[176:179], v[54:57]
	v_mfma_f32_16x16x32_bf16 v[50:53], v[168:171], v[176:179], v[50:53]
	v_mfma_f32_16x16x32_bf16 v[38:41], v[156:159], v[184:187], v[38:41]
	v_mfma_f32_16x16x32_bf16 v[34:37], v[168:171], v[184:187], v[34:37]
	v_mfma_f32_16x16x32_bf16 v[22:25], v[156:159], v[198:201], v[22:25]
	v_mfma_f32_16x16x32_bf16 v[18:21], v[168:171], v[198:201], v[18:21]
	v_mfma_f32_16x16x32_bf16 v[6:9], v[156:159], v[206:209], v[6:9]
	v_mfma_f32_16x16x32_bf16 v[2:5], v[168:171], v[206:209], v[2:5]
	v_mfma_f32_16x16x32_bf16 v[54:57], v[164:167], v[180:183], v[54:57]
	v_mfma_f32_16x16x32_bf16 v[50:53], v[172:175], v[180:183], v[50:53]
	v_mfma_f32_16x16x32_bf16 v[38:41], v[164:167], v[194:197], v[38:41]
	v_mfma_f32_16x16x32_bf16 v[34:37], v[172:175], v[194:197], v[34:37]
	v_mfma_f32_16x16x32_bf16 v[22:25], v[164:167], v[202:205], v[22:25]
	v_mfma_f32_16x16x32_bf16 v[18:21], v[172:175], v[202:205], v[18:21]
	v_mfma_f32_16x16x32_bf16 v[6:9], v[164:167], v[210:213], v[6:9]
	v_mfma_f32_16x16x32_bf16 v[2:5], v[172:175], v[210:213], v[2:5]
	s_setprio 0
	s_barrier
	s_add_i32 s53, 0, 0x18000
	s_add_i32 s60, 0, 0x1c000
	v_add_u32_e32 v152, s53, v161
	v_add_u32_e32 v172, s60, v161
	ds_read_b128 v[140:143], v152
	ds_read_b128 v[144:147], v152 offset:1024
	ds_read_b128 v[148:151], v152 offset:2048
	ds_read_b128 v[152:155], v152 offset:3072
	ds_read_b128 v[156:159], v172
	ds_read_b128 v[164:167], v172 offset:1024
	ds_read_b128 v[168:171], v172 offset:2048
	ds_read_b128 v[172:175], v172 offset:3072
	s_add_u32 s58, s58, 0x40000
	s_addc_u32 s59, s59, 0
	s_mov_b32 m0, s28
	v_lshl_add_u64 v[220:221], s[58:59], 0, v[130:131]
	ds_read_b128 v[176:179], v163 offset:32768
	ds_read_b128 v[180:183], v163 offset:33792
	ds_read_b128 v[184:187], v163 offset:34816
	ds_read_b128 v[194:197], v163 offset:35840
	ds_read_b128 v[198:201], v163 offset:36864
	ds_read_b128 v[202:205], v163 offset:37888
	ds_read_b128 v[206:209], v163 offset:38912
	ds_read_b128 v[210:213], v163 offset:39936
	global_load_lds_dwordx4 v[220:221], off
	v_lshl_add_u64 v[220:221], s[58:59], 0, v[132:133]
	s_mov_b32 m0, s29
	s_nop 0
	global_load_lds_dwordx4 v[220:221], off
	s_waitcnt vmcnt(8)
	s_waitcnt lgkmcnt(0)
	s_barrier
	s_setprio 1
	s_waitcnt lgkmcnt(0)
	v_mfma_f32_16x16x32_bf16 v[126:129], v[140:143], v[176:179], v[126:129]
	v_mfma_f32_16x16x32_bf16 v[122:125], v[148:151], v[176:179], v[122:125]
	v_mfma_f32_16x16x32_bf16 v[118:121], v[140:143], v[184:187], v[118:121]
	v_mfma_f32_16x16x32_bf16 v[106:109], v[148:151], v[184:187], v[106:109]
	v_mfma_f32_16x16x32_bf16 v[94:97], v[140:143], v[198:201], v[94:97]
	v_mfma_f32_16x16x32_bf16 v[90:93], v[148:151], v[198:201], v[90:93]
	v_mfma_f32_16x16x32_bf16 v[78:81], v[140:143], v[206:209], v[78:81]
	v_mfma_f32_16x16x32_bf16 v[74:77], v[148:151], v[206:209], v[74:77]
	v_mfma_f32_16x16x32_bf16 v[126:129], v[144:147], v[180:183], v[126:129]
	v_mfma_f32_16x16x32_bf16 v[122:125], v[152:155], v[180:183], v[122:125]
	v_mfma_f32_16x16x32_bf16 v[118:121], v[144:147], v[194:197], v[118:121]
	v_mfma_f32_16x16x32_bf16 v[106:109], v[152:155], v[194:197], v[106:109]
	v_mfma_f32_16x16x32_bf16 v[94:97], v[144:147], v[202:205], v[94:97]
	v_mfma_f32_16x16x32_bf16 v[90:93], v[152:155], v[202:205], v[90:93]
	v_mfma_f32_16x16x32_bf16 v[78:81], v[144:147], v[210:213], v[78:81]
	v_mfma_f32_16x16x32_bf16 v[74:77], v[152:155], v[210:213], v[74:77]
	s_setprio 0
	s_setprio 1
	v_mfma_f32_16x16x32_bf16 v[114:117], v[156:159], v[176:179], v[114:117]
	v_mfma_f32_16x16x32_bf16 v[110:113], v[168:171], v[176:179], v[110:113]
	v_mfma_f32_16x16x32_bf16 v[102:105], v[156:159], v[184:187], v[102:105]
	v_mfma_f32_16x16x32_bf16 v[98:101], v[168:171], v[184:187], v[98:101]
	v_mfma_f32_16x16x32_bf16 v[86:89], v[156:159], v[198:201], v[86:89]
	v_mfma_f32_16x16x32_bf16 v[82:85], v[168:171], v[198:201], v[82:85]
	v_mfma_f32_16x16x32_bf16 v[70:73], v[156:159], v[206:209], v[70:73]
	v_mfma_f32_16x16x32_bf16 v[66:69], v[168:171], v[206:209], v[66:69]
	v_mfma_f32_16x16x32_bf16 v[114:117], v[164:167], v[180:183], v[114:117]
	v_mfma_f32_16x16x32_bf16 v[110:113], v[172:175], v[180:183], v[110:113]
	v_mfma_f32_16x16x32_bf16 v[102:105], v[164:167], v[194:197], v[102:105]
	v_mfma_f32_16x16x32_bf16 v[98:101], v[172:175], v[194:197], v[98:101]
	v_mfma_f32_16x16x32_bf16 v[86:89], v[164:167], v[202:205], v[86:89]
	v_mfma_f32_16x16x32_bf16 v[82:85], v[172:175], v[202:205], v[82:85]
	v_mfma_f32_16x16x32_bf16 v[70:73], v[164:167], v[210:213], v[70:73]
	v_mfma_f32_16x16x32_bf16 v[66:69], v[172:175], v[210:213], v[66:69]
	s_setprio 0
	s_barrier
; #define PG8_STAGE(bufoff, gbase, voff) do { _Pragma("unroll") for (int _i = 0; _i < 2; ++_i) \
;         __builtin_amdgcn_global_load_lds((const unsigned*)((const char*)(gbase) + (voff)[_i]), (PG8_LAS unsigned*)(lds + (bufoff) + ldsw + _i * 8192), 16, 0, 0); } while (0)
; #define PG8_LDA(dst, b, h) do { _Pragma("unroll") for (int m = 0; m < 4; ++m) _Pragma("unroll") for (int k = 0; k < 2; ++k) dst[m][k] = *(const PG8_LAS bf16x8*)(lds + PG8_SA(b, h) + aoff + m * 2048 + k * 1024); } while (0)
; #define PG8_MMA(ai, bj, At, Bt) do { __builtin_amdgcn_s_setprio(1); _Pragma("unroll") for (int m = 0; m < 4; ++m) _Pragma("unroll") for (int n = 0; n < 2; ++n) _Pragma("unroll") for (int k = 0; k < 2; ++k) \
;         acc[ai][bj][m][n] = __builtin_amdgcn_mfma_f32_16x16x32_bf16(Bt[n][k], At[m][k], acc[ai][bj][m][n], 0, 0, 0); __builtin_amdgcn_s_setprio(0); } while (0)
; #define PG8_WAIT_V(n) asm volatile("s_waitcnt vmcnt(" #n ")" ::: "memory")
; #define PG8_WAIT_L(n) asm volatile("s_waitcnt lgkmcnt(" #n ")" ::: "memory")
; #define PG8_BAR __builtin_amdgcn_s_barrier()
; #define PG8_SCHED __builtin_amdgcn_sched_barrier(0)
; template <class Epi, class Sched, bool ALIGN_EPI = false, bool SP2 = false>
; __device__ __forceinline__ void gemm_phase(PG8_LAS unsigned char* lds, const Gemm g, const Sched& S, const Epi& E) {
;     ...
;             PG8_LDA(At, 1, 1); PG8_STAGE(PG8_SB(1, 0), b3, voffB); PG8_STAGE(PG8_SB(1, 1), b3 + hstep, voffB); PG8_STAGE(PG8_SA(1, 0), a3, voffA);
;             PG8_WAIT_V(8); PG8_WAIT_L(0); PG8_BAR; PG8_MMA(1, 0, At, B0); PG8_MMA(1, 1, At, B1); PG8_BAR; PG8_SCHED;
;     ...
;         if constexpr (ALIGN_EPI) { if (wr == 0) PG8_BAR; }
	s_add_i32 s53, s53, s23
	v_lshl_add_u64 v[188:189], v[188:189], 0, s[8:9]
	s_mov_b32 m0, s53
	ds_read_b128 v[176:179], v163 offset:49152
	ds_read_b128 v[180:183], v163 offset:50176
	ds_read_b128 v[184:187], v163 offset:51200
	ds_read_b128 v[194:197], v163 offset:52224
	ds_read_b128 v[198:201], v163 offset:53248
	ds_read_b128 v[202:205], v163 offset:54272
	ds_read_b128 v[206:209], v163 offset:55296
	ds_read_b128 v[210:213], v163 offset:56320
	global_load_lds_dwordx4 v[188:189], off
	s_add_i32 m0, s53, 0x2000
	s_add_u32 s56, s56, 0x40080
	v_lshl_add_u64 v[188:189], v[214:215], 0, s[8:9]
	s_addc_u32 s57, s57, 0
	s_add_i32 s53, s60, s23
	global_load_lds_dwordx4 v[188:189], off
	v_lshl_add_u64 v[188:189], s[56:57], 0, v[0:1]
	s_mov_b32 m0, s53
	s_nop 0
	global_load_lds_dwordx4 v[188:189], off
	v_lshl_add_u64 v[188:189], s[56:57], 0, v[134:135]
	s_add_i32 m0, s53, 0x2000
	s_nop 0
	global_load_lds_dwordx4 v[188:189], off
	v_lshl_add_u64 v[188:189], v[216:217], 0, s[8:9]
	s_mov_b32 m0, s22
	s_nop 0
	global_load_lds_dwordx4 v[188:189], off
	v_lshl_add_u64 v[188:189], v[218:219], 0, s[8:9]
	s_mov_b32 m0, s51
	s_nop 0
	global_load_lds_dwordx4 v[188:189], off
	s_waitcnt vmcnt(8)
	s_waitcnt lgkmcnt(0)
	s_barrier
	s_setprio 1
	s_waitcnt lgkmcnt(0)
	v_mfma_f32_16x16x32_bf16 v[62:65], v[140:143], v[176:179], v[62:65]
	v_mfma_f32_16x16x32_bf16 v[58:61], v[148:151], v[176:179], v[58:61]
	v_mfma_f32_16x16x32_bf16 v[46:49], v[140:143], v[184:187], v[46:49]
	v_mfma_f32_16x16x32_bf16 v[42:45], v[148:151], v[184:187], v[42:45]
	v_mfma_f32_16x16x32_bf16 v[30:33], v[140:143], v[198:201], v[30:33]
	v_mfma_f32_16x16x32_bf16 v[26:29], v[148:151], v[198:201], v[26:29]
	v_mfma_f32_16x16x32_bf16 v[14:17], v[140:143], v[206:209], v[14:17]
	v_mfma_f32_16x16x32_bf16 v[10:13], v[148:151], v[206:209], v[10:13]
	v_mfma_f32_16x16x32_bf16 v[62:65], v[144:147], v[180:183], v[62:65]
	v_mfma_f32_16x16x32_bf16 v[58:61], v[152:155], v[180:183], v[58:61]
	v_mfma_f32_16x16x32_bf16 v[46:49], v[144:147], v[194:197], v[46:49]
	v_mfma_f32_16x16x32_bf16 v[42:45], v[152:155], v[194:197], v[42:45]
	v_mfma_f32_16x16x32_bf16 v[30:33], v[144:147], v[202:205], v[30:33]
	v_mfma_f32_16x16x32_bf16 v[26:29], v[152:155], v[202:205], v[26:29]
	v_mfma_f32_16x16x32_bf16 v[14:17], v[144:147], v[210:213], v[14:17]
	v_mfma_f32_16x16x32_bf16 v[10:13], v[152:155], v[210:213], v[10:13]
	s_setprio 0
	s_setprio 1
	v_mfma_f32_16x16x32_bf16 v[54:57], v[156:159], v[176:179], v[54:57]
	v_mfma_f32_16x16x32_bf16 v[50:53], v[168:171], v[176:179], v[50:53]
	v_mfma_f32_16x16x32_bf16 v[38:41], v[156:159], v[184:187], v[38:41]
	v_mfma_f32_16x16x32_bf16 v[34:37], v[168:171], v[184:187], v[34:37]
	v_mfma_f32_16x16x32_bf16 v[22:25], v[156:159], v[198:201], v[22:25]
	v_mfma_f32_16x16x32_bf16 v[18:21], v[168:171], v[198:201], v[18:21]
	v_mfma_f32_16x16x32_bf16 v[6:9], v[156:159], v[206:209], v[6:9]
	v_mfma_f32_16x16x32_bf16 v[2:5], v[168:171], v[206:209], v[2:5]
	v_mfma_f32_16x16x32_bf16 v[54:57], v[164:167], v[180:183], v[54:57]
	v_mfma_f32_16x16x32_bf16 v[50:53], v[172:175], v[180:183], v[50:53]
	v_mfma_f32_16x16x32_bf16 v[38:41], v[164:167], v[194:197], v[38:41]
	v_mfma_f32_16x16x32_bf16 v[34:37], v[172:175], v[194:197], v[34:37]
	v_mfma_f32_16x16x32_bf16 v[22:25], v[164:167], v[202:205], v[22:25]
	v_mfma_f32_16x16x32_bf16 v[18:21], v[172:175], v[202:205], v[18:21]
	v_mfma_f32_16x16x32_bf16 v[6:9], v[164:167], v[210:213], v[6:9]
	v_mfma_f32_16x16x32_bf16 v[2:5], v[172:175], v[210:213], v[2:5]
	s_setprio 0
	s_barrier
	s_add_i32 s52, s52, 2
	s_add_u32 s18, s18, 0x100
	s_addc_u32 s19, s19, 0
	s_add_u32 s41, s41, 0x100
	s_addc_u32 s43, s43, 0
	s_cmp_gt_u32 s52, 13
	s_cbranch_scc0 .LBB0_557


; #define PG8_BAR __builtin_amdgcn_s_barrier()
; __device__ __forceinline__ unsigned pkbf(float lo, float hi) { const f32x2_t v = {lo, hi}; const bf16x2_t b = __builtin_convertvector(v, bf16x2_t); return __builtin_bit_cast(unsigned, b); }
; __device__ __forceinline__ float ex2(float x) { return __builtin_amdgcn_exp2f(x); }
; template <class Epi, class Sched, bool ALIGN_EPI = false, bool SP2 = false>
; __device__ __forceinline__ void gemm_phase(PG8_LAS unsigned char* lds, const Gemm g, const Sched& S, const Epi& E) {
;     ...
;         if constexpr (ALIGN_EPI) { if (wr == 0) PG8_BAR; }
;     __device__ __forceinline__ void operator()(const f32x4 (&acc)[2][2][4][2], const pg8::Unit& u, int wr, int wc, int fr, int fq) const {
;         const int row0 = u.pm * 256 + wr * 64 + fr, col0 = u.pn * 128 + wc * 32 + 8 * fq;
;         u64 sv[2][4];
; #pragma unroll
;         for (int ai = 0; ai < 2; ++ai)
; #pragma unroll
;             for (int m = 0; m < 4; ++m) sv[ai][m] = ss[row0 + ai * 128 + m * 16];
; #pragma unroll
;         for (int ai = 0; ai < 2; ++ai)
; #pragma unroll
;             for (int m = 0; m < 4; ++m) {
;                 const int row = row0 + ai * 128 + m * 16;
;                 const float r = __builtin_amdgcn_rsqf((float)sv[ai][m] * SS_INV + 1e-6f);
;                 float h[8];
; #pragma unroll
;                 for (int n = 0; n < 2; ++n)
; #pragma unroll
;                     for (int i = 0; i < 4; ++i) { const float g = acc[ai][0][m][n][i] * r, uu = acc[ai][1][m][n][i] * r;
;                         h[n * 4 + i] = g * uu * __builtin_amdgcn_rcpf(1.0f + ex2(-g * LOG2E)); }
;                 u32x4 w; w.x = pkbf(h[0], h[1]); w.y = pkbf(h[2], h[3]); w.z = pkbf(h[4], h[5]); w.w = pkbf(h[6], h[7]);
;                 *(u32x4*)(O + (size_t)row * DM + col0) = w;
.LBB0_560:
	v_lshl_add_u32 v140, s54, 8, v160
	v_ashrrev_i32_e32 v141, 31, v140
	v_lshl_add_u64 v[142:143], v[140:141], 3, s[36:37]
	global_load_dwordx2 v[164:165], v[142:143], off
	global_load_dwordx2 v[166:167], v[142:143], off offset:128
	v_lshl_or_b32 v144, s50, 7, v162
	v_ashrrev_i32_e32 v145, 31, v144
	v_lshlrev_b64 v[150:151], 1, v[144:145]
	global_load_dwordx2 v[168:169], v[142:143], off offset:256
	global_load_dwordx2 v[156:157], v[142:143], off offset:384
	global_load_dwordx2 v[152:153], v[142:143], off offset:1024
	global_load_dwordx2 v[146:147], v[142:143], off offset:1152
	global_load_dwordx2 v[144:145], v[142:143], off offset:1280
	s_nop 0
	global_load_dwordx2 v[142:143], v[142:143], off offset:1408
	v_or_b32_e32 v158, 16, v140
	v_or_b32_e32 v154, 32, v140
	v_or_b32_e32 v148, 48, v140
	v_lshlrev_b64 v[140:141], 11, v[140:141]
	v_lshl_add_u64 v[140:141], s[98:99], 0, v[140:141]
	v_lshl_add_u64 v[140:141], v[140:141], 0, v[150:151]
	v_ashrrev_i32_e32 v159, 31, v158
	v_ashrrev_i32_e32 v155, 31, v154
	v_ashrrev_i32_e32 v149, 31, v148
	s_mov_b32 s18, 0x40000
	s_and_b64 vcc, exec, s[38:39]
	s_cbranch_vccz .Lalign_go_5
	s_barrier
.Lalign_go_5:
	s_waitcnt vmcnt(0)
	v_ffbh_u32_e32 v170, v165
	v_ffbh_u32_e32 v171, v167
	v_min_u32_e32 v170, 32, v170
	v_min_u32_e32 v171, 32, v171
	v_lshlrev_b64 v[164:165], v170, v[164:165]
	v_lshlrev_b64 v[166:167], v171, v[166:167]
	v_min_u32_e32 v164, 1, v164
	v_or_b32_e32 v164, v165, v164
	v_min_u32_e32 v165, 1, v166
	v_cvt_f32_u32_e32 v164, v164
	v_or_b32_e32 v165, v167, v165
	v_cvt_f32_u32_e32 v165, v165
	v_sub_u32_e32 v170, 32, v170
	v_sub_u32_e32 v171, 32, v171
	v_ldexp_f32 v164, v164, v170
	v_fmamk_f32 v164, v164, 0x30800000, v229
	v_ldexp_f32 v165, v165, v171
	v_rsq_f32_e32 v164, v164
	v_fmamk_f32 v165, v165, 0x30800000, v229
	v_rsq_f32_e32 v166, v165
	v_pk_mul_f32 v[126:127], v[126:127], v[164:165] op_sel_hi:[1,0]
	v_pk_mul_f32 v[114:115], v[114:115], v[164:165] op_sel_hi:[1,0]
	v_pk_mul_f32 v[128:129], v[128:129], v[164:165] op_sel_hi:[1,0]
	v_pk_mul_f32 v[116:117], v[116:117], v[164:165] op_sel_hi:[1,0]
	v_pk_mul_f32 v[122:123], v[122:123], v[164:165] op_sel_hi:[1,0]
	v_pk_mul_f32 v[110:111], v[110:111], v[164:165] op_sel_hi:[1,0]
	v_pk_mul_f32 v[124:125], v[124:125], v[164:165] op_sel_hi:[1,0]
	v_pk_mul_f32 v[112:113], v[112:113], v[164:165] op_sel_hi:[1,0]
	v_pk_mul_f32 v[118:119], v[118:119], v[166:167] op_sel_hi:[1,0]
	v_pk_mul_f32 v[102:103], v[102:103], v[166:167] op_sel_hi:[1,0]
	v_mul_f32_e32 v164, 0xbfb8aa3b, v126
	v_pk_mul_f32 v[114:115], v[126:127], v[114:115]
	v_mul_f32_e32 v126, 0xbfb8aa3b, v127
	v_mul_f32_e32 v127, 0xbfb8aa3b, v128
	v_pk_mul_f32 v[116:117], v[128:129], v[116:117]
	v_mul_f32_e32 v128, 0xbfb8aa3b, v129
	v_mul_f32_e32 v129, 0xbfb8aa3b, v122
	v_pk_mul_f32 v[110:111], v[122:123], v[110:111]
	v_mul_f32_e32 v122, 0xbfb8aa3b, v123
	v_mul_f32_e32 v123, 0xbfb8aa3b, v124
	v_pk_mul_f32 v[112:113], v[124:125], v[112:113]
	v_mul_f32_e32 v124, 0xbfb8aa3b, v125
	v_mul_f32_e32 v125, 0xbfb8aa3b, v118
	v_pk_mul_f32 v[102:103], v[118:119], v[102:103]
	v_mul_f32_e32 v118, 0xbfb8aa3b, v119
	v_exp_f32_e32 v164, v164
	v_exp_f32_e32 v126, v126
	v_exp_f32_e32 v127, v127
	v_exp_f32_e32 v128, v128
	v_exp_f32_e32 v129, v129
	v_exp_f32_e32 v122, v122
	v_exp_f32_e32 v123, v123
	v_exp_f32_e32 v124, v124
	v_exp_f32_e32 v125, v125
	v_exp_f32_e32 v118, v118
	v_pk_mul_f32 v[120:121], v[120:121], v[166:167] op_sel_hi:[1,0]
	v_add_f32_e32 v126, 1.0, v126
	v_mul_f32_e32 v119, 0xbfb8aa3b, v120
	v_exp_f32_e32 v167, v119
	v_add_f32_e32 v119, 1.0, v164
	v_add_f32_e32 v127, 1.0, v127
	v_add_f32_e32 v128, 1.0, v128
	v_add_f32_e32 v129, 1.0, v129
	v_add_f32_e32 v164, 1.0, v122
	v_add_f32_e32 v170, 1.0, v123
	v_add_f32_e32 v171, 1.0, v124
	v_add_f32_e32 v172, 1.0, v125
	v_add_f32_e32 v173, 1.0, v118
	v_rcp_f32_e32 v118, v119
	v_rcp_f32_e32 v119, v126
	v_rcp_f32_e32 v122, v127
	v_rcp_f32_e32 v123, v128
	v_rcp_f32_e32 v124, v129
	v_rcp_f32_e32 v125, v164
	v_rcp_f32_e32 v126, v170
	v_rcp_f32_e32 v127, v171
	v_mul_f32_e32 v165, 0xbfb8aa3b, v121
	v_exp_f32_e32 v165, v165
	v_pk_mul_f32 v[114:115], v[114:115], v[118:119]
	v_pk_mul_f32 v[116:117], v[116:117], v[122:123]
	v_pk_mul_f32 v[118:119], v[110:111], v[124:125]
	v_pk_mul_f32 v[122:123], v[112:113], v[126:127]
	v_cvt_pk_bf16_f32 v110, v114, v115
	v_cvt_pk_bf16_f32 v111, v116, v117
	v_cvt_pk_bf16_f32 v112, v118, v119
	v_cvt_pk_bf16_f32 v113, v122, v123
	global_store_dwordx4 v[140:141], v[110:113], off
	v_pk_mul_f32 v[104:105], v[104:105], v[166:167] op_sel_hi:[1,0]
	v_pk_mul_f32 v[106:107], v[106:107], v[166:167] op_sel_hi:[1,0]
	v_add_f32_e32 v110, 1.0, v167
	v_add_f32_e32 v111, 1.0, v165
	v_rcp_f32_e32 v110, v110
	v_rcp_f32_e32 v111, v111
	v_pk_mul_f32 v[104:105], v[120:121], v[104:105]
	v_mul_f32_e32 v112, 0xbfb8aa3b, v106
	v_pk_mul_f32 v[98:99], v[98:99], v[166:167] op_sel_hi:[1,0]
	v_pk_mul_f32 v[104:105], v[104:105], v[110:111]
	v_mul_f32_e32 v111, 0xbfb8aa3b, v107
	v_exp_f32_e32 v112, v112
	v_exp_f32_e32 v111, v111
	v_pk_mul_f32 v[98:99], v[106:107], v[98:99]
	v_pk_mul_f32 v[106:107], v[108:109], v[166:167] op_sel_hi:[1,0]
	v_add_f32_e32 v110, 1.0, v112
	v_mul_f32_e32 v108, 0xbfb8aa3b, v106
	v_mul_f32_e32 v109, 0xbfb8aa3b, v107
	v_exp_f32_e32 v108, v108
	v_exp_f32_e32 v109, v109
	v_add_f32_e32 v111, 1.0, v111
	v_rcp_f32_e32 v110, v110
	v_rcp_f32_e32 v111, v111
	v_add_f32_e32 v108, 1.0, v108
	v_add_f32_e32 v109, 1.0, v109
	v_rcp_f32_e32 v108, v108
	v_rcp_f32_e32 v109, v109
	v_pk_mul_f32 v[110:111], v[98:99], v[110:111]
	v_pk_mul_f32 v[98:99], v[100:101], v[166:167] op_sel_hi:[1,0]
	v_rcp_f32_e32 v128, v172
	v_pk_mul_f32 v[98:99], v[106:107], v[98:99]
; __device__ __forceinline__ unsigned pkbf(float lo, float hi) { const f32x2_t v = {lo, hi}; const bf16x2_t b = __builtin_convertvector(v, bf16x2_t); return __builtin_bit_cast(unsigned, b); }
; __device__ __forceinline__ float ex2(float x) { return __builtin_amdgcn_exp2f(x); }
;     __device__ __forceinline__ void operator()(const f32x4 (&acc)[2][2][4][2], const pg8::Unit& u, int wr, int wc, int fr, int fq) const {
;     ...
;         for (int ai = 0; ai < 2; ++ai)
; #pragma unroll
;             for (int m = 0; m < 4; ++m) {
;                 const int row = row0 + ai * 128 + m * 16;
;                 const float r = __builtin_amdgcn_rsqf((float)sv[ai][m] * SS_INV + 1e-6f);
;                 float h[8];
; #pragma unroll
;                 for (int n = 0; n < 2; ++n)
; #pragma unroll
;                     for (int i = 0; i < 4; ++i) { const float g = acc[ai][0][m][n][i] * r, uu = acc[ai][1][m][n][i] * r;
;                         h[n * 4 + i] = g * uu * __builtin_amdgcn_rcpf(1.0f + ex2(-g * LOG2E)); }
;                 u32x4 w; w.x = pkbf(h[0], h[1]); w.y = pkbf(h[2], h[3]); w.z = pkbf(h[4], h[5]); w.w = pkbf(h[6], h[7]);
;                 *(u32x4*)(O + (size_t)row * DM + col0) = w;
	v_rcp_f32_e32 v129, v173
	v_pk_mul_f32 v[106:107], v[98:99], v[108:109]
	v_ffbh_u32_e32 v98, v169
	v_min_u32_e32 v100, 32, v98
	v_lshlrev_b64 v[98:99], v100, v[168:169]
	v_min_u32_e32 v98, 1, v98
	v_or_b32_e32 v98, v99, v98
	v_cvt_f32_u32_e32 v101, v98
	v_sub_u32_e32 v100, 32, v100
	v_pk_mul_f32 v[102:103], v[102:103], v[128:129]
	v_cvt_pk_bf16_f32 v99, v104, v105
	v_ldexp_f32 v100, v101, v100
	v_fmamk_f32 v100, v100, 0x30800000, v229
	v_cvt_pk_bf16_f32 v98, v102, v103
	v_rsq_f32_e32 v102, v100
	v_lshlrev_b64 v[104:105], 11, v[158:159]
	v_lshl_add_u64 v[104:105], s[98:99], 0, v[104:105]
	v_cvt_pk_bf16_f32 v100, v110, v111
	v_pk_mul_f32 v[94:95], v[94:95], v[102:103] op_sel_hi:[1,0]
	v_cvt_pk_bf16_f32 v101, v106, v107
	v_mul_f32_e32 v103, 0xbfb8aa3b, v94
	v_lshl_add_u64 v[104:105], v[104:105], 0, v[150:151]
	v_exp_f32_e32 v103, v103
	global_store_dwordx4 v[104:105], v[98:101], off
	v_pk_mul_f32 v[86:87], v[86:87], v[102:103] op_sel_hi:[1,0]
	s_nop 0
	v_mul_f32_e32 v99, 0xbfb8aa3b, v95
	v_exp_f32_e32 v99, v99
	v_add_f32_e32 v98, 1.0, v103
	v_pk_mul_f32 v[86:87], v[94:95], v[86:87]
	v_rcp_f32_e32 v98, v98
	v_add_f32_e32 v94, 1.0, v99
	v_rcp_f32_e32 v99, v94
	v_pk_mul_f32 v[94:95], v[96:97], v[102:103] op_sel_hi:[1,0]
	v_pk_mul_f32 v[90:91], v[90:91], v[102:103] op_sel_hi:[1,0]
	v_pk_mul_f32 v[88:89], v[88:89], v[102:103] op_sel_hi:[1,0]
	v_mul_f32_e32 v97, 0xbfb8aa3b, v95
	v_pk_mul_f32 v[86:87], v[86:87], v[98:99]
	v_mul_f32_e32 v98, 0xbfb8aa3b, v90
	v_pk_mul_f32 v[88:89], v[94:95], v[88:89]
	v_mul_f32_e32 v95, 0xbfb8aa3b, v91
	v_pk_mul_f32 v[82:83], v[82:83], v[102:103] op_sel_hi:[1,0]
	v_exp_f32_e32 v98, v98
	v_exp_f32_e32 v95, v95
	v_pk_mul_f32 v[82:83], v[90:91], v[82:83]
	v_pk_mul_f32 v[90:91], v[92:93], v[102:103] op_sel_hi:[1,0]
	v_mul_f32_e32 v96, 0xbfb8aa3b, v94
	v_mul_f32_e32 v92, 0xbfb8aa3b, v90
	v_mul_f32_e32 v93, 0xbfb8aa3b, v91
	v_exp_f32_e32 v92, v92
	v_exp_f32_e32 v93, v93
	v_add_f32_e32 v94, 1.0, v98
	v_add_f32_e32 v95, 1.0, v95
	v_rcp_f32_e32 v94, v94
	v_rcp_f32_e32 v95, v95
	v_add_f32_e32 v92, 1.0, v92
	v_add_f32_e32 v93, 1.0, v93
	v_rcp_f32_e32 v92, v92
	v_rcp_f32_e32 v93, v93
	v_pk_mul_f32 v[94:95], v[82:83], v[94:95]
	v_pk_mul_f32 v[82:83], v[84:85], v[102:103] op_sel_hi:[1,0]
	v_exp_f32_e32 v96, v96
	v_pk_mul_f32 v[82:83], v[90:91], v[82:83]
	v_exp_f32_e32 v97, v97
	v_pk_mul_f32 v[90:91], v[82:83], v[92:93]
	v_ffbh_u32_e32 v82, v157
	v_min_u32_e32 v84, 32, v82
	v_lshlrev_b64 v[82:83], v84, v[156:157]
	v_min_u32_e32 v82, 1, v82
	v_or_b32_e32 v82, v83, v82
	v_cvt_f32_u32_e32 v85, v82
	v_add_f32_e32 v96, 1.0, v96
	v_add_f32_e32 v97, 1.0, v97
	v_sub_u32_e32 v84, 32, v84
	v_rcp_f32_e32 v96, v96
	v_rcp_f32_e32 v97, v97
	v_ldexp_f32 v84, v85, v84
	v_fmamk_f32 v84, v84, 0x30800000, v229
	v_cvt_pk_bf16_f32 v82, v86, v87
	v_rsq_f32_e32 v86, v84
	v_pk_mul_f32 v[88:89], v[88:89], v[96:97]
	v_cvt_pk_bf16_f32 v84, v94, v95
	v_cvt_pk_bf16_f32 v83, v88, v89
	v_lshlrev_b64 v[88:89], 11, v[154:155]
	v_pk_mul_f32 v[78:79], v[78:79], v[86:87] op_sel_hi:[1,0]
	v_lshl_add_u64 v[88:89], s[98:99], 0, v[88:89]
	v_cvt_pk_bf16_f32 v85, v90, v91
	v_mul_f32_e32 v87, 0xbfb8aa3b, v78
	v_lshl_add_u64 v[88:89], v[88:89], 0, v[150:151]
	v_exp_f32_e32 v87, v87
	global_store_dwordx4 v[88:89], v[82:85], off
	v_pk_mul_f32 v[70:71], v[70:71], v[86:87] op_sel_hi:[1,0]
	s_nop 0
	v_mul_f32_e32 v83, 0xbfb8aa3b, v79
	v_exp_f32_e32 v83, v83
	v_add_f32_e32 v82, 1.0, v87
	v_pk_mul_f32 v[70:71], v[78:79], v[70:71]
	v_rcp_f32_e32 v82, v82
	v_add_f32_e32 v78, 1.0, v83
	v_rcp_f32_e32 v83, v78
	v_pk_mul_f32 v[78:79], v[80:81], v[86:87] op_sel_hi:[1,0]
	v_pk_mul_f32 v[74:75], v[74:75], v[86:87] op_sel_hi:[1,0]
	v_pk_mul_f32 v[72:73], v[72:73], v[86:87] op_sel_hi:[1,0]
	v_mul_f32_e32 v81, 0xbfb8aa3b, v79
	v_pk_mul_f32 v[70:71], v[70:71], v[82:83]
	v_mul_f32_e32 v82, 0xbfb8aa3b, v74
	v_pk_mul_f32 v[72:73], v[78:79], v[72:73]
	v_mul_f32_e32 v79, 0xbfb8aa3b, v75
	v_pk_mul_f32 v[66:67], v[66:67], v[86:87] op_sel_hi:[1,0]
	v_exp_f32_e32 v82, v82
	v_exp_f32_e32 v79, v79
	v_pk_mul_f32 v[66:67], v[74:75], v[66:67]
	v_pk_mul_f32 v[74:75], v[76:77], v[86:87] op_sel_hi:[1,0]
	v_mul_f32_e32 v80, 0xbfb8aa3b, v78
	v_mul_f32_e32 v76, 0xbfb8aa3b, v74
	v_mul_f32_e32 v77, 0xbfb8aa3b, v75
	v_exp_f32_e32 v76, v76
	v_exp_f32_e32 v77, v77
	v_add_f32_e32 v78, 1.0, v82
	v_add_f32_e32 v79, 1.0, v79
	v_rcp_f32_e32 v78, v78
	v_rcp_f32_e32 v79, v79
	v_add_f32_e32 v76, 1.0, v76
	v_add_f32_e32 v77, 1.0, v77
	v_rcp_f32_e32 v76, v76
	v_rcp_f32_e32 v77, v77
	v_pk_mul_f32 v[78:79], v[66:67], v[78:79]
	v_pk_mul_f32 v[66:67], v[68:69], v[86:87] op_sel_hi:[1,0]
	v_ffbh_u32_e32 v68, v153
	v_pk_mul_f32 v[66:67], v[74:75], v[66:67]
	v_exp_f32_e32 v80, v80
	v_pk_mul_f32 v[74:75], v[66:67], v[76:77]
	v_cvt_pk_bf16_f32 v66, v70, v71
	v_min_u32_e32 v70, 32, v68
	v_lshlrev_b64 v[68:69], v70, v[152:153]
	v_min_u32_e32 v68, 1, v68
	v_or_b32_e32 v68, v69, v68
	v_cvt_f32_u32_e32 v71, v68
	v_sub_u32_e32 v70, 32, v70
	v_exp_f32_e32 v81, v81
	v_add_f32_e32 v80, 1.0, v80
	v_ldexp_f32 v70, v71, v70
	v_fmamk_f32 v70, v70, 0x30800000, v229
	v_rsq_f32_e32 v70, v70
	v_add_f32_e32 v81, 1.0, v81
	v_rcp_f32_e32 v80, v80
	v_rcp_f32_e32 v81, v81
	v_pk_mul_f32 v[62:63], v[62:63], v[70:71] op_sel_hi:[1,0]
	v_cvt_pk_bf16_f32 v68, v78, v79
	v_mul_f32_e32 v71, 0xbfb8aa3b, v62
	v_exp_f32_e32 v71, v71
	v_pk_mul_f32 v[72:73], v[72:73], v[80:81]
	v_cvt_pk_bf16_f32 v69, v74, v75
	v_cvt_pk_bf16_f32 v67, v72, v73
	v_lshlrev_b64 v[72:73], 11, v[148:149]
	v_lshl_add_u64 v[72:73], s[98:99], 0, v[72:73]
	v_lshl_add_u64 v[72:73], v[72:73], 0, v[150:151]
	v_pk_mul_f32 v[64:65], v[64:65], v[70:71] op_sel_hi:[1,0]
	v_pk_mul_f32 v[54:55], v[54:55], v[70:71] op_sel_hi:[1,0]
; __device__ __forceinline__ unsigned pkbf(float lo, float hi) { const f32x2_t v = {lo, hi}; const bf16x2_t b = __builtin_convertvector(v, bf16x2_t); return __builtin_bit_cast(unsigned, b); }
; __device__ __forceinline__ float ex2(float x) { return __builtin_amdgcn_exp2f(x); }
;     __device__ __forceinline__ void operator()(const f32x4 (&acc)[2][2][4][2], const pg8::Unit& u, int wr, int wc, int fr, int fq) const {
;     ...
;         for (int ai = 0; ai < 2; ++ai)
; #pragma unroll
;             for (int m = 0; m < 4; ++m) {
;                 const int row = row0 + ai * 128 + m * 16;
;                 const float r = __builtin_amdgcn_rsqf((float)sv[ai][m] * SS_INV + 1e-6f);
;                 float h[8];
; #pragma unroll
;                 for (int n = 0; n < 2; ++n)
; #pragma unroll
;                     for (int i = 0; i < 4; ++i) { const float g = acc[ai][0][m][n][i] * r, uu = acc[ai][1][m][n][i] * r;
;                         h[n * 4 + i] = g * uu * __builtin_amdgcn_rcpf(1.0f + ex2(-g * LOG2E)); }
;                 u32x4 w; w.x = pkbf(h[0], h[1]); w.y = pkbf(h[2], h[3]); w.z = pkbf(h[4], h[5]); w.w = pkbf(h[6], h[7]);
;                 *(u32x4*)(O + (size_t)row * DM + col0) = w;
	v_mul_f32_e32 v74, 0xbfb8aa3b, v63
	global_store_dwordx4 v[72:73], v[66:69], off
	v_pk_mul_f32 v[54:55], v[62:63], v[54:55]
	v_mul_f32_e32 v63, 0xbfb8aa3b, v65
	v_mul_f32_e32 v68, 0xbfb8aa3b, v64
	v_exp_f32_e32 v68, v68
	v_exp_f32_e32 v63, v63
	v_pk_mul_f32 v[56:57], v[56:57], v[70:71] op_sel_hi:[1,0]
	v_pk_mul_f32 v[58:59], v[58:59], v[70:71] op_sel_hi:[1,0]
	v_add_f32_e32 v62, 1.0, v68
	v_pk_mul_f32 v[56:57], v[64:65], v[56:57]
	v_add_f32_e32 v63, 1.0, v63
	v_mul_f32_e32 v64, 0xbfb8aa3b, v58
	v_mul_f32_e32 v65, 0xbfb8aa3b, v59
	v_rcp_f32_e32 v62, v62
	v_rcp_f32_e32 v63, v63
	v_exp_f32_e32 v64, v64
	v_exp_f32_e32 v65, v65
	v_pk_mul_f32 v[50:51], v[50:51], v[70:71] op_sel_hi:[1,0]
	v_pk_mul_f32 v[56:57], v[56:57], v[62:63]
	v_add_f32_e32 v62, 1.0, v64
	v_add_f32_e32 v63, 1.0, v65
	v_rcp_f32_e32 v62, v62
	v_rcp_f32_e32 v63, v63
	v_pk_mul_f32 v[60:61], v[60:61], v[70:71] op_sel_hi:[1,0]
	v_pk_mul_f32 v[50:51], v[58:59], v[50:51]
	v_mul_f32_e32 v64, 0xbfb8aa3b, v60
	v_pk_mul_f32 v[58:59], v[50:51], v[62:63]
	v_mul_f32_e32 v51, 0xbfb8aa3b, v61
	v_exp_f32_e32 v64, v64
	v_exp_f32_e32 v51, v51
	v_pk_mul_f32 v[52:53], v[52:53], v[70:71] op_sel_hi:[1,0]
	v_exp_f32_e32 v74, v74
	v_pk_mul_f32 v[52:53], v[60:61], v[52:53]
	v_ffbh_u32_e32 v60, v147
	v_min_u32_e32 v62, 32, v60
	v_lshlrev_b64 v[60:61], v62, v[146:147]
	v_add_f32_e32 v50, 1.0, v64
	v_add_f32_e32 v51, 1.0, v51
	v_min_u32_e32 v60, 1, v60
	v_rcp_f32_e32 v50, v50
	v_rcp_f32_e32 v51, v51
	v_or_b32_e32 v60, v61, v60
	v_add_f32_e32 v66, 1.0, v71
	v_add_f32_e32 v67, 1.0, v74
	v_cvt_f32_u32_e32 v63, v60
	v_rcp_f32_e32 v66, v66
	v_rcp_f32_e32 v67, v67
	v_pk_mul_f32 v[60:61], v[52:53], v[50:51]
	v_sub_u32_e32 v51, 32, v62
	v_ldexp_f32 v51, v63, v51
	v_pk_mul_f32 v[54:55], v[54:55], v[66:67]
	v_fmamk_f32 v51, v51, 0x30800000, v229
	v_cvt_pk_bf16_f32 v50, v54, v55
	v_rsq_f32_e32 v54, v51
	v_cvt_pk_bf16_f32 v51, v56, v57
	v_add_co_u32_e32 v56, vcc, s18, v140
	v_pk_mul_f32 v[46:47], v[46:47], v[54:55] op_sel_hi:[1,0]
	v_cvt_pk_bf16_f32 v52, v58, v59
	v_cvt_pk_bf16_f32 v53, v60, v61
	v_mul_f32_e32 v55, 0xbfb8aa3b, v46
	v_addc_co_u32_e32 v57, vcc, 0, v141, vcc
	v_exp_f32_e32 v55, v55
	global_store_dwordx4 v[56:57], v[50:53], off
	s_mov_b32 s18, 0x48000
	v_pk_mul_f32 v[38:39], v[38:39], v[54:55] op_sel_hi:[1,0]
	v_mul_f32_e32 v51, 0xbfb8aa3b, v47
	v_exp_f32_e32 v51, v51
	v_add_f32_e32 v50, 1.0, v55
	v_pk_mul_f32 v[38:39], v[46:47], v[38:39]
	v_rcp_f32_e32 v50, v50
	v_add_f32_e32 v46, 1.0, v51
	v_rcp_f32_e32 v51, v46
	v_pk_mul_f32 v[46:47], v[48:49], v[54:55] op_sel_hi:[1,0]
	v_pk_mul_f32 v[42:43], v[42:43], v[54:55] op_sel_hi:[1,0]
	v_pk_mul_f32 v[40:41], v[40:41], v[54:55] op_sel_hi:[1,0]
	v_mul_f32_e32 v49, 0xbfb8aa3b, v47
	v_pk_mul_f32 v[38:39], v[38:39], v[50:51]
	v_mul_f32_e32 v50, 0xbfb8aa3b, v42
	v_pk_mul_f32 v[40:41], v[46:47], v[40:41]
	v_mul_f32_e32 v47, 0xbfb8aa3b, v43
	v_pk_mul_f32 v[34:35], v[34:35], v[54:55] op_sel_hi:[1,0]
	v_exp_f32_e32 v50, v50
	v_exp_f32_e32 v47, v47
	v_pk_mul_f32 v[34:35], v[42:43], v[34:35]
	v_pk_mul_f32 v[42:43], v[44:45], v[54:55] op_sel_hi:[1,0]
	v_mul_f32_e32 v48, 0xbfb8aa3b, v46
	v_mul_f32_e32 v44, 0xbfb8aa3b, v42
	v_mul_f32_e32 v45, 0xbfb8aa3b, v43
	v_exp_f32_e32 v44, v44
	v_exp_f32_e32 v45, v45
	v_add_f32_e32 v46, 1.0, v50
	v_add_f32_e32 v47, 1.0, v47
	v_rcp_f32_e32 v46, v46
	v_rcp_f32_e32 v47, v47
	v_add_f32_e32 v44, 1.0, v44
	v_add_f32_e32 v45, 1.0, v45
	v_rcp_f32_e32 v44, v44
	v_rcp_f32_e32 v45, v45
	v_pk_mul_f32 v[46:47], v[34:35], v[46:47]
	v_pk_mul_f32 v[34:35], v[36:37], v[54:55] op_sel_hi:[1,0]
	v_ffbh_u32_e32 v36, v145
	v_pk_mul_f32 v[34:35], v[42:43], v[34:35]
	v_exp_f32_e32 v48, v48
	v_pk_mul_f32 v[42:43], v[34:35], v[44:45]
	v_cvt_pk_bf16_f32 v34, v38, v39
	v_min_u32_e32 v38, 32, v36
	v_lshlrev_b64 v[36:37], v38, v[144:145]
	v_min_u32_e32 v36, 1, v36
	v_or_b32_e32 v36, v37, v36
	v_cvt_f32_u32_e32 v39, v36
	v_sub_u32_e32 v38, 32, v38
	v_exp_f32_e32 v49, v49
	v_add_f32_e32 v48, 1.0, v48
	v_ldexp_f32 v38, v39, v38
	v_fmamk_f32 v38, v38, 0x30800000, v229
	v_rsq_f32_e32 v38, v38
	v_add_f32_e32 v49, 1.0, v49
	v_rcp_f32_e32 v48, v48
	v_rcp_f32_e32 v49, v49
	v_pk_mul_f32 v[30:31], v[30:31], v[38:39] op_sel_hi:[1,0]
	v_cvt_pk_bf16_f32 v36, v46, v47
	v_mul_f32_e32 v39, 0xbfb8aa3b, v30
	v_exp_f32_e32 v39, v39
	v_pk_mul_f32 v[40:41], v[40:41], v[48:49]
	v_cvt_pk_bf16_f32 v37, v42, v43
	v_cvt_pk_bf16_f32 v35, v40, v41
	v_add_co_u32_e32 v40, vcc, s18, v140
; #define PG8_BAR __builtin_amdgcn_s_barrier()
; __device__ __forceinline__ unsigned pkbf(float lo, float hi) { const f32x2_t v = {lo, hi}; const bf16x2_t b = __builtin_convertvector(v, bf16x2_t); return __builtin_bit_cast(unsigned, b); }
; __device__ __forceinline__ float ex2(float x) { return __builtin_amdgcn_exp2f(x); }
; template <class Epi, class Sched, bool ALIGN_EPI = false, bool SP2 = false>
; __device__ __forceinline__ void gemm_phase(PG8_LAS unsigned char* lds, const Gemm g, const Sched& S, const Epi& E) {
;     ...
;         if (!has_next) break;
; #pragma unroll
;         for (int a = 0; a < 2; ++a)
; #pragma unroll
;             for (int b = 0; b < 2; ++b)
; #pragma unroll
;                 for (int m = 0; m < 4; ++m)
; #pragma unroll
;                     for (int n = 0; n < 2; ++n) acc[a][b][m][n] = (f32x4){0.f, 0.f, 0.f, 0.f};
;         cur = nxt; cA = nA; cB = nB; ++ui;
;         if constexpr (ALIGN_EPI) { if (wr == 1) PG8_BAR; }
;     __device__ __forceinline__ void operator()(const f32x4 (&acc)[2][2][4][2], const pg8::Unit& u, int wr, int wc, int fr, int fq) const {
;     ...
;         for (int ai = 0; ai < 2; ++ai)
; #pragma unroll
;             for (int m = 0; m < 4; ++m) {
;                 const int row = row0 + ai * 128 + m * 16;
;                 const float r = __builtin_amdgcn_rsqf((float)sv[ai][m] * SS_INV + 1e-6f);
;                 float h[8];
; #pragma unroll
;                 for (int n = 0; n < 2; ++n)
; #pragma unroll
;                     for (int i = 0; i < 4; ++i) { const float g = acc[ai][0][m][n][i] * r, uu = acc[ai][1][m][n][i] * r;
;                         h[n * 4 + i] = g * uu * __builtin_amdgcn_rcpf(1.0f + ex2(-g * LOG2E)); }
;                 u32x4 w; w.x = pkbf(h[0], h[1]); w.y = pkbf(h[2], h[3]); w.z = pkbf(h[4], h[5]); w.w = pkbf(h[6], h[7]);
;                 *(u32x4*)(O + (size_t)row * DM + col0) = w;
	v_pk_mul_f32 v[32:33], v[32:33], v[38:39] op_sel_hi:[1,0]
	s_nop 0
	v_addc_co_u32_e32 v41, vcc, 0, v141, vcc
	v_pk_mul_f32 v[22:23], v[22:23], v[38:39] op_sel_hi:[1,0]
	v_mul_f32_e32 v42, 0xbfb8aa3b, v31
	global_store_dwordx4 v[40:41], v[34:37], off
	v_pk_mul_f32 v[22:23], v[30:31], v[22:23]
	v_mul_f32_e32 v31, 0xbfb8aa3b, v33
	v_mul_f32_e32 v36, 0xbfb8aa3b, v32
	v_exp_f32_e32 v36, v36
	v_exp_f32_e32 v31, v31
	v_pk_mul_f32 v[24:25], v[24:25], v[38:39] op_sel_hi:[1,0]
	v_pk_mul_f32 v[26:27], v[26:27], v[38:39] op_sel_hi:[1,0]
	v_add_f32_e32 v30, 1.0, v36
	v_pk_mul_f32 v[24:25], v[32:33], v[24:25]
	v_add_f32_e32 v31, 1.0, v31
	v_mul_f32_e32 v32, 0xbfb8aa3b, v26
	v_mul_f32_e32 v33, 0xbfb8aa3b, v27
	v_rcp_f32_e32 v30, v30
	v_rcp_f32_e32 v31, v31
	v_exp_f32_e32 v32, v32
	v_exp_f32_e32 v33, v33
	v_pk_mul_f32 v[18:19], v[18:19], v[38:39] op_sel_hi:[1,0]
	v_pk_mul_f32 v[24:25], v[24:25], v[30:31]
	v_add_f32_e32 v30, 1.0, v32
	v_add_f32_e32 v31, 1.0, v33
	v_rcp_f32_e32 v30, v30
	v_rcp_f32_e32 v31, v31
	v_pk_mul_f32 v[28:29], v[28:29], v[38:39] op_sel_hi:[1,0]
	v_pk_mul_f32 v[18:19], v[26:27], v[18:19]
	v_mul_f32_e32 v32, 0xbfb8aa3b, v28
	v_pk_mul_f32 v[26:27], v[18:19], v[30:31]
	v_mul_f32_e32 v19, 0xbfb8aa3b, v29
	v_exp_f32_e32 v32, v32
	v_exp_f32_e32 v19, v19
	v_pk_mul_f32 v[20:21], v[20:21], v[38:39] op_sel_hi:[1,0]
	v_exp_f32_e32 v42, v42
	v_pk_mul_f32 v[20:21], v[28:29], v[20:21]
	v_ffbh_u32_e32 v28, v143
	v_min_u32_e32 v30, 32, v28
	v_lshlrev_b64 v[28:29], v30, v[142:143]
	v_add_f32_e32 v18, 1.0, v32
	v_add_f32_e32 v19, 1.0, v19
	v_min_u32_e32 v28, 1, v28
	v_rcp_f32_e32 v18, v18
	v_rcp_f32_e32 v19, v19
	v_or_b32_e32 v28, v29, v28
	v_add_f32_e32 v34, 1.0, v39
	v_add_f32_e32 v35, 1.0, v42
	v_cvt_f32_u32_e32 v31, v28
	v_rcp_f32_e32 v34, v34
	v_rcp_f32_e32 v35, v35
	v_pk_mul_f32 v[28:29], v[20:21], v[18:19]
	v_sub_u32_e32 v19, 32, v30
	v_ldexp_f32 v19, v31, v19
	v_pk_mul_f32 v[22:23], v[22:23], v[34:35]
	v_fmamk_f32 v19, v19, 0x30800000, v229
	v_cvt_pk_bf16_f32 v18, v22, v23
	v_rsq_f32_e32 v22, v19
	s_mov_b32 s18, 0x50000
	v_cvt_pk_bf16_f32 v19, v24, v25
	v_add_co_u32_e32 v24, vcc, s18, v140
	v_pk_mul_f32 v[14:15], v[14:15], v[22:23] op_sel_hi:[1,0]
	v_cvt_pk_bf16_f32 v20, v26, v27
	v_cvt_pk_bf16_f32 v21, v28, v29
	v_mul_f32_e32 v23, 0xbfb8aa3b, v14
	v_addc_co_u32_e32 v25, vcc, 0, v141, vcc
	v_exp_f32_e32 v23, v23
	global_store_dwordx4 v[24:25], v[18:21], off
	s_mov_b64 s[18:19], -1
	v_pk_mul_f32 v[6:7], v[6:7], v[22:23] op_sel_hi:[1,0]
	v_mul_f32_e32 v19, 0xbfb8aa3b, v15
	v_exp_f32_e32 v19, v19
	v_add_f32_e32 v18, 1.0, v23
	v_pk_mul_f32 v[6:7], v[14:15], v[6:7]
	v_rcp_f32_e32 v18, v18
	v_add_f32_e32 v14, 1.0, v19
	v_rcp_f32_e32 v19, v14
	v_pk_mul_f32 v[14:15], v[16:17], v[22:23] op_sel_hi:[1,0]
	v_pk_mul_f32 v[10:11], v[10:11], v[22:23] op_sel_hi:[1,0]
	v_pk_mul_f32 v[8:9], v[8:9], v[22:23] op_sel_hi:[1,0]
	v_mul_f32_e32 v17, 0xbfb8aa3b, v15
	v_pk_mul_f32 v[6:7], v[6:7], v[18:19]
	v_mul_f32_e32 v18, 0xbfb8aa3b, v10
	v_pk_mul_f32 v[8:9], v[14:15], v[8:9]
	v_mul_f32_e32 v15, 0xbfb8aa3b, v11
	v_pk_mul_f32 v[2:3], v[2:3], v[22:23] op_sel_hi:[1,0]
	v_exp_f32_e32 v18, v18
	v_exp_f32_e32 v15, v15
	v_pk_mul_f32 v[2:3], v[10:11], v[2:3]
	v_pk_mul_f32 v[10:11], v[12:13], v[22:23] op_sel_hi:[1,0]
	v_mul_f32_e32 v16, 0xbfb8aa3b, v14
	v_mul_f32_e32 v12, 0xbfb8aa3b, v10
	v_mul_f32_e32 v13, 0xbfb8aa3b, v11
	v_exp_f32_e32 v12, v12
	v_exp_f32_e32 v13, v13
	v_exp_f32_e32 v16, v16
	v_exp_f32_e32 v17, v17
	v_add_f32_e32 v14, 1.0, v18
	v_add_f32_e32 v15, 1.0, v15
	v_rcp_f32_e32 v14, v14
	v_rcp_f32_e32 v15, v15
	v_add_f32_e32 v12, 1.0, v12
	v_add_f32_e32 v13, 1.0, v13
	v_add_f32_e32 v16, 1.0, v16
	v_add_f32_e32 v17, 1.0, v17
	v_rcp_f32_e32 v12, v12
	v_rcp_f32_e32 v13, v13
	v_rcp_f32_e32 v16, v16
	v_rcp_f32_e32 v17, v17
	v_pk_mul_f32 v[14:15], v[2:3], v[14:15]
	v_pk_mul_f32 v[2:3], v[4:5], v[22:23] op_sel_hi:[1,0]
	v_cvt_pk_bf16_f32 v4, v14, v15
	v_pk_mul_f32 v[2:3], v[10:11], v[2:3]
	v_pk_mul_f32 v[8:9], v[8:9], v[16:17]
	v_pk_mul_f32 v[10:11], v[2:3], v[12:13]
	v_cvt_pk_bf16_f32 v2, v6, v7
	v_add_co_u32_e32 v6, vcc, 0x58000, v140
	v_cvt_pk_bf16_f32 v3, v8, v9
	s_nop 0
	v_addc_co_u32_e32 v7, vcc, 0, v141, vcc
	v_cvt_pk_bf16_f32 v5, v10, v11
	s_andn2_b64 vcc, exec, s[44:45]
	global_store_dwordx4 v[6:7], v[2:5], off
	s_cbranch_vccnz .LBB0_545
	s_andn2_b64 vcc, exec, s[0:1]
	s_cbranch_vccnz .LBB0_544
	s_barrier
	s_branch .LBB0_544
